# P5 (RWKV head-norm + bonus + gate): hand-written streaming path, one wave = 32 rows, previous row kept in registers, loads 8 rows ahead
# speedup vs baseline: 1.0075x; 1.0075x over previous
.LBB0_976:
	s_cmp_lt_i32 s88, 6
	s_cselect_b64 s[4:5], -1, 0
	s_and_b64 s[16:17], s[4:5], s[0:1]
	s_andn2_b64 vcc, exec, s[16:17]
	s_cbranch_vccnz .LBB0_987
	s_cmp_eq_u32 s92, 0x100
	s_cbranch_scc0 .Lp5_compiled
	v_readlane_b32 s26, v255, 19
	v_readlane_b32 s27, v255, 20
	v_readlane_b32 s28, v255, 21
	v_readlane_b32 s29, v255, 22
	v_mbcnt_lo_u32_b32 v0, -1, 0
	v_mbcnt_hi_u32_b32 v0, -1, v0
	s_lshl_b32 s4, s2, 3
	s_add_i32 s4, s4, s33
	s_lshl_b32 s4, s4, 5
	v_lshlrev_b32_e32 v1, 4, v0
	v_lshlrev_b32_e32 v2, 5, v0
	v_lshrrev_b32_e32 v3, 3, v0
	v_lshlrev_b32_e32 v3, 2, v3
	v_add_u32_e32 v4, 0x1000, v2
	v_mov_b32_e32 v5, 0x3a27c5ac
	s_lshl_b32 s5, s4, 10
	s_add_u32 s6, s96, 0x1d800000
	s_addc_u32 s7, s97, 0
	s_add_u32 s6, s6, s5
	s_addc_u32 s7, s7, 0
	s_add_u32 s8, s96, 0x37800000
	s_addc_u32 s9, s97, 0
	s_add_u32 s8, s8, s5
	s_addc_u32 s9, s9, 0
	s_mul_i32 s5, s4, 0xe00
	s_add_u32 s10, s96, 0xf800800
	s_addc_u32 s11, s97, 0
	s_add_u32 s10, s10, s5
	s_addc_u32 s11, s11, 0
	s_mul_i32 s5, s4, 0xc00
	s_add_u32 s12, s96, 0x2b800800
	s_addc_u32 s13, s97, 0
	s_add_u32 s12, s12, s5
	s_addc_u32 s13, s13, 0
	s_lshl_b32 s5, s4, 5
	s_add_u32 s14, s96, 0x4100000
	s_addc_u32 s15, s97, 0
	s_add_u32 s14, s14, s5
	s_addc_u32 s15, s15, 0
	s_and_b32 s20, s4, 0x7ff
	s_cmp_eq_u32 s20, 0
	s_cselect_b32 s20, 0, 0xe00
	s_sub_u32 s18, s10, s20
	s_subb_u32 s19, s11, 0
	global_load_dwordx4 v[8:11], v4, s[46:47]
	global_load_dwordx4 v[12:15], v4, s[46:47] offset:16
	global_load_dwordx4 v[16:19], v2, s[26:27]
	global_load_dwordx4 v[20:23], v2, s[26:27] offset:16
	global_load_dwordx4 v[24:27], v2, s[28:29]
	global_load_dwordx4 v[28:31], v2, s[28:29] offset:16
	global_load_dwordx4 v[240:243], v1, s[18:19]
	global_load_dwordx4 v[100:103], v1, s[6:7]
	global_load_dwordx4 v[104:107], v1, s[10:11]
	global_load_dwordx4 v[108:111], v1, s[12:13]
	global_load_dword v112, v3, s[14:15]
	s_add_u32 s6, s6, 0x400
	s_addc_u32 s7, s7, 0
	s_add_u32 s10, s10, 0xe00
	s_addc_u32 s11, s11, 0
	s_add_u32 s12, s12, 0xc00
	s_addc_u32 s13, s13, 0
	s_add_u32 s14, s14, 32
	s_addc_u32 s15, s15, 0
	global_load_dwordx4 v[114:117], v1, s[6:7]
	global_load_dwordx4 v[118:121], v1, s[10:11]
	global_load_dwordx4 v[122:125], v1, s[12:13]
	global_load_dword v126, v3, s[14:15]
	s_add_u32 s6, s6, 0x400
	s_addc_u32 s7, s7, 0
	s_add_u32 s10, s10, 0xe00
	s_addc_u32 s11, s11, 0
	s_add_u32 s12, s12, 0xc00
	s_addc_u32 s13, s13, 0
	s_add_u32 s14, s14, 32
	s_addc_u32 s15, s15, 0
	global_load_dwordx4 v[128:131], v1, s[6:7]
	global_load_dwordx4 v[132:135], v1, s[10:11]
	global_load_dwordx4 v[136:139], v1, s[12:13]
	global_load_dword v140, v3, s[14:15]
	s_add_u32 s6, s6, 0x400
	s_addc_u32 s7, s7, 0
	s_add_u32 s10, s10, 0xe00
	s_addc_u32 s11, s11, 0
	s_add_u32 s12, s12, 0xc00
	s_addc_u32 s13, s13, 0
	s_add_u32 s14, s14, 32
	s_addc_u32 s15, s15, 0
	global_load_dwordx4 v[142:145], v1, s[6:7]
	global_load_dwordx4 v[146:149], v1, s[10:11]
	global_load_dwordx4 v[150:153], v1, s[12:13]
	global_load_dword v154, v3, s[14:15]
	s_add_u32 s6, s6, 0x400
	s_addc_u32 s7, s7, 0
	s_add_u32 s10, s10, 0xe00
	s_addc_u32 s11, s11, 0
	s_add_u32 s12, s12, 0xc00
	s_addc_u32 s13, s13, 0
	s_add_u32 s14, s14, 32
	s_addc_u32 s15, s15, 0
	global_load_dwordx4 v[156:159], v1, s[6:7]
	global_load_dwordx4 v[160:163], v1, s[10:11]
	global_load_dwordx4 v[164:167], v1, s[12:13]
	global_load_dword v168, v3, s[14:15]
	s_add_u32 s6, s6, 0x400
	s_addc_u32 s7, s7, 0
	s_add_u32 s10, s10, 0xe00
	s_addc_u32 s11, s11, 0
	s_add_u32 s12, s12, 0xc00
	s_addc_u32 s13, s13, 0
	s_add_u32 s14, s14, 32
	s_addc_u32 s15, s15, 0
	global_load_dwordx4 v[170:173], v1, s[6:7]
	global_load_dwordx4 v[174:177], v1, s[10:11]
	global_load_dwordx4 v[178:181], v1, s[12:13]
	global_load_dword v182, v3, s[14:15]
	s_add_u32 s6, s6, 0x400
	s_addc_u32 s7, s7, 0
	s_add_u32 s10, s10, 0xe00
	s_addc_u32 s11, s11, 0
	s_add_u32 s12, s12, 0xc00
	s_addc_u32 s13, s13, 0
	s_add_u32 s14, s14, 32
	s_addc_u32 s15, s15, 0
	global_load_dwordx4 v[184:187], v1, s[6:7]
	global_load_dwordx4 v[188:191], v1, s[10:11]
	global_load_dwordx4 v[192:195], v1, s[12:13]
	global_load_dword v196, v3, s[14:15]
	s_add_u32 s6, s6, 0x400
	s_addc_u32 s7, s7, 0
	s_add_u32 s10, s10, 0xe00
	s_addc_u32 s11, s11, 0
	s_add_u32 s12, s12, 0xc00
	s_addc_u32 s13, s13, 0
	s_add_u32 s14, s14, 32
	s_addc_u32 s15, s15, 0
	global_load_dwordx4 v[198:201], v1, s[6:7]
	global_load_dwordx4 v[202:205], v1, s[10:11]
	global_load_dwordx4 v[206:209], v1, s[12:13]
	global_load_dword v210, v3, s[14:15]
	s_add_u32 s6, s6, 0x400
	s_addc_u32 s7, s7, 0
	s_add_u32 s10, s10, 0xe00
	s_addc_u32 s11, s11, 0
	s_add_u32 s12, s12, 0xc00
	s_addc_u32 s13, s13, 0
	s_add_u32 s14, s14, 32
	s_addc_u32 s15, s15, 0
	s_waitcnt vmcnt(32)
	v_lshlrev_b32_e32 v56, 16, v240
	v_and_b32_e32 v57, 0xffff0000, v240
	v_lshlrev_b32_e32 v58, 16, v241
	v_and_b32_e32 v59, 0xffff0000, v241
	v_lshlrev_b32_e32 v60, 16, v242
	v_and_b32_e32 v61, 0xffff0000, v242
	v_lshlrev_b32_e32 v62, 16, v243
	v_and_b32_e32 v63, 0xffff0000, v243
	s_cmp_eq_u32 s20, 0
	s_cbranch_scc0 .Lp5_pv
	v_mov_b64_e32 v[56:57], 0
	v_mov_b64_e32 v[58:59], 0
	v_mov_b64_e32 v[60:61], 0
	v_mov_b64_e32 v[62:63], 0
.Lp5_pv:
	s_waitcnt vmcnt(28)
	v_lshlrev_b32_e32 v40, 16, v100
	v_and_b32_e32 v41, 0xffff0000, v100
	v_lshlrev_b32_e32 v42, 16, v101
	v_and_b32_e32 v43, 0xffff0000, v101
	v_lshlrev_b32_e32 v44, 16, v102
	v_and_b32_e32 v45, 0xffff0000, v102
	v_lshlrev_b32_e32 v46, 16, v103
	v_and_b32_e32 v47, 0xffff0000, v103
	v_pk_add_f32 v[88:89], v[40:41], v[42:43]
	v_pk_add_f32 v[88:89], v[88:89], v[44:45]
	v_pk_add_f32 v[88:89], v[88:89], v[46:47]
	v_add_f32_e32 v90, v88, v89
	v_lshlrev_b32_e32 v48, 16, v104
	v_and_b32_e32 v49, 0xffff0000, v104
	v_lshlrev_b32_e32 v50, 16, v105
	v_and_b32_e32 v51, 0xffff0000, v105
	v_lshlrev_b32_e32 v52, 16, v106
	v_and_b32_e32 v53, 0xffff0000, v106
	v_lshlrev_b32_e32 v54, 16, v107
	v_and_b32_e32 v55, 0xffff0000, v107
	v_add_f32_dpp v90, v90, v90 quad_perm:[1,0,3,2] row_mask:0xf bank_mask:0xf
	v_lshlrev_b32_e32 v64, 16, v108
	v_and_b32_e32 v65, 0xffff0000, v108
	v_lshlrev_b32_e32 v66, 16, v109
	v_and_b32_e32 v67, 0xffff0000, v109
	v_add_f32_dpp v90, v90, v90 quad_perm:[2,3,0,1] row_mask:0xf bank_mask:0xf
	v_lshlrev_b32_e32 v68, 16, v110
	v_and_b32_e32 v69, 0xffff0000, v110
	v_lshlrev_b32_e32 v70, 16, v111
	v_and_b32_e32 v71, 0xffff0000, v111
	v_add_f32_dpp v90, v90, v90 row_half_mirror row_mask:0xf bank_mask:0xf
	v_pk_add_f32 v[72:73], v[56:57], v[48:49] neg_lo:[0,1] neg_hi:[0,1]
	v_pk_add_f32 v[74:75], v[58:59], v[50:51] neg_lo:[0,1] neg_hi:[0,1]
	v_pk_add_f32 v[76:77], v[60:61], v[52:53] neg_lo:[0,1] neg_hi:[0,1]
	v_pk_add_f32 v[78:79], v[62:63], v[54:55] neg_lo:[0,1] neg_hi:[0,1]
	v_mul_f32_e32 v92, 0x3c800000, v90
	v_mov_b32_e32 v96, v112
	v_pk_add_f32 v[40:41], v[40:41], v[92:93] op_sel_hi:[1,0] neg_lo:[0,1] neg_hi:[0,1]
	v_pk_add_f32 v[42:43], v[42:43], v[92:93] op_sel_hi:[1,0] neg_lo:[0,1] neg_hi:[0,1]
	v_pk_add_f32 v[44:45], v[44:45], v[92:93] op_sel_hi:[1,0] neg_lo:[0,1] neg_hi:[0,1]
	v_pk_add_f32 v[46:47], v[46:47], v[92:93] op_sel_hi:[1,0] neg_lo:[0,1] neg_hi:[0,1]
	v_pk_mul_f32 v[88:89], v[40:41], v[40:41]
	v_pk_fma_f32 v[88:89], v[42:43], v[42:43], v[88:89]
	v_pk_fma_f32 v[88:89], v[44:45], v[44:45], v[88:89]
	v_pk_fma_f32 v[88:89], v[46:47], v[46:47], v[88:89]
	v_add_f32_e32 v91, v88, v89
	v_pk_fma_f32 v[72:73], v[72:73], v[8:9], v[48:49]
	v_pk_fma_f32 v[74:75], v[74:75], v[10:11], v[50:51]
	v_add_f32_dpp v91, v91, v91 quad_perm:[1,0,3,2] row_mask:0xf bank_mask:0xf
	v_pk_fma_f32 v[76:77], v[76:77], v[12:13], v[52:53]
	v_pk_fma_f32 v[78:79], v[78:79], v[14:15], v[54:55]
	v_add_f32_dpp v91, v91, v91 quad_perm:[2,3,0,1] row_mask:0xf bank_mask:0xf
	s_nop 1
	v_add_f32_dpp v91, v91, v91 row_half_mirror row_mask:0xf bank_mask:0xf
	s_nop 0
	v_fmamk_f32 v94, v91, 0x3c800000, v5
	v_rsq_f32_e32 v94, v94
	s_nop 0
	v_pk_mul_f32 v[40:41], v[40:41], v[94:95] op_sel_hi:[1,0]
	v_pk_mul_f32 v[42:43], v[42:43], v[94:95] op_sel_hi:[1,0]
	v_pk_mul_f32 v[44:45], v[44:45], v[94:95] op_sel_hi:[1,0]
	v_pk_mul_f32 v[46:47], v[46:47], v[94:95] op_sel_hi:[1,0]
	v_pk_fma_f32 v[40:41], v[40:41], v[16:17], v[24:25]
	v_pk_fma_f32 v[42:43], v[42:43], v[18:19], v[26:27]
	v_pk_fma_f32 v[44:45], v[44:45], v[20:21], v[28:29]
	v_pk_fma_f32 v[46:47], v[46:47], v[22:23], v[30:31]
	v_pk_fma_f32 v[80:81], v[72:73], v[96:97], v[40:41] op_sel_hi:[1,0,1]
	v_pk_fma_f32 v[82:83], v[74:75], v[96:97], v[42:43] op_sel_hi:[1,0,1]
	v_pk_fma_f32 v[84:85], v[76:77], v[96:97], v[44:45] op_sel_hi:[1,0,1]
	v_pk_fma_f32 v[86:87], v[78:79], v[96:97], v[46:47] op_sel_hi:[1,0,1]
	v_pk_mul_f32 v[80:81], v[80:81], v[64:65]
	v_pk_mul_f32 v[82:83], v[82:83], v[66:67]
	v_pk_mul_f32 v[84:85], v[84:85], v[68:69]
	v_pk_mul_f32 v[86:87], v[86:87], v[70:71]
	v_cvt_pk_bf16_f32 v72, v80, v81
	v_cvt_pk_bf16_f32 v73, v82, v83
	v_cvt_pk_bf16_f32 v74, v84, v85
	v_cvt_pk_bf16_f32 v75, v86, v87
	global_store_dwordx4 v1, v[72:75], s[8:9]
	s_add_u32 s8, s8, 0x400
	s_addc_u32 s9, s9, 0
	global_load_dwordx4 v[212:215], v1, s[6:7]
	global_load_dwordx4 v[216:219], v1, s[10:11]
	global_load_dwordx4 v[220:223], v1, s[12:13]
	global_load_dword v224, v3, s[14:15]
	s_add_u32 s6, s6, 0x400
	s_addc_u32 s7, s7, 0
	s_add_u32 s10, s10, 0xe00
	s_addc_u32 s11, s11, 0
	s_add_u32 s12, s12, 0xc00
	s_addc_u32 s13, s13, 0
	s_add_u32 s14, s14, 32
	s_addc_u32 s15, s15, 0
	s_waitcnt vmcnt(29)
	v_lshlrev_b32_e32 v40, 16, v114
	v_and_b32_e32 v41, 0xffff0000, v114
	v_lshlrev_b32_e32 v42, 16, v115
	v_and_b32_e32 v43, 0xffff0000, v115
	v_lshlrev_b32_e32 v44, 16, v116
	v_and_b32_e32 v45, 0xffff0000, v116
	v_lshlrev_b32_e32 v46, 16, v117
	v_and_b32_e32 v47, 0xffff0000, v117
	v_pk_add_f32 v[88:89], v[40:41], v[42:43]
	v_pk_add_f32 v[88:89], v[88:89], v[44:45]
	v_pk_add_f32 v[88:89], v[88:89], v[46:47]
	v_add_f32_e32 v90, v88, v89
	v_lshlrev_b32_e32 v56, 16, v118
	v_and_b32_e32 v57, 0xffff0000, v118
	v_lshlrev_b32_e32 v58, 16, v119
	v_and_b32_e32 v59, 0xffff0000, v119
	v_lshlrev_b32_e32 v60, 16, v120
	v_and_b32_e32 v61, 0xffff0000, v120
	v_lshlrev_b32_e32 v62, 16, v121
	v_and_b32_e32 v63, 0xffff0000, v121
	v_add_f32_dpp v90, v90, v90 quad_perm:[1,0,3,2] row_mask:0xf bank_mask:0xf
	v_lshlrev_b32_e32 v64, 16, v122
	v_and_b32_e32 v65, 0xffff0000, v122
	v_lshlrev_b32_e32 v66, 16, v123
	v_and_b32_e32 v67, 0xffff0000, v123
	v_add_f32_dpp v90, v90, v90 quad_perm:[2,3,0,1] row_mask:0xf bank_mask:0xf
	v_lshlrev_b32_e32 v68, 16, v124
	v_and_b32_e32 v69, 0xffff0000, v124
	v_lshlrev_b32_e32 v70, 16, v125
	v_and_b32_e32 v71, 0xffff0000, v125
	v_add_f32_dpp v90, v90, v90 row_half_mirror row_mask:0xf bank_mask:0xf
	v_pk_add_f32 v[72:73], v[48:49], v[56:57] neg_lo:[0,1] neg_hi:[0,1]
	v_pk_add_f32 v[74:75], v[50:51], v[58:59] neg_lo:[0,1] neg_hi:[0,1]
	v_pk_add_f32 v[76:77], v[52:53], v[60:61] neg_lo:[0,1] neg_hi:[0,1]
	v_pk_add_f32 v[78:79], v[54:55], v[62:63] neg_lo:[0,1] neg_hi:[0,1]
	v_mul_f32_e32 v92, 0x3c800000, v90
	v_mov_b32_e32 v96, v126
	v_pk_add_f32 v[40:41], v[40:41], v[92:93] op_sel_hi:[1,0] neg_lo:[0,1] neg_hi:[0,1]
	v_pk_add_f32 v[42:43], v[42:43], v[92:93] op_sel_hi:[1,0] neg_lo:[0,1] neg_hi:[0,1]
	v_pk_add_f32 v[44:45], v[44:45], v[92:93] op_sel_hi:[1,0] neg_lo:[0,1] neg_hi:[0,1]
	v_pk_add_f32 v[46:47], v[46:47], v[92:93] op_sel_hi:[1,0] neg_lo:[0,1] neg_hi:[0,1]
	v_pk_mul_f32 v[88:89], v[40:41], v[40:41]
	v_pk_fma_f32 v[88:89], v[42:43], v[42:43], v[88:89]
	v_pk_fma_f32 v[88:89], v[44:45], v[44:45], v[88:89]
	v_pk_fma_f32 v[88:89], v[46:47], v[46:47], v[88:89]
	v_add_f32_e32 v91, v88, v89
	v_pk_fma_f32 v[72:73], v[72:73], v[8:9], v[56:57]
	v_pk_fma_f32 v[74:75], v[74:75], v[10:11], v[58:59]
	v_add_f32_dpp v91, v91, v91 quad_perm:[1,0,3,2] row_mask:0xf bank_mask:0xf
	v_pk_fma_f32 v[76:77], v[76:77], v[12:13], v[60:61]
	v_pk_fma_f32 v[78:79], v[78:79], v[14:15], v[62:63]
	v_add_f32_dpp v91, v91, v91 quad_perm:[2,3,0,1] row_mask:0xf bank_mask:0xf
	s_nop 1
	v_add_f32_dpp v91, v91, v91 row_half_mirror row_mask:0xf bank_mask:0xf
	s_nop 0
	v_fmamk_f32 v94, v91, 0x3c800000, v5
	v_rsq_f32_e32 v94, v94
	s_nop 0
	v_pk_mul_f32 v[40:41], v[40:41], v[94:95] op_sel_hi:[1,0]
	v_pk_mul_f32 v[42:43], v[42:43], v[94:95] op_sel_hi:[1,0]
	v_pk_mul_f32 v[44:45], v[44:45], v[94:95] op_sel_hi:[1,0]
	v_pk_mul_f32 v[46:47], v[46:47], v[94:95] op_sel_hi:[1,0]
	v_pk_fma_f32 v[40:41], v[40:41], v[16:17], v[24:25]
	v_pk_fma_f32 v[42:43], v[42:43], v[18:19], v[26:27]
	v_pk_fma_f32 v[44:45], v[44:45], v[20:21], v[28:29]
	v_pk_fma_f32 v[46:47], v[46:47], v[22:23], v[30:31]
	v_pk_fma_f32 v[80:81], v[72:73], v[96:97], v[40:41] op_sel_hi:[1,0,1]
	v_pk_fma_f32 v[82:83], v[74:75], v[96:97], v[42:43] op_sel_hi:[1,0,1]
	v_pk_fma_f32 v[84:85], v[76:77], v[96:97], v[44:45] op_sel_hi:[1,0,1]
	v_pk_fma_f32 v[86:87], v[78:79], v[96:97], v[46:47] op_sel_hi:[1,0,1]
	v_pk_mul_f32 v[80:81], v[80:81], v[64:65]
	v_pk_mul_f32 v[82:83], v[82:83], v[66:67]
	v_pk_mul_f32 v[84:85], v[84:85], v[68:69]
	v_pk_mul_f32 v[86:87], v[86:87], v[70:71]
	v_cvt_pk_bf16_f32 v72, v80, v81
	v_cvt_pk_bf16_f32 v73, v82, v83
	v_cvt_pk_bf16_f32 v74, v84, v85
	v_cvt_pk_bf16_f32 v75, v86, v87
	global_store_dwordx4 v1, v[72:75], s[8:9]
	s_add_u32 s8, s8, 0x400
	s_addc_u32 s9, s9, 0
	global_load_dwordx4 v[226:229], v1, s[6:7]
	global_load_dwordx4 v[230:233], v1, s[10:11]
	global_load_dwordx4 v[234:237], v1, s[12:13]
	global_load_dword v238, v3, s[14:15]
	s_add_u32 s6, s6, 0x400
	s_addc_u32 s7, s7, 0
	s_add_u32 s10, s10, 0xe00
	s_addc_u32 s11, s11, 0
	s_add_u32 s12, s12, 0xc00
	s_addc_u32 s13, s13, 0
	s_add_u32 s14, s14, 32
	s_addc_u32 s15, s15, 0
	s_waitcnt vmcnt(30)
	v_lshlrev_b32_e32 v40, 16, v128
	v_and_b32_e32 v41, 0xffff0000, v128
	v_lshlrev_b32_e32 v42, 16, v129
	v_and_b32_e32 v43, 0xffff0000, v129
	v_lshlrev_b32_e32 v44, 16, v130
	v_and_b32_e32 v45, 0xffff0000, v130
	v_lshlrev_b32_e32 v46, 16, v131
	v_and_b32_e32 v47, 0xffff0000, v131
	v_pk_add_f32 v[88:89], v[40:41], v[42:43]
	v_pk_add_f32 v[88:89], v[88:89], v[44:45]
	v_pk_add_f32 v[88:89], v[88:89], v[46:47]
	v_add_f32_e32 v90, v88, v89
	v_lshlrev_b32_e32 v48, 16, v132
	v_and_b32_e32 v49, 0xffff0000, v132
	v_lshlrev_b32_e32 v50, 16, v133
	v_and_b32_e32 v51, 0xffff0000, v133
	v_lshlrev_b32_e32 v52, 16, v134
	v_and_b32_e32 v53, 0xffff0000, v134
	v_lshlrev_b32_e32 v54, 16, v135
	v_and_b32_e32 v55, 0xffff0000, v135
	v_add_f32_dpp v90, v90, v90 quad_perm:[1,0,3,2] row_mask:0xf bank_mask:0xf
	v_lshlrev_b32_e32 v64, 16, v136
	v_and_b32_e32 v65, 0xffff0000, v136
	v_lshlrev_b32_e32 v66, 16, v137
	v_and_b32_e32 v67, 0xffff0000, v137
	v_add_f32_dpp v90, v90, v90 quad_perm:[2,3,0,1] row_mask:0xf bank_mask:0xf
	v_lshlrev_b32_e32 v68, 16, v138
	v_and_b32_e32 v69, 0xffff0000, v138
	v_lshlrev_b32_e32 v70, 16, v139
	v_and_b32_e32 v71, 0xffff0000, v139
	v_add_f32_dpp v90, v90, v90 row_half_mirror row_mask:0xf bank_mask:0xf
	v_pk_add_f32 v[72:73], v[56:57], v[48:49] neg_lo:[0,1] neg_hi:[0,1]
	v_pk_add_f32 v[74:75], v[58:59], v[50:51] neg_lo:[0,1] neg_hi:[0,1]
	v_pk_add_f32 v[76:77], v[60:61], v[52:53] neg_lo:[0,1] neg_hi:[0,1]
	v_pk_add_f32 v[78:79], v[62:63], v[54:55] neg_lo:[0,1] neg_hi:[0,1]
	v_mul_f32_e32 v92, 0x3c800000, v90
	v_mov_b32_e32 v96, v140
	v_pk_add_f32 v[40:41], v[40:41], v[92:93] op_sel_hi:[1,0] neg_lo:[0,1] neg_hi:[0,1]
	v_pk_add_f32 v[42:43], v[42:43], v[92:93] op_sel_hi:[1,0] neg_lo:[0,1] neg_hi:[0,1]
	v_pk_add_f32 v[44:45], v[44:45], v[92:93] op_sel_hi:[1,0] neg_lo:[0,1] neg_hi:[0,1]
	v_pk_add_f32 v[46:47], v[46:47], v[92:93] op_sel_hi:[1,0] neg_lo:[0,1] neg_hi:[0,1]
	v_pk_mul_f32 v[88:89], v[40:41], v[40:41]
	v_pk_fma_f32 v[88:89], v[42:43], v[42:43], v[88:89]
	v_pk_fma_f32 v[88:89], v[44:45], v[44:45], v[88:89]
	v_pk_fma_f32 v[88:89], v[46:47], v[46:47], v[88:89]
	v_add_f32_e32 v91, v88, v89
	v_pk_fma_f32 v[72:73], v[72:73], v[8:9], v[48:49]
	v_pk_fma_f32 v[74:75], v[74:75], v[10:11], v[50:51]
	v_add_f32_dpp v91, v91, v91 quad_perm:[1,0,3,2] row_mask:0xf bank_mask:0xf
	v_pk_fma_f32 v[76:77], v[76:77], v[12:13], v[52:53]
	v_pk_fma_f32 v[78:79], v[78:79], v[14:15], v[54:55]
	v_add_f32_dpp v91, v91, v91 quad_perm:[2,3,0,1] row_mask:0xf bank_mask:0xf
	s_nop 1
	v_add_f32_dpp v91, v91, v91 row_half_mirror row_mask:0xf bank_mask:0xf
	s_nop 0
	v_fmamk_f32 v94, v91, 0x3c800000, v5
	v_rsq_f32_e32 v94, v94
	s_nop 0
	v_pk_mul_f32 v[40:41], v[40:41], v[94:95] op_sel_hi:[1,0]
	v_pk_mul_f32 v[42:43], v[42:43], v[94:95] op_sel_hi:[1,0]
	v_pk_mul_f32 v[44:45], v[44:45], v[94:95] op_sel_hi:[1,0]
	v_pk_mul_f32 v[46:47], v[46:47], v[94:95] op_sel_hi:[1,0]
	v_pk_fma_f32 v[40:41], v[40:41], v[16:17], v[24:25]
	v_pk_fma_f32 v[42:43], v[42:43], v[18:19], v[26:27]
	v_pk_fma_f32 v[44:45], v[44:45], v[20:21], v[28:29]
	v_pk_fma_f32 v[46:47], v[46:47], v[22:23], v[30:31]
	v_pk_fma_f32 v[80:81], v[72:73], v[96:97], v[40:41] op_sel_hi:[1,0,1]
	v_pk_fma_f32 v[82:83], v[74:75], v[96:97], v[42:43] op_sel_hi:[1,0,1]
	v_pk_fma_f32 v[84:85], v[76:77], v[96:97], v[44:45] op_sel_hi:[1,0,1]
	v_pk_fma_f32 v[86:87], v[78:79], v[96:97], v[46:47] op_sel_hi:[1,0,1]
	v_pk_mul_f32 v[80:81], v[80:81], v[64:65]
	v_pk_mul_f32 v[82:83], v[82:83], v[66:67]
	v_pk_mul_f32 v[84:85], v[84:85], v[68:69]
	v_pk_mul_f32 v[86:87], v[86:87], v[70:71]
	v_cvt_pk_bf16_f32 v72, v80, v81
	v_cvt_pk_bf16_f32 v73, v82, v83
	v_cvt_pk_bf16_f32 v74, v84, v85
	v_cvt_pk_bf16_f32 v75, v86, v87
	global_store_dwordx4 v1, v[72:75], s[8:9]
	s_add_u32 s8, s8, 0x400
	s_addc_u32 s9, s9, 0
	global_load_dwordx4 v[100:103], v1, s[6:7]
	global_load_dwordx4 v[104:107], v1, s[10:11]
	global_load_dwordx4 v[108:111], v1, s[12:13]
	global_load_dword v112, v3, s[14:15]
	s_add_u32 s6, s6, 0x400
	s_addc_u32 s7, s7, 0
	s_add_u32 s10, s10, 0xe00
	s_addc_u32 s11, s11, 0
	s_add_u32 s12, s12, 0xc00
	s_addc_u32 s13, s13, 0
	s_add_u32 s14, s14, 32
	s_addc_u32 s15, s15, 0
	s_waitcnt vmcnt(31)
	v_lshlrev_b32_e32 v40, 16, v142
	v_and_b32_e32 v41, 0xffff0000, v142
	v_lshlrev_b32_e32 v42, 16, v143
	v_and_b32_e32 v43, 0xffff0000, v143
	v_lshlrev_b32_e32 v44, 16, v144
	v_and_b32_e32 v45, 0xffff0000, v144
	v_lshlrev_b32_e32 v46, 16, v145
	v_and_b32_e32 v47, 0xffff0000, v145
	v_pk_add_f32 v[88:89], v[40:41], v[42:43]
	v_pk_add_f32 v[88:89], v[88:89], v[44:45]
	v_pk_add_f32 v[88:89], v[88:89], v[46:47]
	v_add_f32_e32 v90, v88, v89
	v_lshlrev_b32_e32 v56, 16, v146
	v_and_b32_e32 v57, 0xffff0000, v146
	v_lshlrev_b32_e32 v58, 16, v147
	v_and_b32_e32 v59, 0xffff0000, v147
	v_lshlrev_b32_e32 v60, 16, v148
	v_and_b32_e32 v61, 0xffff0000, v148
	v_lshlrev_b32_e32 v62, 16, v149
	v_and_b32_e32 v63, 0xffff0000, v149
	v_add_f32_dpp v90, v90, v90 quad_perm:[1,0,3,2] row_mask:0xf bank_mask:0xf
	v_lshlrev_b32_e32 v64, 16, v150
	v_and_b32_e32 v65, 0xffff0000, v150
	v_lshlrev_b32_e32 v66, 16, v151
	v_and_b32_e32 v67, 0xffff0000, v151
	v_add_f32_dpp v90, v90, v90 quad_perm:[2,3,0,1] row_mask:0xf bank_mask:0xf
	v_lshlrev_b32_e32 v68, 16, v152
	v_and_b32_e32 v69, 0xffff0000, v152
	v_lshlrev_b32_e32 v70, 16, v153
	v_and_b32_e32 v71, 0xffff0000, v153
	v_add_f32_dpp v90, v90, v90 row_half_mirror row_mask:0xf bank_mask:0xf
	v_pk_add_f32 v[72:73], v[48:49], v[56:57] neg_lo:[0,1] neg_hi:[0,1]
	v_pk_add_f32 v[74:75], v[50:51], v[58:59] neg_lo:[0,1] neg_hi:[0,1]
	v_pk_add_f32 v[76:77], v[52:53], v[60:61] neg_lo:[0,1] neg_hi:[0,1]
	v_pk_add_f32 v[78:79], v[54:55], v[62:63] neg_lo:[0,1] neg_hi:[0,1]
	v_mul_f32_e32 v92, 0x3c800000, v90
	v_mov_b32_e32 v96, v154
	v_pk_add_f32 v[40:41], v[40:41], v[92:93] op_sel_hi:[1,0] neg_lo:[0,1] neg_hi:[0,1]
	v_pk_add_f32 v[42:43], v[42:43], v[92:93] op_sel_hi:[1,0] neg_lo:[0,1] neg_hi:[0,1]
	v_pk_add_f32 v[44:45], v[44:45], v[92:93] op_sel_hi:[1,0] neg_lo:[0,1] neg_hi:[0,1]
	v_pk_add_f32 v[46:47], v[46:47], v[92:93] op_sel_hi:[1,0] neg_lo:[0,1] neg_hi:[0,1]
	v_pk_mul_f32 v[88:89], v[40:41], v[40:41]
	v_pk_fma_f32 v[88:89], v[42:43], v[42:43], v[88:89]
	v_pk_fma_f32 v[88:89], v[44:45], v[44:45], v[88:89]
	v_pk_fma_f32 v[88:89], v[46:47], v[46:47], v[88:89]
	v_add_f32_e32 v91, v88, v89
	v_pk_fma_f32 v[72:73], v[72:73], v[8:9], v[56:57]
	v_pk_fma_f32 v[74:75], v[74:75], v[10:11], v[58:59]
	v_add_f32_dpp v91, v91, v91 quad_perm:[1,0,3,2] row_mask:0xf bank_mask:0xf
	v_pk_fma_f32 v[76:77], v[76:77], v[12:13], v[60:61]
	v_pk_fma_f32 v[78:79], v[78:79], v[14:15], v[62:63]
	v_add_f32_dpp v91, v91, v91 quad_perm:[2,3,0,1] row_mask:0xf bank_mask:0xf
	s_nop 1
	v_add_f32_dpp v91, v91, v91 row_half_mirror row_mask:0xf bank_mask:0xf
	s_nop 0
	v_fmamk_f32 v94, v91, 0x3c800000, v5
	v_rsq_f32_e32 v94, v94
	s_nop 0
	v_pk_mul_f32 v[40:41], v[40:41], v[94:95] op_sel_hi:[1,0]
	v_pk_mul_f32 v[42:43], v[42:43], v[94:95] op_sel_hi:[1,0]
	v_pk_mul_f32 v[44:45], v[44:45], v[94:95] op_sel_hi:[1,0]
	v_pk_mul_f32 v[46:47], v[46:47], v[94:95] op_sel_hi:[1,0]
	v_pk_fma_f32 v[40:41], v[40:41], v[16:17], v[24:25]
	v_pk_fma_f32 v[42:43], v[42:43], v[18:19], v[26:27]
	v_pk_fma_f32 v[44:45], v[44:45], v[20:21], v[28:29]
	v_pk_fma_f32 v[46:47], v[46:47], v[22:23], v[30:31]
	v_pk_fma_f32 v[80:81], v[72:73], v[96:97], v[40:41] op_sel_hi:[1,0,1]
	v_pk_fma_f32 v[82:83], v[74:75], v[96:97], v[42:43] op_sel_hi:[1,0,1]
	v_pk_fma_f32 v[84:85], v[76:77], v[96:97], v[44:45] op_sel_hi:[1,0,1]
	v_pk_fma_f32 v[86:87], v[78:79], v[96:97], v[46:47] op_sel_hi:[1,0,1]
	v_pk_mul_f32 v[80:81], v[80:81], v[64:65]
	v_pk_mul_f32 v[82:83], v[82:83], v[66:67]
	v_pk_mul_f32 v[84:85], v[84:85], v[68:69]
	v_pk_mul_f32 v[86:87], v[86:87], v[70:71]
	v_cvt_pk_bf16_f32 v72, v80, v81
	v_cvt_pk_bf16_f32 v73, v82, v83
	v_cvt_pk_bf16_f32 v74, v84, v85
	v_cvt_pk_bf16_f32 v75, v86, v87
	global_store_dwordx4 v1, v[72:75], s[8:9]
	s_add_u32 s8, s8, 0x400
	s_addc_u32 s9, s9, 0
	global_load_dwordx4 v[114:117], v1, s[6:7]
	global_load_dwordx4 v[118:121], v1, s[10:11]
	global_load_dwordx4 v[122:125], v1, s[12:13]
	global_load_dword v126, v3, s[14:15]
	s_add_u32 s6, s6, 0x400
	s_addc_u32 s7, s7, 0
	s_add_u32 s10, s10, 0xe00
	s_addc_u32 s11, s11, 0
	s_add_u32 s12, s12, 0xc00
	s_addc_u32 s13, s13, 0
	s_add_u32 s14, s14, 32
	s_addc_u32 s15, s15, 0
	s_waitcnt vmcnt(32)
	v_lshlrev_b32_e32 v40, 16, v156
	v_and_b32_e32 v41, 0xffff0000, v156
	v_lshlrev_b32_e32 v42, 16, v157
	v_and_b32_e32 v43, 0xffff0000, v157
	v_lshlrev_b32_e32 v44, 16, v158
	v_and_b32_e32 v45, 0xffff0000, v158
	v_lshlrev_b32_e32 v46, 16, v159
	v_and_b32_e32 v47, 0xffff0000, v159
	v_pk_add_f32 v[88:89], v[40:41], v[42:43]
	v_pk_add_f32 v[88:89], v[88:89], v[44:45]
	v_pk_add_f32 v[88:89], v[88:89], v[46:47]
	v_add_f32_e32 v90, v88, v89
	v_lshlrev_b32_e32 v48, 16, v160
	v_and_b32_e32 v49, 0xffff0000, v160
	v_lshlrev_b32_e32 v50, 16, v161
	v_and_b32_e32 v51, 0xffff0000, v161
	v_lshlrev_b32_e32 v52, 16, v162
	v_and_b32_e32 v53, 0xffff0000, v162
	v_lshlrev_b32_e32 v54, 16, v163
	v_and_b32_e32 v55, 0xffff0000, v163
	v_add_f32_dpp v90, v90, v90 quad_perm:[1,0,3,2] row_mask:0xf bank_mask:0xf
	v_lshlrev_b32_e32 v64, 16, v164
	v_and_b32_e32 v65, 0xffff0000, v164
	v_lshlrev_b32_e32 v66, 16, v165
	v_and_b32_e32 v67, 0xffff0000, v165
	v_add_f32_dpp v90, v90, v90 quad_perm:[2,3,0,1] row_mask:0xf bank_mask:0xf
	v_lshlrev_b32_e32 v68, 16, v166
	v_and_b32_e32 v69, 0xffff0000, v166
	v_lshlrev_b32_e32 v70, 16, v167
	v_and_b32_e32 v71, 0xffff0000, v167
	v_add_f32_dpp v90, v90, v90 row_half_mirror row_mask:0xf bank_mask:0xf
	v_pk_add_f32 v[72:73], v[56:57], v[48:49] neg_lo:[0,1] neg_hi:[0,1]
	v_pk_add_f32 v[74:75], v[58:59], v[50:51] neg_lo:[0,1] neg_hi:[0,1]
	v_pk_add_f32 v[76:77], v[60:61], v[52:53] neg_lo:[0,1] neg_hi:[0,1]
	v_pk_add_f32 v[78:79], v[62:63], v[54:55] neg_lo:[0,1] neg_hi:[0,1]
	v_mul_f32_e32 v92, 0x3c800000, v90
	v_mov_b32_e32 v96, v168
	v_pk_add_f32 v[40:41], v[40:41], v[92:93] op_sel_hi:[1,0] neg_lo:[0,1] neg_hi:[0,1]
	v_pk_add_f32 v[42:43], v[42:43], v[92:93] op_sel_hi:[1,0] neg_lo:[0,1] neg_hi:[0,1]
	v_pk_add_f32 v[44:45], v[44:45], v[92:93] op_sel_hi:[1,0] neg_lo:[0,1] neg_hi:[0,1]
	v_pk_add_f32 v[46:47], v[46:47], v[92:93] op_sel_hi:[1,0] neg_lo:[0,1] neg_hi:[0,1]
	v_pk_mul_f32 v[88:89], v[40:41], v[40:41]
	v_pk_fma_f32 v[88:89], v[42:43], v[42:43], v[88:89]
	v_pk_fma_f32 v[88:89], v[44:45], v[44:45], v[88:89]
	v_pk_fma_f32 v[88:89], v[46:47], v[46:47], v[88:89]
	v_add_f32_e32 v91, v88, v89
	v_pk_fma_f32 v[72:73], v[72:73], v[8:9], v[48:49]
	v_pk_fma_f32 v[74:75], v[74:75], v[10:11], v[50:51]
	v_add_f32_dpp v91, v91, v91 quad_perm:[1,0,3,2] row_mask:0xf bank_mask:0xf
	v_pk_fma_f32 v[76:77], v[76:77], v[12:13], v[52:53]
	v_pk_fma_f32 v[78:79], v[78:79], v[14:15], v[54:55]
	v_add_f32_dpp v91, v91, v91 quad_perm:[2,3,0,1] row_mask:0xf bank_mask:0xf
	s_nop 1
	v_add_f32_dpp v91, v91, v91 row_half_mirror row_mask:0xf bank_mask:0xf
	s_nop 0
	v_fmamk_f32 v94, v91, 0x3c800000, v5
	v_rsq_f32_e32 v94, v94
	s_nop 0
	v_pk_mul_f32 v[40:41], v[40:41], v[94:95] op_sel_hi:[1,0]
	v_pk_mul_f32 v[42:43], v[42:43], v[94:95] op_sel_hi:[1,0]
	v_pk_mul_f32 v[44:45], v[44:45], v[94:95] op_sel_hi:[1,0]
	v_pk_mul_f32 v[46:47], v[46:47], v[94:95] op_sel_hi:[1,0]
	v_pk_fma_f32 v[40:41], v[40:41], v[16:17], v[24:25]
	v_pk_fma_f32 v[42:43], v[42:43], v[18:19], v[26:27]
	v_pk_fma_f32 v[44:45], v[44:45], v[20:21], v[28:29]
	v_pk_fma_f32 v[46:47], v[46:47], v[22:23], v[30:31]
	v_pk_fma_f32 v[80:81], v[72:73], v[96:97], v[40:41] op_sel_hi:[1,0,1]
	v_pk_fma_f32 v[82:83], v[74:75], v[96:97], v[42:43] op_sel_hi:[1,0,1]
	v_pk_fma_f32 v[84:85], v[76:77], v[96:97], v[44:45] op_sel_hi:[1,0,1]
	v_pk_fma_f32 v[86:87], v[78:79], v[96:97], v[46:47] op_sel_hi:[1,0,1]
	v_pk_mul_f32 v[80:81], v[80:81], v[64:65]
	v_pk_mul_f32 v[82:83], v[82:83], v[66:67]
	v_pk_mul_f32 v[84:85], v[84:85], v[68:69]
	v_pk_mul_f32 v[86:87], v[86:87], v[70:71]
	v_cvt_pk_bf16_f32 v72, v80, v81
	v_cvt_pk_bf16_f32 v73, v82, v83
	v_cvt_pk_bf16_f32 v74, v84, v85
	v_cvt_pk_bf16_f32 v75, v86, v87
	global_store_dwordx4 v1, v[72:75], s[8:9]
	s_add_u32 s8, s8, 0x400
	s_addc_u32 s9, s9, 0
	global_load_dwordx4 v[128:131], v1, s[6:7]
	global_load_dwordx4 v[132:135], v1, s[10:11]
	global_load_dwordx4 v[136:139], v1, s[12:13]
	global_load_dword v140, v3, s[14:15]
	s_add_u32 s6, s6, 0x400
	s_addc_u32 s7, s7, 0
	s_add_u32 s10, s10, 0xe00
	s_addc_u32 s11, s11, 0
	s_add_u32 s12, s12, 0xc00
	s_addc_u32 s13, s13, 0
	s_add_u32 s14, s14, 32
	s_addc_u32 s15, s15, 0
	s_waitcnt vmcnt(33)
	v_lshlrev_b32_e32 v40, 16, v170
	v_and_b32_e32 v41, 0xffff0000, v170
	v_lshlrev_b32_e32 v42, 16, v171
	v_and_b32_e32 v43, 0xffff0000, v171
	v_lshlrev_b32_e32 v44, 16, v172
	v_and_b32_e32 v45, 0xffff0000, v172
	v_lshlrev_b32_e32 v46, 16, v173
	v_and_b32_e32 v47, 0xffff0000, v173
	v_pk_add_f32 v[88:89], v[40:41], v[42:43]
	v_pk_add_f32 v[88:89], v[88:89], v[44:45]
	v_pk_add_f32 v[88:89], v[88:89], v[46:47]
	v_add_f32_e32 v90, v88, v89
	v_lshlrev_b32_e32 v56, 16, v174
	v_and_b32_e32 v57, 0xffff0000, v174
	v_lshlrev_b32_e32 v58, 16, v175
	v_and_b32_e32 v59, 0xffff0000, v175
	v_lshlrev_b32_e32 v60, 16, v176
	v_and_b32_e32 v61, 0xffff0000, v176
	v_lshlrev_b32_e32 v62, 16, v177
	v_and_b32_e32 v63, 0xffff0000, v177
	v_add_f32_dpp v90, v90, v90 quad_perm:[1,0,3,2] row_mask:0xf bank_mask:0xf
	v_lshlrev_b32_e32 v64, 16, v178
	v_and_b32_e32 v65, 0xffff0000, v178
	v_lshlrev_b32_e32 v66, 16, v179
	v_and_b32_e32 v67, 0xffff0000, v179
	v_add_f32_dpp v90, v90, v90 quad_perm:[2,3,0,1] row_mask:0xf bank_mask:0xf
	v_lshlrev_b32_e32 v68, 16, v180
	v_and_b32_e32 v69, 0xffff0000, v180
	v_lshlrev_b32_e32 v70, 16, v181
	v_and_b32_e32 v71, 0xffff0000, v181
	v_add_f32_dpp v90, v90, v90 row_half_mirror row_mask:0xf bank_mask:0xf
	v_pk_add_f32 v[72:73], v[48:49], v[56:57] neg_lo:[0,1] neg_hi:[0,1]
	v_pk_add_f32 v[74:75], v[50:51], v[58:59] neg_lo:[0,1] neg_hi:[0,1]
	v_pk_add_f32 v[76:77], v[52:53], v[60:61] neg_lo:[0,1] neg_hi:[0,1]
	v_pk_add_f32 v[78:79], v[54:55], v[62:63] neg_lo:[0,1] neg_hi:[0,1]
	v_mul_f32_e32 v92, 0x3c800000, v90
	v_mov_b32_e32 v96, v182
	v_pk_add_f32 v[40:41], v[40:41], v[92:93] op_sel_hi:[1,0] neg_lo:[0,1] neg_hi:[0,1]
	v_pk_add_f32 v[42:43], v[42:43], v[92:93] op_sel_hi:[1,0] neg_lo:[0,1] neg_hi:[0,1]
	v_pk_add_f32 v[44:45], v[44:45], v[92:93] op_sel_hi:[1,0] neg_lo:[0,1] neg_hi:[0,1]
	v_pk_add_f32 v[46:47], v[46:47], v[92:93] op_sel_hi:[1,0] neg_lo:[0,1] neg_hi:[0,1]
	v_pk_mul_f32 v[88:89], v[40:41], v[40:41]
	v_pk_fma_f32 v[88:89], v[42:43], v[42:43], v[88:89]
	v_pk_fma_f32 v[88:89], v[44:45], v[44:45], v[88:89]
	v_pk_fma_f32 v[88:89], v[46:47], v[46:47], v[88:89]
	v_add_f32_e32 v91, v88, v89
	v_pk_fma_f32 v[72:73], v[72:73], v[8:9], v[56:57]
	v_pk_fma_f32 v[74:75], v[74:75], v[10:11], v[58:59]
	v_add_f32_dpp v91, v91, v91 quad_perm:[1,0,3,2] row_mask:0xf bank_mask:0xf
	v_pk_fma_f32 v[76:77], v[76:77], v[12:13], v[60:61]
	v_pk_fma_f32 v[78:79], v[78:79], v[14:15], v[62:63]
	v_add_f32_dpp v91, v91, v91 quad_perm:[2,3,0,1] row_mask:0xf bank_mask:0xf
	s_nop 1
	v_add_f32_dpp v91, v91, v91 row_half_mirror row_mask:0xf bank_mask:0xf
	s_nop 0
	v_fmamk_f32 v94, v91, 0x3c800000, v5
	v_rsq_f32_e32 v94, v94
	s_nop 0
	v_pk_mul_f32 v[40:41], v[40:41], v[94:95] op_sel_hi:[1,0]
	v_pk_mul_f32 v[42:43], v[42:43], v[94:95] op_sel_hi:[1,0]
	v_pk_mul_f32 v[44:45], v[44:45], v[94:95] op_sel_hi:[1,0]
	v_pk_mul_f32 v[46:47], v[46:47], v[94:95] op_sel_hi:[1,0]
	v_pk_fma_f32 v[40:41], v[40:41], v[16:17], v[24:25]
	v_pk_fma_f32 v[42:43], v[42:43], v[18:19], v[26:27]
	v_pk_fma_f32 v[44:45], v[44:45], v[20:21], v[28:29]
	v_pk_fma_f32 v[46:47], v[46:47], v[22:23], v[30:31]
	v_pk_fma_f32 v[80:81], v[72:73], v[96:97], v[40:41] op_sel_hi:[1,0,1]
	v_pk_fma_f32 v[82:83], v[74:75], v[96:97], v[42:43] op_sel_hi:[1,0,1]
	v_pk_fma_f32 v[84:85], v[76:77], v[96:97], v[44:45] op_sel_hi:[1,0,1]
	v_pk_fma_f32 v[86:87], v[78:79], v[96:97], v[46:47] op_sel_hi:[1,0,1]
	v_pk_mul_f32 v[80:81], v[80:81], v[64:65]
	v_pk_mul_f32 v[82:83], v[82:83], v[66:67]
	v_pk_mul_f32 v[84:85], v[84:85], v[68:69]
	v_pk_mul_f32 v[86:87], v[86:87], v[70:71]
	v_cvt_pk_bf16_f32 v72, v80, v81
	v_cvt_pk_bf16_f32 v73, v82, v83
	v_cvt_pk_bf16_f32 v74, v84, v85
	v_cvt_pk_bf16_f32 v75, v86, v87
	global_store_dwordx4 v1, v[72:75], s[8:9]
	s_add_u32 s8, s8, 0x400
	s_addc_u32 s9, s9, 0
	global_load_dwordx4 v[142:145], v1, s[6:7]
	global_load_dwordx4 v[146:149], v1, s[10:11]
	global_load_dwordx4 v[150:153], v1, s[12:13]
	global_load_dword v154, v3, s[14:15]
	s_add_u32 s6, s6, 0x400
	s_addc_u32 s7, s7, 0
	s_add_u32 s10, s10, 0xe00
	s_addc_u32 s11, s11, 0
	s_add_u32 s12, s12, 0xc00
	s_addc_u32 s13, s13, 0
	s_add_u32 s14, s14, 32
	s_addc_u32 s15, s15, 0
	s_waitcnt vmcnt(34)
	v_lshlrev_b32_e32 v40, 16, v184
	v_and_b32_e32 v41, 0xffff0000, v184
	v_lshlrev_b32_e32 v42, 16, v185
	v_and_b32_e32 v43, 0xffff0000, v185
	v_lshlrev_b32_e32 v44, 16, v186
	v_and_b32_e32 v45, 0xffff0000, v186
	v_lshlrev_b32_e32 v46, 16, v187
	v_and_b32_e32 v47, 0xffff0000, v187
	v_pk_add_f32 v[88:89], v[40:41], v[42:43]
	v_pk_add_f32 v[88:89], v[88:89], v[44:45]
	v_pk_add_f32 v[88:89], v[88:89], v[46:47]
	v_add_f32_e32 v90, v88, v89
	v_lshlrev_b32_e32 v48, 16, v188
	v_and_b32_e32 v49, 0xffff0000, v188
	v_lshlrev_b32_e32 v50, 16, v189
	v_and_b32_e32 v51, 0xffff0000, v189
	v_lshlrev_b32_e32 v52, 16, v190
	v_and_b32_e32 v53, 0xffff0000, v190
	v_lshlrev_b32_e32 v54, 16, v191
	v_and_b32_e32 v55, 0xffff0000, v191
	v_add_f32_dpp v90, v90, v90 quad_perm:[1,0,3,2] row_mask:0xf bank_mask:0xf
	v_lshlrev_b32_e32 v64, 16, v192
	v_and_b32_e32 v65, 0xffff0000, v192
	v_lshlrev_b32_e32 v66, 16, v193
	v_and_b32_e32 v67, 0xffff0000, v193
	v_add_f32_dpp v90, v90, v90 quad_perm:[2,3,0,1] row_mask:0xf bank_mask:0xf
	v_lshlrev_b32_e32 v68, 16, v194
	v_and_b32_e32 v69, 0xffff0000, v194
	v_lshlrev_b32_e32 v70, 16, v195
	v_and_b32_e32 v71, 0xffff0000, v195
	v_add_f32_dpp v90, v90, v90 row_half_mirror row_mask:0xf bank_mask:0xf
	v_pk_add_f32 v[72:73], v[56:57], v[48:49] neg_lo:[0,1] neg_hi:[0,1]
	v_pk_add_f32 v[74:75], v[58:59], v[50:51] neg_lo:[0,1] neg_hi:[0,1]
	v_pk_add_f32 v[76:77], v[60:61], v[52:53] neg_lo:[0,1] neg_hi:[0,1]
	v_pk_add_f32 v[78:79], v[62:63], v[54:55] neg_lo:[0,1] neg_hi:[0,1]
	v_mul_f32_e32 v92, 0x3c800000, v90
	v_mov_b32_e32 v96, v196
	v_pk_add_f32 v[40:41], v[40:41], v[92:93] op_sel_hi:[1,0] neg_lo:[0,1] neg_hi:[0,1]
	v_pk_add_f32 v[42:43], v[42:43], v[92:93] op_sel_hi:[1,0] neg_lo:[0,1] neg_hi:[0,1]
	v_pk_add_f32 v[44:45], v[44:45], v[92:93] op_sel_hi:[1,0] neg_lo:[0,1] neg_hi:[0,1]
	v_pk_add_f32 v[46:47], v[46:47], v[92:93] op_sel_hi:[1,0] neg_lo:[0,1] neg_hi:[0,1]
	v_pk_mul_f32 v[88:89], v[40:41], v[40:41]
	v_pk_fma_f32 v[88:89], v[42:43], v[42:43], v[88:89]
	v_pk_fma_f32 v[88:89], v[44:45], v[44:45], v[88:89]
	v_pk_fma_f32 v[88:89], v[46:47], v[46:47], v[88:89]
	v_add_f32_e32 v91, v88, v89
	v_pk_fma_f32 v[72:73], v[72:73], v[8:9], v[48:49]
	v_pk_fma_f32 v[74:75], v[74:75], v[10:11], v[50:51]
	v_add_f32_dpp v91, v91, v91 quad_perm:[1,0,3,2] row_mask:0xf bank_mask:0xf
	v_pk_fma_f32 v[76:77], v[76:77], v[12:13], v[52:53]
	v_pk_fma_f32 v[78:79], v[78:79], v[14:15], v[54:55]
	v_add_f32_dpp v91, v91, v91 quad_perm:[2,3,0,1] row_mask:0xf bank_mask:0xf
	s_nop 1
	v_add_f32_dpp v91, v91, v91 row_half_mirror row_mask:0xf bank_mask:0xf
	s_nop 0
	v_fmamk_f32 v94, v91, 0x3c800000, v5
	v_rsq_f32_e32 v94, v94
	s_nop 0
	v_pk_mul_f32 v[40:41], v[40:41], v[94:95] op_sel_hi:[1,0]
	v_pk_mul_f32 v[42:43], v[42:43], v[94:95] op_sel_hi:[1,0]
	v_pk_mul_f32 v[44:45], v[44:45], v[94:95] op_sel_hi:[1,0]
	v_pk_mul_f32 v[46:47], v[46:47], v[94:95] op_sel_hi:[1,0]
	v_pk_fma_f32 v[40:41], v[40:41], v[16:17], v[24:25]
	v_pk_fma_f32 v[42:43], v[42:43], v[18:19], v[26:27]
	v_pk_fma_f32 v[44:45], v[44:45], v[20:21], v[28:29]
	v_pk_fma_f32 v[46:47], v[46:47], v[22:23], v[30:31]
	v_pk_fma_f32 v[80:81], v[72:73], v[96:97], v[40:41] op_sel_hi:[1,0,1]
	v_pk_fma_f32 v[82:83], v[74:75], v[96:97], v[42:43] op_sel_hi:[1,0,1]
	v_pk_fma_f32 v[84:85], v[76:77], v[96:97], v[44:45] op_sel_hi:[1,0,1]
	v_pk_fma_f32 v[86:87], v[78:79], v[96:97], v[46:47] op_sel_hi:[1,0,1]
	v_pk_mul_f32 v[80:81], v[80:81], v[64:65]
	v_pk_mul_f32 v[82:83], v[82:83], v[66:67]
	v_pk_mul_f32 v[84:85], v[84:85], v[68:69]
	v_pk_mul_f32 v[86:87], v[86:87], v[70:71]
	v_cvt_pk_bf16_f32 v72, v80, v81
	v_cvt_pk_bf16_f32 v73, v82, v83
	v_cvt_pk_bf16_f32 v74, v84, v85
	v_cvt_pk_bf16_f32 v75, v86, v87
	global_store_dwordx4 v1, v[72:75], s[8:9]
	s_add_u32 s8, s8, 0x400
	s_addc_u32 s9, s9, 0
	global_load_dwordx4 v[156:159], v1, s[6:7]
	global_load_dwordx4 v[160:163], v1, s[10:11]
	global_load_dwordx4 v[164:167], v1, s[12:13]
	global_load_dword v168, v3, s[14:15]
	s_add_u32 s6, s6, 0x400
	s_addc_u32 s7, s7, 0
	s_add_u32 s10, s10, 0xe00
	s_addc_u32 s11, s11, 0
	s_add_u32 s12, s12, 0xc00
	s_addc_u32 s13, s13, 0
	s_add_u32 s14, s14, 32
	s_addc_u32 s15, s15, 0
	s_waitcnt vmcnt(35)
	v_lshlrev_b32_e32 v40, 16, v198
	v_and_b32_e32 v41, 0xffff0000, v198
	v_lshlrev_b32_e32 v42, 16, v199
	v_and_b32_e32 v43, 0xffff0000, v199
	v_lshlrev_b32_e32 v44, 16, v200
	v_and_b32_e32 v45, 0xffff0000, v200
	v_lshlrev_b32_e32 v46, 16, v201
	v_and_b32_e32 v47, 0xffff0000, v201
	v_pk_add_f32 v[88:89], v[40:41], v[42:43]
	v_pk_add_f32 v[88:89], v[88:89], v[44:45]
	v_pk_add_f32 v[88:89], v[88:89], v[46:47]
	v_add_f32_e32 v90, v88, v89
	v_lshlrev_b32_e32 v56, 16, v202
	v_and_b32_e32 v57, 0xffff0000, v202
	v_lshlrev_b32_e32 v58, 16, v203
	v_and_b32_e32 v59, 0xffff0000, v203
	v_lshlrev_b32_e32 v60, 16, v204
	v_and_b32_e32 v61, 0xffff0000, v204
	v_lshlrev_b32_e32 v62, 16, v205
	v_and_b32_e32 v63, 0xffff0000, v205
	v_add_f32_dpp v90, v90, v90 quad_perm:[1,0,3,2] row_mask:0xf bank_mask:0xf
	v_lshlrev_b32_e32 v64, 16, v206
	v_and_b32_e32 v65, 0xffff0000, v206
	v_lshlrev_b32_e32 v66, 16, v207
	v_and_b32_e32 v67, 0xffff0000, v207
	v_add_f32_dpp v90, v90, v90 quad_perm:[2,3,0,1] row_mask:0xf bank_mask:0xf
	v_lshlrev_b32_e32 v68, 16, v208
	v_and_b32_e32 v69, 0xffff0000, v208
	v_lshlrev_b32_e32 v70, 16, v209
	v_and_b32_e32 v71, 0xffff0000, v209
	v_add_f32_dpp v90, v90, v90 row_half_mirror row_mask:0xf bank_mask:0xf
	v_pk_add_f32 v[72:73], v[48:49], v[56:57] neg_lo:[0,1] neg_hi:[0,1]
	v_pk_add_f32 v[74:75], v[50:51], v[58:59] neg_lo:[0,1] neg_hi:[0,1]
	v_pk_add_f32 v[76:77], v[52:53], v[60:61] neg_lo:[0,1] neg_hi:[0,1]
	v_pk_add_f32 v[78:79], v[54:55], v[62:63] neg_lo:[0,1] neg_hi:[0,1]
	v_mul_f32_e32 v92, 0x3c800000, v90
	v_mov_b32_e32 v96, v210
	v_pk_add_f32 v[40:41], v[40:41], v[92:93] op_sel_hi:[1,0] neg_lo:[0,1] neg_hi:[0,1]
	v_pk_add_f32 v[42:43], v[42:43], v[92:93] op_sel_hi:[1,0] neg_lo:[0,1] neg_hi:[0,1]
	v_pk_add_f32 v[44:45], v[44:45], v[92:93] op_sel_hi:[1,0] neg_lo:[0,1] neg_hi:[0,1]
	v_pk_add_f32 v[46:47], v[46:47], v[92:93] op_sel_hi:[1,0] neg_lo:[0,1] neg_hi:[0,1]
	v_pk_mul_f32 v[88:89], v[40:41], v[40:41]
	v_pk_fma_f32 v[88:89], v[42:43], v[42:43], v[88:89]
	v_pk_fma_f32 v[88:89], v[44:45], v[44:45], v[88:89]
	v_pk_fma_f32 v[88:89], v[46:47], v[46:47], v[88:89]
	v_add_f32_e32 v91, v88, v89
	v_pk_fma_f32 v[72:73], v[72:73], v[8:9], v[56:57]
	v_pk_fma_f32 v[74:75], v[74:75], v[10:11], v[58:59]
	v_add_f32_dpp v91, v91, v91 quad_perm:[1,0,3,2] row_mask:0xf bank_mask:0xf
	v_pk_fma_f32 v[76:77], v[76:77], v[12:13], v[60:61]
	v_pk_fma_f32 v[78:79], v[78:79], v[14:15], v[62:63]
	v_add_f32_dpp v91, v91, v91 quad_perm:[2,3,0,1] row_mask:0xf bank_mask:0xf
	s_nop 1
	v_add_f32_dpp v91, v91, v91 row_half_mirror row_mask:0xf bank_mask:0xf
	s_nop 0
	v_fmamk_f32 v94, v91, 0x3c800000, v5
	v_rsq_f32_e32 v94, v94
	s_nop 0
	v_pk_mul_f32 v[40:41], v[40:41], v[94:95] op_sel_hi:[1,0]
	v_pk_mul_f32 v[42:43], v[42:43], v[94:95] op_sel_hi:[1,0]
	v_pk_mul_f32 v[44:45], v[44:45], v[94:95] op_sel_hi:[1,0]
	v_pk_mul_f32 v[46:47], v[46:47], v[94:95] op_sel_hi:[1,0]
	v_pk_fma_f32 v[40:41], v[40:41], v[16:17], v[24:25]
	v_pk_fma_f32 v[42:43], v[42:43], v[18:19], v[26:27]
	v_pk_fma_f32 v[44:45], v[44:45], v[20:21], v[28:29]
	v_pk_fma_f32 v[46:47], v[46:47], v[22:23], v[30:31]
	v_pk_fma_f32 v[80:81], v[72:73], v[96:97], v[40:41] op_sel_hi:[1,0,1]
	v_pk_fma_f32 v[82:83], v[74:75], v[96:97], v[42:43] op_sel_hi:[1,0,1]
	v_pk_fma_f32 v[84:85], v[76:77], v[96:97], v[44:45] op_sel_hi:[1,0,1]
	v_pk_fma_f32 v[86:87], v[78:79], v[96:97], v[46:47] op_sel_hi:[1,0,1]
	v_pk_mul_f32 v[80:81], v[80:81], v[64:65]
	v_pk_mul_f32 v[82:83], v[82:83], v[66:67]
	v_pk_mul_f32 v[84:85], v[84:85], v[68:69]
	v_pk_mul_f32 v[86:87], v[86:87], v[70:71]
	v_cvt_pk_bf16_f32 v72, v80, v81
	v_cvt_pk_bf16_f32 v73, v82, v83
	v_cvt_pk_bf16_f32 v74, v84, v85
	v_cvt_pk_bf16_f32 v75, v86, v87
	global_store_dwordx4 v1, v[72:75], s[8:9]
	s_add_u32 s8, s8, 0x400
	s_addc_u32 s9, s9, 0
	global_load_dwordx4 v[170:173], v1, s[6:7]
	global_load_dwordx4 v[174:177], v1, s[10:11]
	global_load_dwordx4 v[178:181], v1, s[12:13]
	global_load_dword v182, v3, s[14:15]
	s_add_u32 s6, s6, 0x400
	s_addc_u32 s7, s7, 0
	s_add_u32 s10, s10, 0xe00
	s_addc_u32 s11, s11, 0
	s_add_u32 s12, s12, 0xc00
	s_addc_u32 s13, s13, 0
	s_add_u32 s14, s14, 32
	s_addc_u32 s15, s15, 0
	s_waitcnt vmcnt(35)
	v_lshlrev_b32_e32 v40, 16, v212
	v_and_b32_e32 v41, 0xffff0000, v212
	v_lshlrev_b32_e32 v42, 16, v213
	v_and_b32_e32 v43, 0xffff0000, v213
	v_lshlrev_b32_e32 v44, 16, v214
	v_and_b32_e32 v45, 0xffff0000, v214
	v_lshlrev_b32_e32 v46, 16, v215
	v_and_b32_e32 v47, 0xffff0000, v215
	v_pk_add_f32 v[88:89], v[40:41], v[42:43]
	v_pk_add_f32 v[88:89], v[88:89], v[44:45]
	v_pk_add_f32 v[88:89], v[88:89], v[46:47]
	v_add_f32_e32 v90, v88, v89
	v_lshlrev_b32_e32 v48, 16, v216
	v_and_b32_e32 v49, 0xffff0000, v216
	v_lshlrev_b32_e32 v50, 16, v217
	v_and_b32_e32 v51, 0xffff0000, v217
	v_lshlrev_b32_e32 v52, 16, v218
	v_and_b32_e32 v53, 0xffff0000, v218
	v_lshlrev_b32_e32 v54, 16, v219
	v_and_b32_e32 v55, 0xffff0000, v219
	v_add_f32_dpp v90, v90, v90 quad_perm:[1,0,3,2] row_mask:0xf bank_mask:0xf
	v_lshlrev_b32_e32 v64, 16, v220
	v_and_b32_e32 v65, 0xffff0000, v220
	v_lshlrev_b32_e32 v66, 16, v221
	v_and_b32_e32 v67, 0xffff0000, v221
	v_add_f32_dpp v90, v90, v90 quad_perm:[2,3,0,1] row_mask:0xf bank_mask:0xf
	v_lshlrev_b32_e32 v68, 16, v222
	v_and_b32_e32 v69, 0xffff0000, v222
	v_lshlrev_b32_e32 v70, 16, v223
	v_and_b32_e32 v71, 0xffff0000, v223
	v_add_f32_dpp v90, v90, v90 row_half_mirror row_mask:0xf bank_mask:0xf
	v_pk_add_f32 v[72:73], v[56:57], v[48:49] neg_lo:[0,1] neg_hi:[0,1]
	v_pk_add_f32 v[74:75], v[58:59], v[50:51] neg_lo:[0,1] neg_hi:[0,1]
	v_pk_add_f32 v[76:77], v[60:61], v[52:53] neg_lo:[0,1] neg_hi:[0,1]
	v_pk_add_f32 v[78:79], v[62:63], v[54:55] neg_lo:[0,1] neg_hi:[0,1]
	v_mul_f32_e32 v92, 0x3c800000, v90
	v_mov_b32_e32 v96, v224
	v_pk_add_f32 v[40:41], v[40:41], v[92:93] op_sel_hi:[1,0] neg_lo:[0,1] neg_hi:[0,1]
	v_pk_add_f32 v[42:43], v[42:43], v[92:93] op_sel_hi:[1,0] neg_lo:[0,1] neg_hi:[0,1]
	v_pk_add_f32 v[44:45], v[44:45], v[92:93] op_sel_hi:[1,0] neg_lo:[0,1] neg_hi:[0,1]
	v_pk_add_f32 v[46:47], v[46:47], v[92:93] op_sel_hi:[1,0] neg_lo:[0,1] neg_hi:[0,1]
	v_pk_mul_f32 v[88:89], v[40:41], v[40:41]
	v_pk_fma_f32 v[88:89], v[42:43], v[42:43], v[88:89]
	v_pk_fma_f32 v[88:89], v[44:45], v[44:45], v[88:89]
	v_pk_fma_f32 v[88:89], v[46:47], v[46:47], v[88:89]
	v_add_f32_e32 v91, v88, v89
	v_pk_fma_f32 v[72:73], v[72:73], v[8:9], v[48:49]
	v_pk_fma_f32 v[74:75], v[74:75], v[10:11], v[50:51]
	v_add_f32_dpp v91, v91, v91 quad_perm:[1,0,3,2] row_mask:0xf bank_mask:0xf
	v_pk_fma_f32 v[76:77], v[76:77], v[12:13], v[52:53]
	v_pk_fma_f32 v[78:79], v[78:79], v[14:15], v[54:55]
	v_add_f32_dpp v91, v91, v91 quad_perm:[2,3,0,1] row_mask:0xf bank_mask:0xf
	s_nop 1
	v_add_f32_dpp v91, v91, v91 row_half_mirror row_mask:0xf bank_mask:0xf
	s_nop 0
	v_fmamk_f32 v94, v91, 0x3c800000, v5
	v_rsq_f32_e32 v94, v94
	s_nop 0
	v_pk_mul_f32 v[40:41], v[40:41], v[94:95] op_sel_hi:[1,0]
	v_pk_mul_f32 v[42:43], v[42:43], v[94:95] op_sel_hi:[1,0]
	v_pk_mul_f32 v[44:45], v[44:45], v[94:95] op_sel_hi:[1,0]
	v_pk_mul_f32 v[46:47], v[46:47], v[94:95] op_sel_hi:[1,0]
	v_pk_fma_f32 v[40:41], v[40:41], v[16:17], v[24:25]
	v_pk_fma_f32 v[42:43], v[42:43], v[18:19], v[26:27]
	v_pk_fma_f32 v[44:45], v[44:45], v[20:21], v[28:29]
	v_pk_fma_f32 v[46:47], v[46:47], v[22:23], v[30:31]
	v_pk_fma_f32 v[80:81], v[72:73], v[96:97], v[40:41] op_sel_hi:[1,0,1]
	v_pk_fma_f32 v[82:83], v[74:75], v[96:97], v[42:43] op_sel_hi:[1,0,1]
	v_pk_fma_f32 v[84:85], v[76:77], v[96:97], v[44:45] op_sel_hi:[1,0,1]
	v_pk_fma_f32 v[86:87], v[78:79], v[96:97], v[46:47] op_sel_hi:[1,0,1]
	v_pk_mul_f32 v[80:81], v[80:81], v[64:65]
	v_pk_mul_f32 v[82:83], v[82:83], v[66:67]
	v_pk_mul_f32 v[84:85], v[84:85], v[68:69]
	v_pk_mul_f32 v[86:87], v[86:87], v[70:71]
	v_cvt_pk_bf16_f32 v72, v80, v81
	v_cvt_pk_bf16_f32 v73, v82, v83
	v_cvt_pk_bf16_f32 v74, v84, v85
	v_cvt_pk_bf16_f32 v75, v86, v87
	global_store_dwordx4 v1, v[72:75], s[8:9]
	s_add_u32 s8, s8, 0x400
	s_addc_u32 s9, s9, 0
	global_load_dwordx4 v[184:187], v1, s[6:7]
	global_load_dwordx4 v[188:191], v1, s[10:11]
	global_load_dwordx4 v[192:195], v1, s[12:13]
	global_load_dword v196, v3, s[14:15]
	s_add_u32 s6, s6, 0x400
	s_addc_u32 s7, s7, 0
	s_add_u32 s10, s10, 0xe00
	s_addc_u32 s11, s11, 0
	s_add_u32 s12, s12, 0xc00
	s_addc_u32 s13, s13, 0
	s_add_u32 s14, s14, 32
	s_addc_u32 s15, s15, 0
	s_waitcnt vmcnt(35)
	v_lshlrev_b32_e32 v40, 16, v226
	v_and_b32_e32 v41, 0xffff0000, v226
	v_lshlrev_b32_e32 v42, 16, v227
	v_and_b32_e32 v43, 0xffff0000, v227
	v_lshlrev_b32_e32 v44, 16, v228
	v_and_b32_e32 v45, 0xffff0000, v228
	v_lshlrev_b32_e32 v46, 16, v229
	v_and_b32_e32 v47, 0xffff0000, v229
	v_pk_add_f32 v[88:89], v[40:41], v[42:43]
	v_pk_add_f32 v[88:89], v[88:89], v[44:45]
	v_pk_add_f32 v[88:89], v[88:89], v[46:47]
	v_add_f32_e32 v90, v88, v89
	v_lshlrev_b32_e32 v56, 16, v230
	v_and_b32_e32 v57, 0xffff0000, v230
	v_lshlrev_b32_e32 v58, 16, v231
	v_and_b32_e32 v59, 0xffff0000, v231
	v_lshlrev_b32_e32 v60, 16, v232
	v_and_b32_e32 v61, 0xffff0000, v232
	v_lshlrev_b32_e32 v62, 16, v233
	v_and_b32_e32 v63, 0xffff0000, v233
	v_add_f32_dpp v90, v90, v90 quad_perm:[1,0,3,2] row_mask:0xf bank_mask:0xf
	v_lshlrev_b32_e32 v64, 16, v234
	v_and_b32_e32 v65, 0xffff0000, v234
	v_lshlrev_b32_e32 v66, 16, v235
	v_and_b32_e32 v67, 0xffff0000, v235
	v_add_f32_dpp v90, v90, v90 quad_perm:[2,3,0,1] row_mask:0xf bank_mask:0xf
	v_lshlrev_b32_e32 v68, 16, v236
	v_and_b32_e32 v69, 0xffff0000, v236
	v_lshlrev_b32_e32 v70, 16, v237
	v_and_b32_e32 v71, 0xffff0000, v237
	v_add_f32_dpp v90, v90, v90 row_half_mirror row_mask:0xf bank_mask:0xf
	v_pk_add_f32 v[72:73], v[48:49], v[56:57] neg_lo:[0,1] neg_hi:[0,1]
	v_pk_add_f32 v[74:75], v[50:51], v[58:59] neg_lo:[0,1] neg_hi:[0,1]
	v_pk_add_f32 v[76:77], v[52:53], v[60:61] neg_lo:[0,1] neg_hi:[0,1]
	v_pk_add_f32 v[78:79], v[54:55], v[62:63] neg_lo:[0,1] neg_hi:[0,1]
	v_mul_f32_e32 v92, 0x3c800000, v90
	v_mov_b32_e32 v96, v238
	v_pk_add_f32 v[40:41], v[40:41], v[92:93] op_sel_hi:[1,0] neg_lo:[0,1] neg_hi:[0,1]
	v_pk_add_f32 v[42:43], v[42:43], v[92:93] op_sel_hi:[1,0] neg_lo:[0,1] neg_hi:[0,1]
	v_pk_add_f32 v[44:45], v[44:45], v[92:93] op_sel_hi:[1,0] neg_lo:[0,1] neg_hi:[0,1]
	v_pk_add_f32 v[46:47], v[46:47], v[92:93] op_sel_hi:[1,0] neg_lo:[0,1] neg_hi:[0,1]
	v_pk_mul_f32 v[88:89], v[40:41], v[40:41]
	v_pk_fma_f32 v[88:89], v[42:43], v[42:43], v[88:89]
	v_pk_fma_f32 v[88:89], v[44:45], v[44:45], v[88:89]
	v_pk_fma_f32 v[88:89], v[46:47], v[46:47], v[88:89]
	v_add_f32_e32 v91, v88, v89
	v_pk_fma_f32 v[72:73], v[72:73], v[8:9], v[56:57]
	v_pk_fma_f32 v[74:75], v[74:75], v[10:11], v[58:59]
	v_add_f32_dpp v91, v91, v91 quad_perm:[1,0,3,2] row_mask:0xf bank_mask:0xf
	v_pk_fma_f32 v[76:77], v[76:77], v[12:13], v[60:61]
	v_pk_fma_f32 v[78:79], v[78:79], v[14:15], v[62:63]
	v_add_f32_dpp v91, v91, v91 quad_perm:[2,3,0,1] row_mask:0xf bank_mask:0xf
	s_nop 1
	v_add_f32_dpp v91, v91, v91 row_half_mirror row_mask:0xf bank_mask:0xf
	s_nop 0
	v_fmamk_f32 v94, v91, 0x3c800000, v5
	v_rsq_f32_e32 v94, v94
	s_nop 0
	v_pk_mul_f32 v[40:41], v[40:41], v[94:95] op_sel_hi:[1,0]
	v_pk_mul_f32 v[42:43], v[42:43], v[94:95] op_sel_hi:[1,0]
	v_pk_mul_f32 v[44:45], v[44:45], v[94:95] op_sel_hi:[1,0]
	v_pk_mul_f32 v[46:47], v[46:47], v[94:95] op_sel_hi:[1,0]
	v_pk_fma_f32 v[40:41], v[40:41], v[16:17], v[24:25]
	v_pk_fma_f32 v[42:43], v[42:43], v[18:19], v[26:27]
	v_pk_fma_f32 v[44:45], v[44:45], v[20:21], v[28:29]
	v_pk_fma_f32 v[46:47], v[46:47], v[22:23], v[30:31]
	v_pk_fma_f32 v[80:81], v[72:73], v[96:97], v[40:41] op_sel_hi:[1,0,1]
	v_pk_fma_f32 v[82:83], v[74:75], v[96:97], v[42:43] op_sel_hi:[1,0,1]
	v_pk_fma_f32 v[84:85], v[76:77], v[96:97], v[44:45] op_sel_hi:[1,0,1]
	v_pk_fma_f32 v[86:87], v[78:79], v[96:97], v[46:47] op_sel_hi:[1,0,1]
	v_pk_mul_f32 v[80:81], v[80:81], v[64:65]
	v_pk_mul_f32 v[82:83], v[82:83], v[66:67]
	v_pk_mul_f32 v[84:85], v[84:85], v[68:69]
	v_pk_mul_f32 v[86:87], v[86:87], v[70:71]
	v_cvt_pk_bf16_f32 v72, v80, v81
	v_cvt_pk_bf16_f32 v73, v82, v83
	v_cvt_pk_bf16_f32 v74, v84, v85
	v_cvt_pk_bf16_f32 v75, v86, v87
	global_store_dwordx4 v1, v[72:75], s[8:9]
	s_add_u32 s8, s8, 0x400
	s_addc_u32 s9, s9, 0
	global_load_dwordx4 v[198:201], v1, s[6:7]
	global_load_dwordx4 v[202:205], v1, s[10:11]
	global_load_dwordx4 v[206:209], v1, s[12:13]
	global_load_dword v210, v3, s[14:15]
	s_add_u32 s6, s6, 0x400
	s_addc_u32 s7, s7, 0
	s_add_u32 s10, s10, 0xe00
	s_addc_u32 s11, s11, 0
	s_add_u32 s12, s12, 0xc00
	s_addc_u32 s13, s13, 0
	s_add_u32 s14, s14, 32
	s_addc_u32 s15, s15, 0
	s_waitcnt vmcnt(35)
	v_lshlrev_b32_e32 v40, 16, v100
	v_and_b32_e32 v41, 0xffff0000, v100
	v_lshlrev_b32_e32 v42, 16, v101
	v_and_b32_e32 v43, 0xffff0000, v101
	v_lshlrev_b32_e32 v44, 16, v102
	v_and_b32_e32 v45, 0xffff0000, v102
	v_lshlrev_b32_e32 v46, 16, v103
	v_and_b32_e32 v47, 0xffff0000, v103
	v_pk_add_f32 v[88:89], v[40:41], v[42:43]
	v_pk_add_f32 v[88:89], v[88:89], v[44:45]
	v_pk_add_f32 v[88:89], v[88:89], v[46:47]
	v_add_f32_e32 v90, v88, v89
	v_lshlrev_b32_e32 v48, 16, v104
	v_and_b32_e32 v49, 0xffff0000, v104
	v_lshlrev_b32_e32 v50, 16, v105
	v_and_b32_e32 v51, 0xffff0000, v105
	v_lshlrev_b32_e32 v52, 16, v106
	v_and_b32_e32 v53, 0xffff0000, v106
	v_lshlrev_b32_e32 v54, 16, v107
	v_and_b32_e32 v55, 0xffff0000, v107
	v_add_f32_dpp v90, v90, v90 quad_perm:[1,0,3,2] row_mask:0xf bank_mask:0xf
	v_lshlrev_b32_e32 v64, 16, v108
	v_and_b32_e32 v65, 0xffff0000, v108
	v_lshlrev_b32_e32 v66, 16, v109
	v_and_b32_e32 v67, 0xffff0000, v109
	v_add_f32_dpp v90, v90, v90 quad_perm:[2,3,0,1] row_mask:0xf bank_mask:0xf
	v_lshlrev_b32_e32 v68, 16, v110
	v_and_b32_e32 v69, 0xffff0000, v110
	v_lshlrev_b32_e32 v70, 16, v111
	v_and_b32_e32 v71, 0xffff0000, v111
	v_add_f32_dpp v90, v90, v90 row_half_mirror row_mask:0xf bank_mask:0xf
	v_pk_add_f32 v[72:73], v[56:57], v[48:49] neg_lo:[0,1] neg_hi:[0,1]
	v_pk_add_f32 v[74:75], v[58:59], v[50:51] neg_lo:[0,1] neg_hi:[0,1]
	v_pk_add_f32 v[76:77], v[60:61], v[52:53] neg_lo:[0,1] neg_hi:[0,1]
	v_pk_add_f32 v[78:79], v[62:63], v[54:55] neg_lo:[0,1] neg_hi:[0,1]
	v_mul_f32_e32 v92, 0x3c800000, v90
	v_mov_b32_e32 v96, v112
	v_pk_add_f32 v[40:41], v[40:41], v[92:93] op_sel_hi:[1,0] neg_lo:[0,1] neg_hi:[0,1]
	v_pk_add_f32 v[42:43], v[42:43], v[92:93] op_sel_hi:[1,0] neg_lo:[0,1] neg_hi:[0,1]
	v_pk_add_f32 v[44:45], v[44:45], v[92:93] op_sel_hi:[1,0] neg_lo:[0,1] neg_hi:[0,1]
	v_pk_add_f32 v[46:47], v[46:47], v[92:93] op_sel_hi:[1,0] neg_lo:[0,1] neg_hi:[0,1]
	v_pk_mul_f32 v[88:89], v[40:41], v[40:41]
	v_pk_fma_f32 v[88:89], v[42:43], v[42:43], v[88:89]
	v_pk_fma_f32 v[88:89], v[44:45], v[44:45], v[88:89]
	v_pk_fma_f32 v[88:89], v[46:47], v[46:47], v[88:89]
	v_add_f32_e32 v91, v88, v89
	v_pk_fma_f32 v[72:73], v[72:73], v[8:9], v[48:49]
	v_pk_fma_f32 v[74:75], v[74:75], v[10:11], v[50:51]
	v_add_f32_dpp v91, v91, v91 quad_perm:[1,0,3,2] row_mask:0xf bank_mask:0xf
	v_pk_fma_f32 v[76:77], v[76:77], v[12:13], v[52:53]
	v_pk_fma_f32 v[78:79], v[78:79], v[14:15], v[54:55]
	v_add_f32_dpp v91, v91, v91 quad_perm:[2,3,0,1] row_mask:0xf bank_mask:0xf
	s_nop 1
	v_add_f32_dpp v91, v91, v91 row_half_mirror row_mask:0xf bank_mask:0xf
	s_nop 0
	v_fmamk_f32 v94, v91, 0x3c800000, v5
	v_rsq_f32_e32 v94, v94
	s_nop 0
	v_pk_mul_f32 v[40:41], v[40:41], v[94:95] op_sel_hi:[1,0]
	v_pk_mul_f32 v[42:43], v[42:43], v[94:95] op_sel_hi:[1,0]
	v_pk_mul_f32 v[44:45], v[44:45], v[94:95] op_sel_hi:[1,0]
	v_pk_mul_f32 v[46:47], v[46:47], v[94:95] op_sel_hi:[1,0]
	v_pk_fma_f32 v[40:41], v[40:41], v[16:17], v[24:25]
	v_pk_fma_f32 v[42:43], v[42:43], v[18:19], v[26:27]
	v_pk_fma_f32 v[44:45], v[44:45], v[20:21], v[28:29]
	v_pk_fma_f32 v[46:47], v[46:47], v[22:23], v[30:31]
	v_pk_fma_f32 v[80:81], v[72:73], v[96:97], v[40:41] op_sel_hi:[1,0,1]
	v_pk_fma_f32 v[82:83], v[74:75], v[96:97], v[42:43] op_sel_hi:[1,0,1]
	v_pk_fma_f32 v[84:85], v[76:77], v[96:97], v[44:45] op_sel_hi:[1,0,1]
	v_pk_fma_f32 v[86:87], v[78:79], v[96:97], v[46:47] op_sel_hi:[1,0,1]
	v_pk_mul_f32 v[80:81], v[80:81], v[64:65]
	v_pk_mul_f32 v[82:83], v[82:83], v[66:67]
	v_pk_mul_f32 v[84:85], v[84:85], v[68:69]
	v_pk_mul_f32 v[86:87], v[86:87], v[70:71]
	v_cvt_pk_bf16_f32 v72, v80, v81
	v_cvt_pk_bf16_f32 v73, v82, v83
	v_cvt_pk_bf16_f32 v74, v84, v85
	v_cvt_pk_bf16_f32 v75, v86, v87
	global_store_dwordx4 v1, v[72:75], s[8:9]
	s_add_u32 s8, s8, 0x400
	s_addc_u32 s9, s9, 0
	global_load_dwordx4 v[212:215], v1, s[6:7]
	global_load_dwordx4 v[216:219], v1, s[10:11]
	global_load_dwordx4 v[220:223], v1, s[12:13]
	global_load_dword v224, v3, s[14:15]
	s_add_u32 s6, s6, 0x400
	s_addc_u32 s7, s7, 0
	s_add_u32 s10, s10, 0xe00
	s_addc_u32 s11, s11, 0
	s_add_u32 s12, s12, 0xc00
	s_addc_u32 s13, s13, 0
	s_add_u32 s14, s14, 32
	s_addc_u32 s15, s15, 0
	s_waitcnt vmcnt(35)
	v_lshlrev_b32_e32 v40, 16, v114
	v_and_b32_e32 v41, 0xffff0000, v114
	v_lshlrev_b32_e32 v42, 16, v115
	v_and_b32_e32 v43, 0xffff0000, v115
	v_lshlrev_b32_e32 v44, 16, v116
	v_and_b32_e32 v45, 0xffff0000, v116
	v_lshlrev_b32_e32 v46, 16, v117
	v_and_b32_e32 v47, 0xffff0000, v117
	v_pk_add_f32 v[88:89], v[40:41], v[42:43]
	v_pk_add_f32 v[88:89], v[88:89], v[44:45]
	v_pk_add_f32 v[88:89], v[88:89], v[46:47]
	v_add_f32_e32 v90, v88, v89
	v_lshlrev_b32_e32 v56, 16, v118
	v_and_b32_e32 v57, 0xffff0000, v118
	v_lshlrev_b32_e32 v58, 16, v119
	v_and_b32_e32 v59, 0xffff0000, v119
	v_lshlrev_b32_e32 v60, 16, v120
	v_and_b32_e32 v61, 0xffff0000, v120
	v_lshlrev_b32_e32 v62, 16, v121
	v_and_b32_e32 v63, 0xffff0000, v121
	v_add_f32_dpp v90, v90, v90 quad_perm:[1,0,3,2] row_mask:0xf bank_mask:0xf
	v_lshlrev_b32_e32 v64, 16, v122
	v_and_b32_e32 v65, 0xffff0000, v122
	v_lshlrev_b32_e32 v66, 16, v123
	v_and_b32_e32 v67, 0xffff0000, v123
	v_add_f32_dpp v90, v90, v90 quad_perm:[2,3,0,1] row_mask:0xf bank_mask:0xf
	v_lshlrev_b32_e32 v68, 16, v124
	v_and_b32_e32 v69, 0xffff0000, v124
	v_lshlrev_b32_e32 v70, 16, v125
	v_and_b32_e32 v71, 0xffff0000, v125
	v_add_f32_dpp v90, v90, v90 row_half_mirror row_mask:0xf bank_mask:0xf
	v_pk_add_f32 v[72:73], v[48:49], v[56:57] neg_lo:[0,1] neg_hi:[0,1]
	v_pk_add_f32 v[74:75], v[50:51], v[58:59] neg_lo:[0,1] neg_hi:[0,1]
	v_pk_add_f32 v[76:77], v[52:53], v[60:61] neg_lo:[0,1] neg_hi:[0,1]
	v_pk_add_f32 v[78:79], v[54:55], v[62:63] neg_lo:[0,1] neg_hi:[0,1]
	v_mul_f32_e32 v92, 0x3c800000, v90
	v_mov_b32_e32 v96, v126
	v_pk_add_f32 v[40:41], v[40:41], v[92:93] op_sel_hi:[1,0] neg_lo:[0,1] neg_hi:[0,1]
	v_pk_add_f32 v[42:43], v[42:43], v[92:93] op_sel_hi:[1,0] neg_lo:[0,1] neg_hi:[0,1]
	v_pk_add_f32 v[44:45], v[44:45], v[92:93] op_sel_hi:[1,0] neg_lo:[0,1] neg_hi:[0,1]
	v_pk_add_f32 v[46:47], v[46:47], v[92:93] op_sel_hi:[1,0] neg_lo:[0,1] neg_hi:[0,1]
	v_pk_mul_f32 v[88:89], v[40:41], v[40:41]
	v_pk_fma_f32 v[88:89], v[42:43], v[42:43], v[88:89]
	v_pk_fma_f32 v[88:89], v[44:45], v[44:45], v[88:89]
	v_pk_fma_f32 v[88:89], v[46:47], v[46:47], v[88:89]
	v_add_f32_e32 v91, v88, v89
	v_pk_fma_f32 v[72:73], v[72:73], v[8:9], v[56:57]
	v_pk_fma_f32 v[74:75], v[74:75], v[10:11], v[58:59]
	v_add_f32_dpp v91, v91, v91 quad_perm:[1,0,3,2] row_mask:0xf bank_mask:0xf
	v_pk_fma_f32 v[76:77], v[76:77], v[12:13], v[60:61]
	v_pk_fma_f32 v[78:79], v[78:79], v[14:15], v[62:63]
	v_add_f32_dpp v91, v91, v91 quad_perm:[2,3,0,1] row_mask:0xf bank_mask:0xf
	s_nop 1
	v_add_f32_dpp v91, v91, v91 row_half_mirror row_mask:0xf bank_mask:0xf
	s_nop 0
	v_fmamk_f32 v94, v91, 0x3c800000, v5
	v_rsq_f32_e32 v94, v94
	s_nop 0
	v_pk_mul_f32 v[40:41], v[40:41], v[94:95] op_sel_hi:[1,0]
	v_pk_mul_f32 v[42:43], v[42:43], v[94:95] op_sel_hi:[1,0]
	v_pk_mul_f32 v[44:45], v[44:45], v[94:95] op_sel_hi:[1,0]
	v_pk_mul_f32 v[46:47], v[46:47], v[94:95] op_sel_hi:[1,0]
	v_pk_fma_f32 v[40:41], v[40:41], v[16:17], v[24:25]
	v_pk_fma_f32 v[42:43], v[42:43], v[18:19], v[26:27]
	v_pk_fma_f32 v[44:45], v[44:45], v[20:21], v[28:29]
	v_pk_fma_f32 v[46:47], v[46:47], v[22:23], v[30:31]
	v_pk_fma_f32 v[80:81], v[72:73], v[96:97], v[40:41] op_sel_hi:[1,0,1]
	v_pk_fma_f32 v[82:83], v[74:75], v[96:97], v[42:43] op_sel_hi:[1,0,1]
	v_pk_fma_f32 v[84:85], v[76:77], v[96:97], v[44:45] op_sel_hi:[1,0,1]
	v_pk_fma_f32 v[86:87], v[78:79], v[96:97], v[46:47] op_sel_hi:[1,0,1]
	v_pk_mul_f32 v[80:81], v[80:81], v[64:65]
	v_pk_mul_f32 v[82:83], v[82:83], v[66:67]
	v_pk_mul_f32 v[84:85], v[84:85], v[68:69]
	v_pk_mul_f32 v[86:87], v[86:87], v[70:71]
	v_cvt_pk_bf16_f32 v72, v80, v81
	v_cvt_pk_bf16_f32 v73, v82, v83
	v_cvt_pk_bf16_f32 v74, v84, v85
	v_cvt_pk_bf16_f32 v75, v86, v87
	global_store_dwordx4 v1, v[72:75], s[8:9]
	s_add_u32 s8, s8, 0x400
	s_addc_u32 s9, s9, 0
	global_load_dwordx4 v[226:229], v1, s[6:7]
	global_load_dwordx4 v[230:233], v1, s[10:11]
	global_load_dwordx4 v[234:237], v1, s[12:13]
	global_load_dword v238, v3, s[14:15]
	s_add_u32 s6, s6, 0x400
	s_addc_u32 s7, s7, 0
	s_add_u32 s10, s10, 0xe00
	s_addc_u32 s11, s11, 0
	s_add_u32 s12, s12, 0xc00
	s_addc_u32 s13, s13, 0
	s_add_u32 s14, s14, 32
	s_addc_u32 s15, s15, 0
	s_waitcnt vmcnt(35)
	v_lshlrev_b32_e32 v40, 16, v128
	v_and_b32_e32 v41, 0xffff0000, v128
	v_lshlrev_b32_e32 v42, 16, v129
	v_and_b32_e32 v43, 0xffff0000, v129
	v_lshlrev_b32_e32 v44, 16, v130
	v_and_b32_e32 v45, 0xffff0000, v130
	v_lshlrev_b32_e32 v46, 16, v131
	v_and_b32_e32 v47, 0xffff0000, v131
	v_pk_add_f32 v[88:89], v[40:41], v[42:43]
	v_pk_add_f32 v[88:89], v[88:89], v[44:45]
	v_pk_add_f32 v[88:89], v[88:89], v[46:47]
	v_add_f32_e32 v90, v88, v89
	v_lshlrev_b32_e32 v48, 16, v132
	v_and_b32_e32 v49, 0xffff0000, v132
	v_lshlrev_b32_e32 v50, 16, v133
	v_and_b32_e32 v51, 0xffff0000, v133
	v_lshlrev_b32_e32 v52, 16, v134
	v_and_b32_e32 v53, 0xffff0000, v134
	v_lshlrev_b32_e32 v54, 16, v135
	v_and_b32_e32 v55, 0xffff0000, v135
	v_add_f32_dpp v90, v90, v90 quad_perm:[1,0,3,2] row_mask:0xf bank_mask:0xf
	v_lshlrev_b32_e32 v64, 16, v136
	v_and_b32_e32 v65, 0xffff0000, v136
	v_lshlrev_b32_e32 v66, 16, v137
	v_and_b32_e32 v67, 0xffff0000, v137
	v_add_f32_dpp v90, v90, v90 quad_perm:[2,3,0,1] row_mask:0xf bank_mask:0xf
	v_lshlrev_b32_e32 v68, 16, v138
	v_and_b32_e32 v69, 0xffff0000, v138
	v_lshlrev_b32_e32 v70, 16, v139
	v_and_b32_e32 v71, 0xffff0000, v139
	v_add_f32_dpp v90, v90, v90 row_half_mirror row_mask:0xf bank_mask:0xf
	v_pk_add_f32 v[72:73], v[56:57], v[48:49] neg_lo:[0,1] neg_hi:[0,1]
	v_pk_add_f32 v[74:75], v[58:59], v[50:51] neg_lo:[0,1] neg_hi:[0,1]
	v_pk_add_f32 v[76:77], v[60:61], v[52:53] neg_lo:[0,1] neg_hi:[0,1]
	v_pk_add_f32 v[78:79], v[62:63], v[54:55] neg_lo:[0,1] neg_hi:[0,1]
	v_mul_f32_e32 v92, 0x3c800000, v90
	v_mov_b32_e32 v96, v140
	v_pk_add_f32 v[40:41], v[40:41], v[92:93] op_sel_hi:[1,0] neg_lo:[0,1] neg_hi:[0,1]
	v_pk_add_f32 v[42:43], v[42:43], v[92:93] op_sel_hi:[1,0] neg_lo:[0,1] neg_hi:[0,1]
	v_pk_add_f32 v[44:45], v[44:45], v[92:93] op_sel_hi:[1,0] neg_lo:[0,1] neg_hi:[0,1]
	v_pk_add_f32 v[46:47], v[46:47], v[92:93] op_sel_hi:[1,0] neg_lo:[0,1] neg_hi:[0,1]
	v_pk_mul_f32 v[88:89], v[40:41], v[40:41]
	v_pk_fma_f32 v[88:89], v[42:43], v[42:43], v[88:89]
	v_pk_fma_f32 v[88:89], v[44:45], v[44:45], v[88:89]
	v_pk_fma_f32 v[88:89], v[46:47], v[46:47], v[88:89]
	v_add_f32_e32 v91, v88, v89
	v_pk_fma_f32 v[72:73], v[72:73], v[8:9], v[48:49]
	v_pk_fma_f32 v[74:75], v[74:75], v[10:11], v[50:51]
	v_add_f32_dpp v91, v91, v91 quad_perm:[1,0,3,2] row_mask:0xf bank_mask:0xf
	v_pk_fma_f32 v[76:77], v[76:77], v[12:13], v[52:53]
	v_pk_fma_f32 v[78:79], v[78:79], v[14:15], v[54:55]
	v_add_f32_dpp v91, v91, v91 quad_perm:[2,3,0,1] row_mask:0xf bank_mask:0xf
	s_nop 1
	v_add_f32_dpp v91, v91, v91 row_half_mirror row_mask:0xf bank_mask:0xf
	s_nop 0
	v_fmamk_f32 v94, v91, 0x3c800000, v5
	v_rsq_f32_e32 v94, v94
	s_nop 0
	v_pk_mul_f32 v[40:41], v[40:41], v[94:95] op_sel_hi:[1,0]
	v_pk_mul_f32 v[42:43], v[42:43], v[94:95] op_sel_hi:[1,0]
	v_pk_mul_f32 v[44:45], v[44:45], v[94:95] op_sel_hi:[1,0]
	v_pk_mul_f32 v[46:47], v[46:47], v[94:95] op_sel_hi:[1,0]
	v_pk_fma_f32 v[40:41], v[40:41], v[16:17], v[24:25]
	v_pk_fma_f32 v[42:43], v[42:43], v[18:19], v[26:27]
	v_pk_fma_f32 v[44:45], v[44:45], v[20:21], v[28:29]
	v_pk_fma_f32 v[46:47], v[46:47], v[22:23], v[30:31]
	v_pk_fma_f32 v[80:81], v[72:73], v[96:97], v[40:41] op_sel_hi:[1,0,1]
	v_pk_fma_f32 v[82:83], v[74:75], v[96:97], v[42:43] op_sel_hi:[1,0,1]
	v_pk_fma_f32 v[84:85], v[76:77], v[96:97], v[44:45] op_sel_hi:[1,0,1]
	v_pk_fma_f32 v[86:87], v[78:79], v[96:97], v[46:47] op_sel_hi:[1,0,1]
	v_pk_mul_f32 v[80:81], v[80:81], v[64:65]
	v_pk_mul_f32 v[82:83], v[82:83], v[66:67]
	v_pk_mul_f32 v[84:85], v[84:85], v[68:69]
	v_pk_mul_f32 v[86:87], v[86:87], v[70:71]
	v_cvt_pk_bf16_f32 v72, v80, v81
	v_cvt_pk_bf16_f32 v73, v82, v83
	v_cvt_pk_bf16_f32 v74, v84, v85
	v_cvt_pk_bf16_f32 v75, v86, v87
	global_store_dwordx4 v1, v[72:75], s[8:9]
	s_add_u32 s8, s8, 0x400
	s_addc_u32 s9, s9, 0
	global_load_dwordx4 v[100:103], v1, s[6:7]
	global_load_dwordx4 v[104:107], v1, s[10:11]
	global_load_dwordx4 v[108:111], v1, s[12:13]
	global_load_dword v112, v3, s[14:15]
	s_add_u32 s6, s6, 0x400
	s_addc_u32 s7, s7, 0
	s_add_u32 s10, s10, 0xe00
	s_addc_u32 s11, s11, 0
	s_add_u32 s12, s12, 0xc00
	s_addc_u32 s13, s13, 0
	s_add_u32 s14, s14, 32
	s_addc_u32 s15, s15, 0
	s_waitcnt vmcnt(35)
	v_lshlrev_b32_e32 v40, 16, v142
	v_and_b32_e32 v41, 0xffff0000, v142
	v_lshlrev_b32_e32 v42, 16, v143
	v_and_b32_e32 v43, 0xffff0000, v143
	v_lshlrev_b32_e32 v44, 16, v144
	v_and_b32_e32 v45, 0xffff0000, v144
	v_lshlrev_b32_e32 v46, 16, v145
	v_and_b32_e32 v47, 0xffff0000, v145
	v_pk_add_f32 v[88:89], v[40:41], v[42:43]
	v_pk_add_f32 v[88:89], v[88:89], v[44:45]
	v_pk_add_f32 v[88:89], v[88:89], v[46:47]
	v_add_f32_e32 v90, v88, v89
	v_lshlrev_b32_e32 v56, 16, v146
	v_and_b32_e32 v57, 0xffff0000, v146
	v_lshlrev_b32_e32 v58, 16, v147
	v_and_b32_e32 v59, 0xffff0000, v147
	v_lshlrev_b32_e32 v60, 16, v148
	v_and_b32_e32 v61, 0xffff0000, v148
	v_lshlrev_b32_e32 v62, 16, v149
	v_and_b32_e32 v63, 0xffff0000, v149
	v_add_f32_dpp v90, v90, v90 quad_perm:[1,0,3,2] row_mask:0xf bank_mask:0xf
	v_lshlrev_b32_e32 v64, 16, v150
	v_and_b32_e32 v65, 0xffff0000, v150
	v_lshlrev_b32_e32 v66, 16, v151
	v_and_b32_e32 v67, 0xffff0000, v151
	v_add_f32_dpp v90, v90, v90 quad_perm:[2,3,0,1] row_mask:0xf bank_mask:0xf
	v_lshlrev_b32_e32 v68, 16, v152
	v_and_b32_e32 v69, 0xffff0000, v152
	v_lshlrev_b32_e32 v70, 16, v153
	v_and_b32_e32 v71, 0xffff0000, v153
	v_add_f32_dpp v90, v90, v90 row_half_mirror row_mask:0xf bank_mask:0xf
	v_pk_add_f32 v[72:73], v[48:49], v[56:57] neg_lo:[0,1] neg_hi:[0,1]
	v_pk_add_f32 v[74:75], v[50:51], v[58:59] neg_lo:[0,1] neg_hi:[0,1]
	v_pk_add_f32 v[76:77], v[52:53], v[60:61] neg_lo:[0,1] neg_hi:[0,1]
	v_pk_add_f32 v[78:79], v[54:55], v[62:63] neg_lo:[0,1] neg_hi:[0,1]
	v_mul_f32_e32 v92, 0x3c800000, v90
	v_mov_b32_e32 v96, v154
	v_pk_add_f32 v[40:41], v[40:41], v[92:93] op_sel_hi:[1,0] neg_lo:[0,1] neg_hi:[0,1]
	v_pk_add_f32 v[42:43], v[42:43], v[92:93] op_sel_hi:[1,0] neg_lo:[0,1] neg_hi:[0,1]
	v_pk_add_f32 v[44:45], v[44:45], v[92:93] op_sel_hi:[1,0] neg_lo:[0,1] neg_hi:[0,1]
	v_pk_add_f32 v[46:47], v[46:47], v[92:93] op_sel_hi:[1,0] neg_lo:[0,1] neg_hi:[0,1]
	v_pk_mul_f32 v[88:89], v[40:41], v[40:41]
	v_pk_fma_f32 v[88:89], v[42:43], v[42:43], v[88:89]
	v_pk_fma_f32 v[88:89], v[44:45], v[44:45], v[88:89]
	v_pk_fma_f32 v[88:89], v[46:47], v[46:47], v[88:89]
	v_add_f32_e32 v91, v88, v89
	v_pk_fma_f32 v[72:73], v[72:73], v[8:9], v[56:57]
	v_pk_fma_f32 v[74:75], v[74:75], v[10:11], v[58:59]
	v_add_f32_dpp v91, v91, v91 quad_perm:[1,0,3,2] row_mask:0xf bank_mask:0xf
	v_pk_fma_f32 v[76:77], v[76:77], v[12:13], v[60:61]
	v_pk_fma_f32 v[78:79], v[78:79], v[14:15], v[62:63]
	v_add_f32_dpp v91, v91, v91 quad_perm:[2,3,0,1] row_mask:0xf bank_mask:0xf
	s_nop 1
	v_add_f32_dpp v91, v91, v91 row_half_mirror row_mask:0xf bank_mask:0xf
	s_nop 0
	v_fmamk_f32 v94, v91, 0x3c800000, v5
	v_rsq_f32_e32 v94, v94
	s_nop 0
	v_pk_mul_f32 v[40:41], v[40:41], v[94:95] op_sel_hi:[1,0]
	v_pk_mul_f32 v[42:43], v[42:43], v[94:95] op_sel_hi:[1,0]
	v_pk_mul_f32 v[44:45], v[44:45], v[94:95] op_sel_hi:[1,0]
	v_pk_mul_f32 v[46:47], v[46:47], v[94:95] op_sel_hi:[1,0]
	v_pk_fma_f32 v[40:41], v[40:41], v[16:17], v[24:25]
	v_pk_fma_f32 v[42:43], v[42:43], v[18:19], v[26:27]
	v_pk_fma_f32 v[44:45], v[44:45], v[20:21], v[28:29]
	v_pk_fma_f32 v[46:47], v[46:47], v[22:23], v[30:31]
	v_pk_fma_f32 v[80:81], v[72:73], v[96:97], v[40:41] op_sel_hi:[1,0,1]
	v_pk_fma_f32 v[82:83], v[74:75], v[96:97], v[42:43] op_sel_hi:[1,0,1]
	v_pk_fma_f32 v[84:85], v[76:77], v[96:97], v[44:45] op_sel_hi:[1,0,1]
	v_pk_fma_f32 v[86:87], v[78:79], v[96:97], v[46:47] op_sel_hi:[1,0,1]
	v_pk_mul_f32 v[80:81], v[80:81], v[64:65]
	v_pk_mul_f32 v[82:83], v[82:83], v[66:67]
	v_pk_mul_f32 v[84:85], v[84:85], v[68:69]
	v_pk_mul_f32 v[86:87], v[86:87], v[70:71]
	v_cvt_pk_bf16_f32 v72, v80, v81
	v_cvt_pk_bf16_f32 v73, v82, v83
	v_cvt_pk_bf16_f32 v74, v84, v85
	v_cvt_pk_bf16_f32 v75, v86, v87
	global_store_dwordx4 v1, v[72:75], s[8:9]
	s_add_u32 s8, s8, 0x400
	s_addc_u32 s9, s9, 0
	global_load_dwordx4 v[114:117], v1, s[6:7]
	global_load_dwordx4 v[118:121], v1, s[10:11]
	global_load_dwordx4 v[122:125], v1, s[12:13]
	global_load_dword v126, v3, s[14:15]
	s_add_u32 s6, s6, 0x400
	s_addc_u32 s7, s7, 0
	s_add_u32 s10, s10, 0xe00
	s_addc_u32 s11, s11, 0
	s_add_u32 s12, s12, 0xc00
	s_addc_u32 s13, s13, 0
	s_add_u32 s14, s14, 32
	s_addc_u32 s15, s15, 0
	s_waitcnt vmcnt(35)
	v_lshlrev_b32_e32 v40, 16, v156
	v_and_b32_e32 v41, 0xffff0000, v156
	v_lshlrev_b32_e32 v42, 16, v157
	v_and_b32_e32 v43, 0xffff0000, v157
	v_lshlrev_b32_e32 v44, 16, v158
	v_and_b32_e32 v45, 0xffff0000, v158
	v_lshlrev_b32_e32 v46, 16, v159
	v_and_b32_e32 v47, 0xffff0000, v159
	v_pk_add_f32 v[88:89], v[40:41], v[42:43]
	v_pk_add_f32 v[88:89], v[88:89], v[44:45]
	v_pk_add_f32 v[88:89], v[88:89], v[46:47]
	v_add_f32_e32 v90, v88, v89
	v_lshlrev_b32_e32 v48, 16, v160
	v_and_b32_e32 v49, 0xffff0000, v160
	v_lshlrev_b32_e32 v50, 16, v161
	v_and_b32_e32 v51, 0xffff0000, v161
	v_lshlrev_b32_e32 v52, 16, v162
	v_and_b32_e32 v53, 0xffff0000, v162
	v_lshlrev_b32_e32 v54, 16, v163
	v_and_b32_e32 v55, 0xffff0000, v163
	v_add_f32_dpp v90, v90, v90 quad_perm:[1,0,3,2] row_mask:0xf bank_mask:0xf
	v_lshlrev_b32_e32 v64, 16, v164
	v_and_b32_e32 v65, 0xffff0000, v164
	v_lshlrev_b32_e32 v66, 16, v165
	v_and_b32_e32 v67, 0xffff0000, v165
	v_add_f32_dpp v90, v90, v90 quad_perm:[2,3,0,1] row_mask:0xf bank_mask:0xf
	v_lshlrev_b32_e32 v68, 16, v166
	v_and_b32_e32 v69, 0xffff0000, v166
	v_lshlrev_b32_e32 v70, 16, v167
	v_and_b32_e32 v71, 0xffff0000, v167
	v_add_f32_dpp v90, v90, v90 row_half_mirror row_mask:0xf bank_mask:0xf
	v_pk_add_f32 v[72:73], v[56:57], v[48:49] neg_lo:[0,1] neg_hi:[0,1]
	v_pk_add_f32 v[74:75], v[58:59], v[50:51] neg_lo:[0,1] neg_hi:[0,1]
	v_pk_add_f32 v[76:77], v[60:61], v[52:53] neg_lo:[0,1] neg_hi:[0,1]
	v_pk_add_f32 v[78:79], v[62:63], v[54:55] neg_lo:[0,1] neg_hi:[0,1]
	v_mul_f32_e32 v92, 0x3c800000, v90
	v_mov_b32_e32 v96, v168
	v_pk_add_f32 v[40:41], v[40:41], v[92:93] op_sel_hi:[1,0] neg_lo:[0,1] neg_hi:[0,1]
	v_pk_add_f32 v[42:43], v[42:43], v[92:93] op_sel_hi:[1,0] neg_lo:[0,1] neg_hi:[0,1]
	v_pk_add_f32 v[44:45], v[44:45], v[92:93] op_sel_hi:[1,0] neg_lo:[0,1] neg_hi:[0,1]
	v_pk_add_f32 v[46:47], v[46:47], v[92:93] op_sel_hi:[1,0] neg_lo:[0,1] neg_hi:[0,1]
	v_pk_mul_f32 v[88:89], v[40:41], v[40:41]
	v_pk_fma_f32 v[88:89], v[42:43], v[42:43], v[88:89]
	v_pk_fma_f32 v[88:89], v[44:45], v[44:45], v[88:89]
	v_pk_fma_f32 v[88:89], v[46:47], v[46:47], v[88:89]
	v_add_f32_e32 v91, v88, v89
	v_pk_fma_f32 v[72:73], v[72:73], v[8:9], v[48:49]
	v_pk_fma_f32 v[74:75], v[74:75], v[10:11], v[50:51]
	v_add_f32_dpp v91, v91, v91 quad_perm:[1,0,3,2] row_mask:0xf bank_mask:0xf
	v_pk_fma_f32 v[76:77], v[76:77], v[12:13], v[52:53]
	v_pk_fma_f32 v[78:79], v[78:79], v[14:15], v[54:55]
	v_add_f32_dpp v91, v91, v91 quad_perm:[2,3,0,1] row_mask:0xf bank_mask:0xf
	s_nop 1
	v_add_f32_dpp v91, v91, v91 row_half_mirror row_mask:0xf bank_mask:0xf
	s_nop 0
	v_fmamk_f32 v94, v91, 0x3c800000, v5
	v_rsq_f32_e32 v94, v94
	s_nop 0
	v_pk_mul_f32 v[40:41], v[40:41], v[94:95] op_sel_hi:[1,0]
	v_pk_mul_f32 v[42:43], v[42:43], v[94:95] op_sel_hi:[1,0]
	v_pk_mul_f32 v[44:45], v[44:45], v[94:95] op_sel_hi:[1,0]
	v_pk_mul_f32 v[46:47], v[46:47], v[94:95] op_sel_hi:[1,0]
	v_pk_fma_f32 v[40:41], v[40:41], v[16:17], v[24:25]
	v_pk_fma_f32 v[42:43], v[42:43], v[18:19], v[26:27]
	v_pk_fma_f32 v[44:45], v[44:45], v[20:21], v[28:29]
	v_pk_fma_f32 v[46:47], v[46:47], v[22:23], v[30:31]
	v_pk_fma_f32 v[80:81], v[72:73], v[96:97], v[40:41] op_sel_hi:[1,0,1]
	v_pk_fma_f32 v[82:83], v[74:75], v[96:97], v[42:43] op_sel_hi:[1,0,1]
	v_pk_fma_f32 v[84:85], v[76:77], v[96:97], v[44:45] op_sel_hi:[1,0,1]
	v_pk_fma_f32 v[86:87], v[78:79], v[96:97], v[46:47] op_sel_hi:[1,0,1]
	v_pk_mul_f32 v[80:81], v[80:81], v[64:65]
	v_pk_mul_f32 v[82:83], v[82:83], v[66:67]
	v_pk_mul_f32 v[84:85], v[84:85], v[68:69]
	v_pk_mul_f32 v[86:87], v[86:87], v[70:71]
	v_cvt_pk_bf16_f32 v72, v80, v81
	v_cvt_pk_bf16_f32 v73, v82, v83
	v_cvt_pk_bf16_f32 v74, v84, v85
	v_cvt_pk_bf16_f32 v75, v86, v87
	global_store_dwordx4 v1, v[72:75], s[8:9]
	s_add_u32 s8, s8, 0x400
	s_addc_u32 s9, s9, 0
	global_load_dwordx4 v[128:131], v1, s[6:7]
	global_load_dwordx4 v[132:135], v1, s[10:11]
	global_load_dwordx4 v[136:139], v1, s[12:13]
	global_load_dword v140, v3, s[14:15]
	s_add_u32 s6, s6, 0x400
	s_addc_u32 s7, s7, 0
	s_add_u32 s10, s10, 0xe00
	s_addc_u32 s11, s11, 0
	s_add_u32 s12, s12, 0xc00
	s_addc_u32 s13, s13, 0
	s_add_u32 s14, s14, 32
	s_addc_u32 s15, s15, 0
	s_waitcnt vmcnt(35)
	v_lshlrev_b32_e32 v40, 16, v170
	v_and_b32_e32 v41, 0xffff0000, v170
	v_lshlrev_b32_e32 v42, 16, v171
	v_and_b32_e32 v43, 0xffff0000, v171
	v_lshlrev_b32_e32 v44, 16, v172
	v_and_b32_e32 v45, 0xffff0000, v172
	v_lshlrev_b32_e32 v46, 16, v173
	v_and_b32_e32 v47, 0xffff0000, v173
	v_pk_add_f32 v[88:89], v[40:41], v[42:43]
	v_pk_add_f32 v[88:89], v[88:89], v[44:45]
	v_pk_add_f32 v[88:89], v[88:89], v[46:47]
	v_add_f32_e32 v90, v88, v89
	v_lshlrev_b32_e32 v56, 16, v174
	v_and_b32_e32 v57, 0xffff0000, v174
	v_lshlrev_b32_e32 v58, 16, v175
	v_and_b32_e32 v59, 0xffff0000, v175
	v_lshlrev_b32_e32 v60, 16, v176
	v_and_b32_e32 v61, 0xffff0000, v176
	v_lshlrev_b32_e32 v62, 16, v177
	v_and_b32_e32 v63, 0xffff0000, v177
	v_add_f32_dpp v90, v90, v90 quad_perm:[1,0,3,2] row_mask:0xf bank_mask:0xf
	v_lshlrev_b32_e32 v64, 16, v178
	v_and_b32_e32 v65, 0xffff0000, v178
	v_lshlrev_b32_e32 v66, 16, v179
	v_and_b32_e32 v67, 0xffff0000, v179
	v_add_f32_dpp v90, v90, v90 quad_perm:[2,3,0,1] row_mask:0xf bank_mask:0xf
	v_lshlrev_b32_e32 v68, 16, v180
	v_and_b32_e32 v69, 0xffff0000, v180
	v_lshlrev_b32_e32 v70, 16, v181
	v_and_b32_e32 v71, 0xffff0000, v181
	v_add_f32_dpp v90, v90, v90 row_half_mirror row_mask:0xf bank_mask:0xf
	v_pk_add_f32 v[72:73], v[48:49], v[56:57] neg_lo:[0,1] neg_hi:[0,1]
	v_pk_add_f32 v[74:75], v[50:51], v[58:59] neg_lo:[0,1] neg_hi:[0,1]
	v_pk_add_f32 v[76:77], v[52:53], v[60:61] neg_lo:[0,1] neg_hi:[0,1]
	v_pk_add_f32 v[78:79], v[54:55], v[62:63] neg_lo:[0,1] neg_hi:[0,1]
	v_mul_f32_e32 v92, 0x3c800000, v90
	v_mov_b32_e32 v96, v182
	v_pk_add_f32 v[40:41], v[40:41], v[92:93] op_sel_hi:[1,0] neg_lo:[0,1] neg_hi:[0,1]
	v_pk_add_f32 v[42:43], v[42:43], v[92:93] op_sel_hi:[1,0] neg_lo:[0,1] neg_hi:[0,1]
	v_pk_add_f32 v[44:45], v[44:45], v[92:93] op_sel_hi:[1,0] neg_lo:[0,1] neg_hi:[0,1]
	v_pk_add_f32 v[46:47], v[46:47], v[92:93] op_sel_hi:[1,0] neg_lo:[0,1] neg_hi:[0,1]
	v_pk_mul_f32 v[88:89], v[40:41], v[40:41]
	v_pk_fma_f32 v[88:89], v[42:43], v[42:43], v[88:89]
	v_pk_fma_f32 v[88:89], v[44:45], v[44:45], v[88:89]
	v_pk_fma_f32 v[88:89], v[46:47], v[46:47], v[88:89]
	v_add_f32_e32 v91, v88, v89
	v_pk_fma_f32 v[72:73], v[72:73], v[8:9], v[56:57]
	v_pk_fma_f32 v[74:75], v[74:75], v[10:11], v[58:59]
	v_add_f32_dpp v91, v91, v91 quad_perm:[1,0,3,2] row_mask:0xf bank_mask:0xf
	v_pk_fma_f32 v[76:77], v[76:77], v[12:13], v[60:61]
	v_pk_fma_f32 v[78:79], v[78:79], v[14:15], v[62:63]
	v_add_f32_dpp v91, v91, v91 quad_perm:[2,3,0,1] row_mask:0xf bank_mask:0xf
	s_nop 1
	v_add_f32_dpp v91, v91, v91 row_half_mirror row_mask:0xf bank_mask:0xf
	s_nop 0
	v_fmamk_f32 v94, v91, 0x3c800000, v5
	v_rsq_f32_e32 v94, v94
	s_nop 0
	v_pk_mul_f32 v[40:41], v[40:41], v[94:95] op_sel_hi:[1,0]
	v_pk_mul_f32 v[42:43], v[42:43], v[94:95] op_sel_hi:[1,0]
	v_pk_mul_f32 v[44:45], v[44:45], v[94:95] op_sel_hi:[1,0]
	v_pk_mul_f32 v[46:47], v[46:47], v[94:95] op_sel_hi:[1,0]
	v_pk_fma_f32 v[40:41], v[40:41], v[16:17], v[24:25]
	v_pk_fma_f32 v[42:43], v[42:43], v[18:19], v[26:27]
	v_pk_fma_f32 v[44:45], v[44:45], v[20:21], v[28:29]
	v_pk_fma_f32 v[46:47], v[46:47], v[22:23], v[30:31]
	v_pk_fma_f32 v[80:81], v[72:73], v[96:97], v[40:41] op_sel_hi:[1,0,1]
	v_pk_fma_f32 v[82:83], v[74:75], v[96:97], v[42:43] op_sel_hi:[1,0,1]
	v_pk_fma_f32 v[84:85], v[76:77], v[96:97], v[44:45] op_sel_hi:[1,0,1]
	v_pk_fma_f32 v[86:87], v[78:79], v[96:97], v[46:47] op_sel_hi:[1,0,1]
	v_pk_mul_f32 v[80:81], v[80:81], v[64:65]
	v_pk_mul_f32 v[82:83], v[82:83], v[66:67]
	v_pk_mul_f32 v[84:85], v[84:85], v[68:69]
	v_pk_mul_f32 v[86:87], v[86:87], v[70:71]
	v_cvt_pk_bf16_f32 v72, v80, v81
	v_cvt_pk_bf16_f32 v73, v82, v83
	v_cvt_pk_bf16_f32 v74, v84, v85
	v_cvt_pk_bf16_f32 v75, v86, v87
	global_store_dwordx4 v1, v[72:75], s[8:9]
	s_add_u32 s8, s8, 0x400
	s_addc_u32 s9, s9, 0
	global_load_dwordx4 v[142:145], v1, s[6:7]
	global_load_dwordx4 v[146:149], v1, s[10:11]
	global_load_dwordx4 v[150:153], v1, s[12:13]
	global_load_dword v154, v3, s[14:15]
	s_add_u32 s6, s6, 0x400
	s_addc_u32 s7, s7, 0
	s_add_u32 s10, s10, 0xe00
	s_addc_u32 s11, s11, 0
	s_add_u32 s12, s12, 0xc00
	s_addc_u32 s13, s13, 0
	s_add_u32 s14, s14, 32
	s_addc_u32 s15, s15, 0
	s_waitcnt vmcnt(35)
	v_lshlrev_b32_e32 v40, 16, v184
	v_and_b32_e32 v41, 0xffff0000, v184
	v_lshlrev_b32_e32 v42, 16, v185
	v_and_b32_e32 v43, 0xffff0000, v185
	v_lshlrev_b32_e32 v44, 16, v186
	v_and_b32_e32 v45, 0xffff0000, v186
	v_lshlrev_b32_e32 v46, 16, v187
	v_and_b32_e32 v47, 0xffff0000, v187
	v_pk_add_f32 v[88:89], v[40:41], v[42:43]
	v_pk_add_f32 v[88:89], v[88:89], v[44:45]
	v_pk_add_f32 v[88:89], v[88:89], v[46:47]
	v_add_f32_e32 v90, v88, v89
	v_lshlrev_b32_e32 v48, 16, v188
	v_and_b32_e32 v49, 0xffff0000, v188
	v_lshlrev_b32_e32 v50, 16, v189
	v_and_b32_e32 v51, 0xffff0000, v189
	v_lshlrev_b32_e32 v52, 16, v190
	v_and_b32_e32 v53, 0xffff0000, v190
	v_lshlrev_b32_e32 v54, 16, v191
	v_and_b32_e32 v55, 0xffff0000, v191
	v_add_f32_dpp v90, v90, v90 quad_perm:[1,0,3,2] row_mask:0xf bank_mask:0xf
	v_lshlrev_b32_e32 v64, 16, v192
	v_and_b32_e32 v65, 0xffff0000, v192
	v_lshlrev_b32_e32 v66, 16, v193
	v_and_b32_e32 v67, 0xffff0000, v193
	v_add_f32_dpp v90, v90, v90 quad_perm:[2,3,0,1] row_mask:0xf bank_mask:0xf
	v_lshlrev_b32_e32 v68, 16, v194
	v_and_b32_e32 v69, 0xffff0000, v194
	v_lshlrev_b32_e32 v70, 16, v195
	v_and_b32_e32 v71, 0xffff0000, v195
	v_add_f32_dpp v90, v90, v90 row_half_mirror row_mask:0xf bank_mask:0xf
	v_pk_add_f32 v[72:73], v[56:57], v[48:49] neg_lo:[0,1] neg_hi:[0,1]
	v_pk_add_f32 v[74:75], v[58:59], v[50:51] neg_lo:[0,1] neg_hi:[0,1]
	v_pk_add_f32 v[76:77], v[60:61], v[52:53] neg_lo:[0,1] neg_hi:[0,1]
	v_pk_add_f32 v[78:79], v[62:63], v[54:55] neg_lo:[0,1] neg_hi:[0,1]
	v_mul_f32_e32 v92, 0x3c800000, v90
	v_mov_b32_e32 v96, v196
	v_pk_add_f32 v[40:41], v[40:41], v[92:93] op_sel_hi:[1,0] neg_lo:[0,1] neg_hi:[0,1]
	v_pk_add_f32 v[42:43], v[42:43], v[92:93] op_sel_hi:[1,0] neg_lo:[0,1] neg_hi:[0,1]
	v_pk_add_f32 v[44:45], v[44:45], v[92:93] op_sel_hi:[1,0] neg_lo:[0,1] neg_hi:[0,1]
	v_pk_add_f32 v[46:47], v[46:47], v[92:93] op_sel_hi:[1,0] neg_lo:[0,1] neg_hi:[0,1]
	v_pk_mul_f32 v[88:89], v[40:41], v[40:41]
	v_pk_fma_f32 v[88:89], v[42:43], v[42:43], v[88:89]
	v_pk_fma_f32 v[88:89], v[44:45], v[44:45], v[88:89]
	v_pk_fma_f32 v[88:89], v[46:47], v[46:47], v[88:89]
	v_add_f32_e32 v91, v88, v89
	v_pk_fma_f32 v[72:73], v[72:73], v[8:9], v[48:49]
	v_pk_fma_f32 v[74:75], v[74:75], v[10:11], v[50:51]
	v_add_f32_dpp v91, v91, v91 quad_perm:[1,0,3,2] row_mask:0xf bank_mask:0xf
	v_pk_fma_f32 v[76:77], v[76:77], v[12:13], v[52:53]
	v_pk_fma_f32 v[78:79], v[78:79], v[14:15], v[54:55]
	v_add_f32_dpp v91, v91, v91 quad_perm:[2,3,0,1] row_mask:0xf bank_mask:0xf
	s_nop 1
	v_add_f32_dpp v91, v91, v91 row_half_mirror row_mask:0xf bank_mask:0xf
	s_nop 0
	v_fmamk_f32 v94, v91, 0x3c800000, v5
	v_rsq_f32_e32 v94, v94
	s_nop 0
	v_pk_mul_f32 v[40:41], v[40:41], v[94:95] op_sel_hi:[1,0]
	v_pk_mul_f32 v[42:43], v[42:43], v[94:95] op_sel_hi:[1,0]
	v_pk_mul_f32 v[44:45], v[44:45], v[94:95] op_sel_hi:[1,0]
	v_pk_mul_f32 v[46:47], v[46:47], v[94:95] op_sel_hi:[1,0]
	v_pk_fma_f32 v[40:41], v[40:41], v[16:17], v[24:25]
	v_pk_fma_f32 v[42:43], v[42:43], v[18:19], v[26:27]
	v_pk_fma_f32 v[44:45], v[44:45], v[20:21], v[28:29]
	v_pk_fma_f32 v[46:47], v[46:47], v[22:23], v[30:31]
	v_pk_fma_f32 v[80:81], v[72:73], v[96:97], v[40:41] op_sel_hi:[1,0,1]
	v_pk_fma_f32 v[82:83], v[74:75], v[96:97], v[42:43] op_sel_hi:[1,0,1]
	v_pk_fma_f32 v[84:85], v[76:77], v[96:97], v[44:45] op_sel_hi:[1,0,1]
	v_pk_fma_f32 v[86:87], v[78:79], v[96:97], v[46:47] op_sel_hi:[1,0,1]
	v_pk_mul_f32 v[80:81], v[80:81], v[64:65]
	v_pk_mul_f32 v[82:83], v[82:83], v[66:67]
	v_pk_mul_f32 v[84:85], v[84:85], v[68:69]
	v_pk_mul_f32 v[86:87], v[86:87], v[70:71]
	v_cvt_pk_bf16_f32 v72, v80, v81
	v_cvt_pk_bf16_f32 v73, v82, v83
	v_cvt_pk_bf16_f32 v74, v84, v85
	v_cvt_pk_bf16_f32 v75, v86, v87
	global_store_dwordx4 v1, v[72:75], s[8:9]
	s_add_u32 s8, s8, 0x400
	s_addc_u32 s9, s9, 0
	global_load_dwordx4 v[156:159], v1, s[6:7]
	global_load_dwordx4 v[160:163], v1, s[10:11]
	global_load_dwordx4 v[164:167], v1, s[12:13]
	global_load_dword v168, v3, s[14:15]
	s_add_u32 s6, s6, 0x400
	s_addc_u32 s7, s7, 0
	s_add_u32 s10, s10, 0xe00
	s_addc_u32 s11, s11, 0
	s_add_u32 s12, s12, 0xc00
	s_addc_u32 s13, s13, 0
	s_add_u32 s14, s14, 32
	s_addc_u32 s15, s15, 0
	s_waitcnt vmcnt(35)
	v_lshlrev_b32_e32 v40, 16, v198
	v_and_b32_e32 v41, 0xffff0000, v198
	v_lshlrev_b32_e32 v42, 16, v199
	v_and_b32_e32 v43, 0xffff0000, v199
	v_lshlrev_b32_e32 v44, 16, v200
	v_and_b32_e32 v45, 0xffff0000, v200
	v_lshlrev_b32_e32 v46, 16, v201
	v_and_b32_e32 v47, 0xffff0000, v201
	v_pk_add_f32 v[88:89], v[40:41], v[42:43]
	v_pk_add_f32 v[88:89], v[88:89], v[44:45]
	v_pk_add_f32 v[88:89], v[88:89], v[46:47]
	v_add_f32_e32 v90, v88, v89
	v_lshlrev_b32_e32 v56, 16, v202
	v_and_b32_e32 v57, 0xffff0000, v202
	v_lshlrev_b32_e32 v58, 16, v203
	v_and_b32_e32 v59, 0xffff0000, v203
	v_lshlrev_b32_e32 v60, 16, v204
	v_and_b32_e32 v61, 0xffff0000, v204
	v_lshlrev_b32_e32 v62, 16, v205
	v_and_b32_e32 v63, 0xffff0000, v205
	v_add_f32_dpp v90, v90, v90 quad_perm:[1,0,3,2] row_mask:0xf bank_mask:0xf
	v_lshlrev_b32_e32 v64, 16, v206
	v_and_b32_e32 v65, 0xffff0000, v206
	v_lshlrev_b32_e32 v66, 16, v207
	v_and_b32_e32 v67, 0xffff0000, v207
	v_add_f32_dpp v90, v90, v90 quad_perm:[2,3,0,1] row_mask:0xf bank_mask:0xf
	v_lshlrev_b32_e32 v68, 16, v208
	v_and_b32_e32 v69, 0xffff0000, v208
	v_lshlrev_b32_e32 v70, 16, v209
	v_and_b32_e32 v71, 0xffff0000, v209
	v_add_f32_dpp v90, v90, v90 row_half_mirror row_mask:0xf bank_mask:0xf
	v_pk_add_f32 v[72:73], v[48:49], v[56:57] neg_lo:[0,1] neg_hi:[0,1]
	v_pk_add_f32 v[74:75], v[50:51], v[58:59] neg_lo:[0,1] neg_hi:[0,1]
	v_pk_add_f32 v[76:77], v[52:53], v[60:61] neg_lo:[0,1] neg_hi:[0,1]
	v_pk_add_f32 v[78:79], v[54:55], v[62:63] neg_lo:[0,1] neg_hi:[0,1]
	v_mul_f32_e32 v92, 0x3c800000, v90
	v_mov_b32_e32 v96, v210
	v_pk_add_f32 v[40:41], v[40:41], v[92:93] op_sel_hi:[1,0] neg_lo:[0,1] neg_hi:[0,1]
	v_pk_add_f32 v[42:43], v[42:43], v[92:93] op_sel_hi:[1,0] neg_lo:[0,1] neg_hi:[0,1]
	v_pk_add_f32 v[44:45], v[44:45], v[92:93] op_sel_hi:[1,0] neg_lo:[0,1] neg_hi:[0,1]
	v_pk_add_f32 v[46:47], v[46:47], v[92:93] op_sel_hi:[1,0] neg_lo:[0,1] neg_hi:[0,1]
	v_pk_mul_f32 v[88:89], v[40:41], v[40:41]
	v_pk_fma_f32 v[88:89], v[42:43], v[42:43], v[88:89]
	v_pk_fma_f32 v[88:89], v[44:45], v[44:45], v[88:89]
	v_pk_fma_f32 v[88:89], v[46:47], v[46:47], v[88:89]
	v_add_f32_e32 v91, v88, v89
	v_pk_fma_f32 v[72:73], v[72:73], v[8:9], v[56:57]
	v_pk_fma_f32 v[74:75], v[74:75], v[10:11], v[58:59]
	v_add_f32_dpp v91, v91, v91 quad_perm:[1,0,3,2] row_mask:0xf bank_mask:0xf
	v_pk_fma_f32 v[76:77], v[76:77], v[12:13], v[60:61]
	v_pk_fma_f32 v[78:79], v[78:79], v[14:15], v[62:63]
	v_add_f32_dpp v91, v91, v91 quad_perm:[2,3,0,1] row_mask:0xf bank_mask:0xf
	s_nop 1
	v_add_f32_dpp v91, v91, v91 row_half_mirror row_mask:0xf bank_mask:0xf
	s_nop 0
	v_fmamk_f32 v94, v91, 0x3c800000, v5
	v_rsq_f32_e32 v94, v94
	s_nop 0
	v_pk_mul_f32 v[40:41], v[40:41], v[94:95] op_sel_hi:[1,0]
	v_pk_mul_f32 v[42:43], v[42:43], v[94:95] op_sel_hi:[1,0]
	v_pk_mul_f32 v[44:45], v[44:45], v[94:95] op_sel_hi:[1,0]
	v_pk_mul_f32 v[46:47], v[46:47], v[94:95] op_sel_hi:[1,0]
	v_pk_fma_f32 v[40:41], v[40:41], v[16:17], v[24:25]
	v_pk_fma_f32 v[42:43], v[42:43], v[18:19], v[26:27]
	v_pk_fma_f32 v[44:45], v[44:45], v[20:21], v[28:29]
	v_pk_fma_f32 v[46:47], v[46:47], v[22:23], v[30:31]
	v_pk_fma_f32 v[80:81], v[72:73], v[96:97], v[40:41] op_sel_hi:[1,0,1]
	v_pk_fma_f32 v[82:83], v[74:75], v[96:97], v[42:43] op_sel_hi:[1,0,1]
	v_pk_fma_f32 v[84:85], v[76:77], v[96:97], v[44:45] op_sel_hi:[1,0,1]
	v_pk_fma_f32 v[86:87], v[78:79], v[96:97], v[46:47] op_sel_hi:[1,0,1]
	v_pk_mul_f32 v[80:81], v[80:81], v[64:65]
	v_pk_mul_f32 v[82:83], v[82:83], v[66:67]
	v_pk_mul_f32 v[84:85], v[84:85], v[68:69]
	v_pk_mul_f32 v[86:87], v[86:87], v[70:71]
	v_cvt_pk_bf16_f32 v72, v80, v81
	v_cvt_pk_bf16_f32 v73, v82, v83
	v_cvt_pk_bf16_f32 v74, v84, v85
	v_cvt_pk_bf16_f32 v75, v86, v87
	global_store_dwordx4 v1, v[72:75], s[8:9]
	s_add_u32 s8, s8, 0x400
	s_addc_u32 s9, s9, 0
	global_load_dwordx4 v[170:173], v1, s[6:7]
	global_load_dwordx4 v[174:177], v1, s[10:11]
	global_load_dwordx4 v[178:181], v1, s[12:13]
	global_load_dword v182, v3, s[14:15]
	s_add_u32 s6, s6, 0x400
	s_addc_u32 s7, s7, 0
	s_add_u32 s10, s10, 0xe00
	s_addc_u32 s11, s11, 0
	s_add_u32 s12, s12, 0xc00
	s_addc_u32 s13, s13, 0
	s_add_u32 s14, s14, 32
	s_addc_u32 s15, s15, 0
	s_waitcnt vmcnt(35)
	v_lshlrev_b32_e32 v40, 16, v212
	v_and_b32_e32 v41, 0xffff0000, v212
	v_lshlrev_b32_e32 v42, 16, v213
	v_and_b32_e32 v43, 0xffff0000, v213
	v_lshlrev_b32_e32 v44, 16, v214
	v_and_b32_e32 v45, 0xffff0000, v214
	v_lshlrev_b32_e32 v46, 16, v215
	v_and_b32_e32 v47, 0xffff0000, v215
	v_pk_add_f32 v[88:89], v[40:41], v[42:43]
	v_pk_add_f32 v[88:89], v[88:89], v[44:45]
	v_pk_add_f32 v[88:89], v[88:89], v[46:47]
	v_add_f32_e32 v90, v88, v89
	v_lshlrev_b32_e32 v48, 16, v216
	v_and_b32_e32 v49, 0xffff0000, v216
	v_lshlrev_b32_e32 v50, 16, v217
	v_and_b32_e32 v51, 0xffff0000, v217
	v_lshlrev_b32_e32 v52, 16, v218
	v_and_b32_e32 v53, 0xffff0000, v218
	v_lshlrev_b32_e32 v54, 16, v219
	v_and_b32_e32 v55, 0xffff0000, v219
	v_add_f32_dpp v90, v90, v90 quad_perm:[1,0,3,2] row_mask:0xf bank_mask:0xf
	v_lshlrev_b32_e32 v64, 16, v220
	v_and_b32_e32 v65, 0xffff0000, v220
	v_lshlrev_b32_e32 v66, 16, v221
	v_and_b32_e32 v67, 0xffff0000, v221
	v_add_f32_dpp v90, v90, v90 quad_perm:[2,3,0,1] row_mask:0xf bank_mask:0xf
	v_lshlrev_b32_e32 v68, 16, v222
	v_and_b32_e32 v69, 0xffff0000, v222
	v_lshlrev_b32_e32 v70, 16, v223
	v_and_b32_e32 v71, 0xffff0000, v223
	v_add_f32_dpp v90, v90, v90 row_half_mirror row_mask:0xf bank_mask:0xf
	v_pk_add_f32 v[72:73], v[56:57], v[48:49] neg_lo:[0,1] neg_hi:[0,1]
	v_pk_add_f32 v[74:75], v[58:59], v[50:51] neg_lo:[0,1] neg_hi:[0,1]
	v_pk_add_f32 v[76:77], v[60:61], v[52:53] neg_lo:[0,1] neg_hi:[0,1]
	v_pk_add_f32 v[78:79], v[62:63], v[54:55] neg_lo:[0,1] neg_hi:[0,1]
	v_mul_f32_e32 v92, 0x3c800000, v90
	v_mov_b32_e32 v96, v224
	v_pk_add_f32 v[40:41], v[40:41], v[92:93] op_sel_hi:[1,0] neg_lo:[0,1] neg_hi:[0,1]
	v_pk_add_f32 v[42:43], v[42:43], v[92:93] op_sel_hi:[1,0] neg_lo:[0,1] neg_hi:[0,1]
	v_pk_add_f32 v[44:45], v[44:45], v[92:93] op_sel_hi:[1,0] neg_lo:[0,1] neg_hi:[0,1]
	v_pk_add_f32 v[46:47], v[46:47], v[92:93] op_sel_hi:[1,0] neg_lo:[0,1] neg_hi:[0,1]
	v_pk_mul_f32 v[88:89], v[40:41], v[40:41]
	v_pk_fma_f32 v[88:89], v[42:43], v[42:43], v[88:89]
	v_pk_fma_f32 v[88:89], v[44:45], v[44:45], v[88:89]
	v_pk_fma_f32 v[88:89], v[46:47], v[46:47], v[88:89]
	v_add_f32_e32 v91, v88, v89
	v_pk_fma_f32 v[72:73], v[72:73], v[8:9], v[48:49]
	v_pk_fma_f32 v[74:75], v[74:75], v[10:11], v[50:51]
	v_add_f32_dpp v91, v91, v91 quad_perm:[1,0,3,2] row_mask:0xf bank_mask:0xf
	v_pk_fma_f32 v[76:77], v[76:77], v[12:13], v[52:53]
	v_pk_fma_f32 v[78:79], v[78:79], v[14:15], v[54:55]
	v_add_f32_dpp v91, v91, v91 quad_perm:[2,3,0,1] row_mask:0xf bank_mask:0xf
	s_nop 1
	v_add_f32_dpp v91, v91, v91 row_half_mirror row_mask:0xf bank_mask:0xf
	s_nop 0
	v_fmamk_f32 v94, v91, 0x3c800000, v5
	v_rsq_f32_e32 v94, v94
	s_nop 0
	v_pk_mul_f32 v[40:41], v[40:41], v[94:95] op_sel_hi:[1,0]
	v_pk_mul_f32 v[42:43], v[42:43], v[94:95] op_sel_hi:[1,0]
	v_pk_mul_f32 v[44:45], v[44:45], v[94:95] op_sel_hi:[1,0]
	v_pk_mul_f32 v[46:47], v[46:47], v[94:95] op_sel_hi:[1,0]
	v_pk_fma_f32 v[40:41], v[40:41], v[16:17], v[24:25]
	v_pk_fma_f32 v[42:43], v[42:43], v[18:19], v[26:27]
	v_pk_fma_f32 v[44:45], v[44:45], v[20:21], v[28:29]
	v_pk_fma_f32 v[46:47], v[46:47], v[22:23], v[30:31]
	v_pk_fma_f32 v[80:81], v[72:73], v[96:97], v[40:41] op_sel_hi:[1,0,1]
	v_pk_fma_f32 v[82:83], v[74:75], v[96:97], v[42:43] op_sel_hi:[1,0,1]
	v_pk_fma_f32 v[84:85], v[76:77], v[96:97], v[44:45] op_sel_hi:[1,0,1]
	v_pk_fma_f32 v[86:87], v[78:79], v[96:97], v[46:47] op_sel_hi:[1,0,1]
	v_pk_mul_f32 v[80:81], v[80:81], v[64:65]
	v_pk_mul_f32 v[82:83], v[82:83], v[66:67]
	v_pk_mul_f32 v[84:85], v[84:85], v[68:69]
	v_pk_mul_f32 v[86:87], v[86:87], v[70:71]
	v_cvt_pk_bf16_f32 v72, v80, v81
	v_cvt_pk_bf16_f32 v73, v82, v83
	v_cvt_pk_bf16_f32 v74, v84, v85
	v_cvt_pk_bf16_f32 v75, v86, v87
	global_store_dwordx4 v1, v[72:75], s[8:9]
	s_add_u32 s8, s8, 0x400
	s_addc_u32 s9, s9, 0
	global_load_dwordx4 v[184:187], v1, s[6:7]
	global_load_dwordx4 v[188:191], v1, s[10:11]
	global_load_dwordx4 v[192:195], v1, s[12:13]
	global_load_dword v196, v3, s[14:15]
	s_add_u32 s6, s6, 0x400
	s_addc_u32 s7, s7, 0
	s_add_u32 s10, s10, 0xe00
	s_addc_u32 s11, s11, 0
	s_add_u32 s12, s12, 0xc00
	s_addc_u32 s13, s13, 0
	s_add_u32 s14, s14, 32
	s_addc_u32 s15, s15, 0
	s_waitcnt vmcnt(35)
	v_lshlrev_b32_e32 v40, 16, v226
	v_and_b32_e32 v41, 0xffff0000, v226
	v_lshlrev_b32_e32 v42, 16, v227
	v_and_b32_e32 v43, 0xffff0000, v227
	v_lshlrev_b32_e32 v44, 16, v228
	v_and_b32_e32 v45, 0xffff0000, v228
	v_lshlrev_b32_e32 v46, 16, v229
	v_and_b32_e32 v47, 0xffff0000, v229
	v_pk_add_f32 v[88:89], v[40:41], v[42:43]
	v_pk_add_f32 v[88:89], v[88:89], v[44:45]
	v_pk_add_f32 v[88:89], v[88:89], v[46:47]
	v_add_f32_e32 v90, v88, v89
	v_lshlrev_b32_e32 v56, 16, v230
	v_and_b32_e32 v57, 0xffff0000, v230
	v_lshlrev_b32_e32 v58, 16, v231
	v_and_b32_e32 v59, 0xffff0000, v231
	v_lshlrev_b32_e32 v60, 16, v232
	v_and_b32_e32 v61, 0xffff0000, v232
	v_lshlrev_b32_e32 v62, 16, v233
	v_and_b32_e32 v63, 0xffff0000, v233
	v_add_f32_dpp v90, v90, v90 quad_perm:[1,0,3,2] row_mask:0xf bank_mask:0xf
	v_lshlrev_b32_e32 v64, 16, v234
	v_and_b32_e32 v65, 0xffff0000, v234
	v_lshlrev_b32_e32 v66, 16, v235
	v_and_b32_e32 v67, 0xffff0000, v235
	v_add_f32_dpp v90, v90, v90 quad_perm:[2,3,0,1] row_mask:0xf bank_mask:0xf
	v_lshlrev_b32_e32 v68, 16, v236
	v_and_b32_e32 v69, 0xffff0000, v236
	v_lshlrev_b32_e32 v70, 16, v237
	v_and_b32_e32 v71, 0xffff0000, v237
	v_add_f32_dpp v90, v90, v90 row_half_mirror row_mask:0xf bank_mask:0xf
	v_pk_add_f32 v[72:73], v[48:49], v[56:57] neg_lo:[0,1] neg_hi:[0,1]
	v_pk_add_f32 v[74:75], v[50:51], v[58:59] neg_lo:[0,1] neg_hi:[0,1]
	v_pk_add_f32 v[76:77], v[52:53], v[60:61] neg_lo:[0,1] neg_hi:[0,1]
	v_pk_add_f32 v[78:79], v[54:55], v[62:63] neg_lo:[0,1] neg_hi:[0,1]
	v_mul_f32_e32 v92, 0x3c800000, v90
	v_mov_b32_e32 v96, v238
	v_pk_add_f32 v[40:41], v[40:41], v[92:93] op_sel_hi:[1,0] neg_lo:[0,1] neg_hi:[0,1]
	v_pk_add_f32 v[42:43], v[42:43], v[92:93] op_sel_hi:[1,0] neg_lo:[0,1] neg_hi:[0,1]
	v_pk_add_f32 v[44:45], v[44:45], v[92:93] op_sel_hi:[1,0] neg_lo:[0,1] neg_hi:[0,1]
	v_pk_add_f32 v[46:47], v[46:47], v[92:93] op_sel_hi:[1,0] neg_lo:[0,1] neg_hi:[0,1]
	v_pk_mul_f32 v[88:89], v[40:41], v[40:41]
	v_pk_fma_f32 v[88:89], v[42:43], v[42:43], v[88:89]
	v_pk_fma_f32 v[88:89], v[44:45], v[44:45], v[88:89]
	v_pk_fma_f32 v[88:89], v[46:47], v[46:47], v[88:89]
	v_add_f32_e32 v91, v88, v89
	v_pk_fma_f32 v[72:73], v[72:73], v[8:9], v[56:57]
	v_pk_fma_f32 v[74:75], v[74:75], v[10:11], v[58:59]
	v_add_f32_dpp v91, v91, v91 quad_perm:[1,0,3,2] row_mask:0xf bank_mask:0xf
	v_pk_fma_f32 v[76:77], v[76:77], v[12:13], v[60:61]
	v_pk_fma_f32 v[78:79], v[78:79], v[14:15], v[62:63]
	v_add_f32_dpp v91, v91, v91 quad_perm:[2,3,0,1] row_mask:0xf bank_mask:0xf
	s_nop 1
	v_add_f32_dpp v91, v91, v91 row_half_mirror row_mask:0xf bank_mask:0xf
	s_nop 0
	v_fmamk_f32 v94, v91, 0x3c800000, v5
	v_rsq_f32_e32 v94, v94
	s_nop 0
	v_pk_mul_f32 v[40:41], v[40:41], v[94:95] op_sel_hi:[1,0]
	v_pk_mul_f32 v[42:43], v[42:43], v[94:95] op_sel_hi:[1,0]
	v_pk_mul_f32 v[44:45], v[44:45], v[94:95] op_sel_hi:[1,0]
	v_pk_mul_f32 v[46:47], v[46:47], v[94:95] op_sel_hi:[1,0]
	v_pk_fma_f32 v[40:41], v[40:41], v[16:17], v[24:25]
	v_pk_fma_f32 v[42:43], v[42:43], v[18:19], v[26:27]
	v_pk_fma_f32 v[44:45], v[44:45], v[20:21], v[28:29]
	v_pk_fma_f32 v[46:47], v[46:47], v[22:23], v[30:31]
	v_pk_fma_f32 v[80:81], v[72:73], v[96:97], v[40:41] op_sel_hi:[1,0,1]
	v_pk_fma_f32 v[82:83], v[74:75], v[96:97], v[42:43] op_sel_hi:[1,0,1]
	v_pk_fma_f32 v[84:85], v[76:77], v[96:97], v[44:45] op_sel_hi:[1,0,1]
	v_pk_fma_f32 v[86:87], v[78:79], v[96:97], v[46:47] op_sel_hi:[1,0,1]
	v_pk_mul_f32 v[80:81], v[80:81], v[64:65]
	v_pk_mul_f32 v[82:83], v[82:83], v[66:67]
	v_pk_mul_f32 v[84:85], v[84:85], v[68:69]
	v_pk_mul_f32 v[86:87], v[86:87], v[70:71]
	v_cvt_pk_bf16_f32 v72, v80, v81
	v_cvt_pk_bf16_f32 v73, v82, v83
	v_cvt_pk_bf16_f32 v74, v84, v85
	v_cvt_pk_bf16_f32 v75, v86, v87
	global_store_dwordx4 v1, v[72:75], s[8:9]
	s_add_u32 s8, s8, 0x400
	s_addc_u32 s9, s9, 0
	global_load_dwordx4 v[198:201], v1, s[6:7]
	global_load_dwordx4 v[202:205], v1, s[10:11]
	global_load_dwordx4 v[206:209], v1, s[12:13]
	global_load_dword v210, v3, s[14:15]
	s_add_u32 s6, s6, 0x400
	s_addc_u32 s7, s7, 0
	s_add_u32 s10, s10, 0xe00
	s_addc_u32 s11, s11, 0
	s_add_u32 s12, s12, 0xc00
	s_addc_u32 s13, s13, 0
	s_add_u32 s14, s14, 32
	s_addc_u32 s15, s15, 0
	s_waitcnt vmcnt(35)
	v_lshlrev_b32_e32 v40, 16, v100
	v_and_b32_e32 v41, 0xffff0000, v100
	v_lshlrev_b32_e32 v42, 16, v101
	v_and_b32_e32 v43, 0xffff0000, v101
	v_lshlrev_b32_e32 v44, 16, v102
	v_and_b32_e32 v45, 0xffff0000, v102
	v_lshlrev_b32_e32 v46, 16, v103
	v_and_b32_e32 v47, 0xffff0000, v103
	v_pk_add_f32 v[88:89], v[40:41], v[42:43]
	v_pk_add_f32 v[88:89], v[88:89], v[44:45]
	v_pk_add_f32 v[88:89], v[88:89], v[46:47]
	v_add_f32_e32 v90, v88, v89
	v_lshlrev_b32_e32 v48, 16, v104
	v_and_b32_e32 v49, 0xffff0000, v104
	v_lshlrev_b32_e32 v50, 16, v105
	v_and_b32_e32 v51, 0xffff0000, v105
	v_lshlrev_b32_e32 v52, 16, v106
	v_and_b32_e32 v53, 0xffff0000, v106
	v_lshlrev_b32_e32 v54, 16, v107
	v_and_b32_e32 v55, 0xffff0000, v107
	v_add_f32_dpp v90, v90, v90 quad_perm:[1,0,3,2] row_mask:0xf bank_mask:0xf
	v_lshlrev_b32_e32 v64, 16, v108
	v_and_b32_e32 v65, 0xffff0000, v108
	v_lshlrev_b32_e32 v66, 16, v109
	v_and_b32_e32 v67, 0xffff0000, v109
	v_add_f32_dpp v90, v90, v90 quad_perm:[2,3,0,1] row_mask:0xf bank_mask:0xf
	v_lshlrev_b32_e32 v68, 16, v110
	v_and_b32_e32 v69, 0xffff0000, v110
	v_lshlrev_b32_e32 v70, 16, v111
	v_and_b32_e32 v71, 0xffff0000, v111
	v_add_f32_dpp v90, v90, v90 row_half_mirror row_mask:0xf bank_mask:0xf
	v_pk_add_f32 v[72:73], v[56:57], v[48:49] neg_lo:[0,1] neg_hi:[0,1]
	v_pk_add_f32 v[74:75], v[58:59], v[50:51] neg_lo:[0,1] neg_hi:[0,1]
	v_pk_add_f32 v[76:77], v[60:61], v[52:53] neg_lo:[0,1] neg_hi:[0,1]
	v_pk_add_f32 v[78:79], v[62:63], v[54:55] neg_lo:[0,1] neg_hi:[0,1]
	v_mul_f32_e32 v92, 0x3c800000, v90
	v_mov_b32_e32 v96, v112
	v_pk_add_f32 v[40:41], v[40:41], v[92:93] op_sel_hi:[1,0] neg_lo:[0,1] neg_hi:[0,1]
	v_pk_add_f32 v[42:43], v[42:43], v[92:93] op_sel_hi:[1,0] neg_lo:[0,1] neg_hi:[0,1]
	v_pk_add_f32 v[44:45], v[44:45], v[92:93] op_sel_hi:[1,0] neg_lo:[0,1] neg_hi:[0,1]
	v_pk_add_f32 v[46:47], v[46:47], v[92:93] op_sel_hi:[1,0] neg_lo:[0,1] neg_hi:[0,1]
	v_pk_mul_f32 v[88:89], v[40:41], v[40:41]
	v_pk_fma_f32 v[88:89], v[42:43], v[42:43], v[88:89]
	v_pk_fma_f32 v[88:89], v[44:45], v[44:45], v[88:89]
	v_pk_fma_f32 v[88:89], v[46:47], v[46:47], v[88:89]
	v_add_f32_e32 v91, v88, v89
	v_pk_fma_f32 v[72:73], v[72:73], v[8:9], v[48:49]
	v_pk_fma_f32 v[74:75], v[74:75], v[10:11], v[50:51]
	v_add_f32_dpp v91, v91, v91 quad_perm:[1,0,3,2] row_mask:0xf bank_mask:0xf
	v_pk_fma_f32 v[76:77], v[76:77], v[12:13], v[52:53]
	v_pk_fma_f32 v[78:79], v[78:79], v[14:15], v[54:55]
	v_add_f32_dpp v91, v91, v91 quad_perm:[2,3,0,1] row_mask:0xf bank_mask:0xf
	s_nop 1
	v_add_f32_dpp v91, v91, v91 row_half_mirror row_mask:0xf bank_mask:0xf
	s_nop 0
	v_fmamk_f32 v94, v91, 0x3c800000, v5
	v_rsq_f32_e32 v94, v94
	s_nop 0
	v_pk_mul_f32 v[40:41], v[40:41], v[94:95] op_sel_hi:[1,0]
	v_pk_mul_f32 v[42:43], v[42:43], v[94:95] op_sel_hi:[1,0]
	v_pk_mul_f32 v[44:45], v[44:45], v[94:95] op_sel_hi:[1,0]
	v_pk_mul_f32 v[46:47], v[46:47], v[94:95] op_sel_hi:[1,0]
	v_pk_fma_f32 v[40:41], v[40:41], v[16:17], v[24:25]
	v_pk_fma_f32 v[42:43], v[42:43], v[18:19], v[26:27]
	v_pk_fma_f32 v[44:45], v[44:45], v[20:21], v[28:29]
	v_pk_fma_f32 v[46:47], v[46:47], v[22:23], v[30:31]
	v_pk_fma_f32 v[80:81], v[72:73], v[96:97], v[40:41] op_sel_hi:[1,0,1]
	v_pk_fma_f32 v[82:83], v[74:75], v[96:97], v[42:43] op_sel_hi:[1,0,1]
	v_pk_fma_f32 v[84:85], v[76:77], v[96:97], v[44:45] op_sel_hi:[1,0,1]
	v_pk_fma_f32 v[86:87], v[78:79], v[96:97], v[46:47] op_sel_hi:[1,0,1]
	v_pk_mul_f32 v[80:81], v[80:81], v[64:65]
	v_pk_mul_f32 v[82:83], v[82:83], v[66:67]
	v_pk_mul_f32 v[84:85], v[84:85], v[68:69]
	v_pk_mul_f32 v[86:87], v[86:87], v[70:71]
	v_cvt_pk_bf16_f32 v72, v80, v81
	v_cvt_pk_bf16_f32 v73, v82, v83
	v_cvt_pk_bf16_f32 v74, v84, v85
	v_cvt_pk_bf16_f32 v75, v86, v87
	global_store_dwordx4 v1, v[72:75], s[8:9]
	s_add_u32 s8, s8, 0x400
	s_addc_u32 s9, s9, 0
	global_load_dwordx4 v[212:215], v1, s[6:7]
	global_load_dwordx4 v[216:219], v1, s[10:11]
	global_load_dwordx4 v[220:223], v1, s[12:13]
	global_load_dword v224, v3, s[14:15]
	s_add_u32 s6, s6, 0x400
	s_addc_u32 s7, s7, 0
	s_add_u32 s10, s10, 0xe00
	s_addc_u32 s11, s11, 0
	s_add_u32 s12, s12, 0xc00
	s_addc_u32 s13, s13, 0
	s_add_u32 s14, s14, 32
	s_addc_u32 s15, s15, 0
	s_waitcnt vmcnt(35)
	v_lshlrev_b32_e32 v40, 16, v114
	v_and_b32_e32 v41, 0xffff0000, v114
	v_lshlrev_b32_e32 v42, 16, v115
	v_and_b32_e32 v43, 0xffff0000, v115
	v_lshlrev_b32_e32 v44, 16, v116
	v_and_b32_e32 v45, 0xffff0000, v116
	v_lshlrev_b32_e32 v46, 16, v117
	v_and_b32_e32 v47, 0xffff0000, v117
	v_pk_add_f32 v[88:89], v[40:41], v[42:43]
	v_pk_add_f32 v[88:89], v[88:89], v[44:45]
	v_pk_add_f32 v[88:89], v[88:89], v[46:47]
	v_add_f32_e32 v90, v88, v89
	v_lshlrev_b32_e32 v56, 16, v118
	v_and_b32_e32 v57, 0xffff0000, v118
	v_lshlrev_b32_e32 v58, 16, v119
	v_and_b32_e32 v59, 0xffff0000, v119
	v_lshlrev_b32_e32 v60, 16, v120
	v_and_b32_e32 v61, 0xffff0000, v120
	v_lshlrev_b32_e32 v62, 16, v121
	v_and_b32_e32 v63, 0xffff0000, v121
	v_add_f32_dpp v90, v90, v90 quad_perm:[1,0,3,2] row_mask:0xf bank_mask:0xf
	v_lshlrev_b32_e32 v64, 16, v122
	v_and_b32_e32 v65, 0xffff0000, v122
	v_lshlrev_b32_e32 v66, 16, v123
	v_and_b32_e32 v67, 0xffff0000, v123
	v_add_f32_dpp v90, v90, v90 quad_perm:[2,3,0,1] row_mask:0xf bank_mask:0xf
	v_lshlrev_b32_e32 v68, 16, v124
	v_and_b32_e32 v69, 0xffff0000, v124
	v_lshlrev_b32_e32 v70, 16, v125
	v_and_b32_e32 v71, 0xffff0000, v125
	v_add_f32_dpp v90, v90, v90 row_half_mirror row_mask:0xf bank_mask:0xf
	v_pk_add_f32 v[72:73], v[48:49], v[56:57] neg_lo:[0,1] neg_hi:[0,1]
	v_pk_add_f32 v[74:75], v[50:51], v[58:59] neg_lo:[0,1] neg_hi:[0,1]
	v_pk_add_f32 v[76:77], v[52:53], v[60:61] neg_lo:[0,1] neg_hi:[0,1]
	v_pk_add_f32 v[78:79], v[54:55], v[62:63] neg_lo:[0,1] neg_hi:[0,1]
	v_mul_f32_e32 v92, 0x3c800000, v90
	v_mov_b32_e32 v96, v126
	v_pk_add_f32 v[40:41], v[40:41], v[92:93] op_sel_hi:[1,0] neg_lo:[0,1] neg_hi:[0,1]
	v_pk_add_f32 v[42:43], v[42:43], v[92:93] op_sel_hi:[1,0] neg_lo:[0,1] neg_hi:[0,1]
	v_pk_add_f32 v[44:45], v[44:45], v[92:93] op_sel_hi:[1,0] neg_lo:[0,1] neg_hi:[0,1]
	v_pk_add_f32 v[46:47], v[46:47], v[92:93] op_sel_hi:[1,0] neg_lo:[0,1] neg_hi:[0,1]
	v_pk_mul_f32 v[88:89], v[40:41], v[40:41]
	v_pk_fma_f32 v[88:89], v[42:43], v[42:43], v[88:89]
	v_pk_fma_f32 v[88:89], v[44:45], v[44:45], v[88:89]
	v_pk_fma_f32 v[88:89], v[46:47], v[46:47], v[88:89]
	v_add_f32_e32 v91, v88, v89
	v_pk_fma_f32 v[72:73], v[72:73], v[8:9], v[56:57]
	v_pk_fma_f32 v[74:75], v[74:75], v[10:11], v[58:59]
	v_add_f32_dpp v91, v91, v91 quad_perm:[1,0,3,2] row_mask:0xf bank_mask:0xf
	v_pk_fma_f32 v[76:77], v[76:77], v[12:13], v[60:61]
	v_pk_fma_f32 v[78:79], v[78:79], v[14:15], v[62:63]
	v_add_f32_dpp v91, v91, v91 quad_perm:[2,3,0,1] row_mask:0xf bank_mask:0xf
	s_nop 1
	v_add_f32_dpp v91, v91, v91 row_half_mirror row_mask:0xf bank_mask:0xf
	s_nop 0
	v_fmamk_f32 v94, v91, 0x3c800000, v5
	v_rsq_f32_e32 v94, v94
	s_nop 0
	v_pk_mul_f32 v[40:41], v[40:41], v[94:95] op_sel_hi:[1,0]
	v_pk_mul_f32 v[42:43], v[42:43], v[94:95] op_sel_hi:[1,0]
	v_pk_mul_f32 v[44:45], v[44:45], v[94:95] op_sel_hi:[1,0]
	v_pk_mul_f32 v[46:47], v[46:47], v[94:95] op_sel_hi:[1,0]
	v_pk_fma_f32 v[40:41], v[40:41], v[16:17], v[24:25]
	v_pk_fma_f32 v[42:43], v[42:43], v[18:19], v[26:27]
	v_pk_fma_f32 v[44:45], v[44:45], v[20:21], v[28:29]
	v_pk_fma_f32 v[46:47], v[46:47], v[22:23], v[30:31]
	v_pk_fma_f32 v[80:81], v[72:73], v[96:97], v[40:41] op_sel_hi:[1,0,1]
	v_pk_fma_f32 v[82:83], v[74:75], v[96:97], v[42:43] op_sel_hi:[1,0,1]
	v_pk_fma_f32 v[84:85], v[76:77], v[96:97], v[44:45] op_sel_hi:[1,0,1]
	v_pk_fma_f32 v[86:87], v[78:79], v[96:97], v[46:47] op_sel_hi:[1,0,1]
	v_pk_mul_f32 v[80:81], v[80:81], v[64:65]
	v_pk_mul_f32 v[82:83], v[82:83], v[66:67]
	v_pk_mul_f32 v[84:85], v[84:85], v[68:69]
	v_pk_mul_f32 v[86:87], v[86:87], v[70:71]
	v_cvt_pk_bf16_f32 v72, v80, v81
	v_cvt_pk_bf16_f32 v73, v82, v83
	v_cvt_pk_bf16_f32 v74, v84, v85
	v_cvt_pk_bf16_f32 v75, v86, v87
	global_store_dwordx4 v1, v[72:75], s[8:9]
	s_add_u32 s8, s8, 0x400
	s_addc_u32 s9, s9, 0
	global_load_dwordx4 v[226:229], v1, s[6:7]
	global_load_dwordx4 v[230:233], v1, s[10:11]
	global_load_dwordx4 v[234:237], v1, s[12:13]
	global_load_dword v238, v3, s[14:15]
	s_add_u32 s6, s6, 0x400
	s_addc_u32 s7, s7, 0
	s_add_u32 s10, s10, 0xe00
	s_addc_u32 s11, s11, 0
	s_add_u32 s12, s12, 0xc00
	s_addc_u32 s13, s13, 0
	s_add_u32 s14, s14, 32
	s_addc_u32 s15, s15, 0
	s_waitcnt vmcnt(35)
	v_lshlrev_b32_e32 v40, 16, v128
	v_and_b32_e32 v41, 0xffff0000, v128
	v_lshlrev_b32_e32 v42, 16, v129
	v_and_b32_e32 v43, 0xffff0000, v129
	v_lshlrev_b32_e32 v44, 16, v130
	v_and_b32_e32 v45, 0xffff0000, v130
	v_lshlrev_b32_e32 v46, 16, v131
	v_and_b32_e32 v47, 0xffff0000, v131
	v_pk_add_f32 v[88:89], v[40:41], v[42:43]
	v_pk_add_f32 v[88:89], v[88:89], v[44:45]
	v_pk_add_f32 v[88:89], v[88:89], v[46:47]
	v_add_f32_e32 v90, v88, v89
	v_lshlrev_b32_e32 v48, 16, v132
	v_and_b32_e32 v49, 0xffff0000, v132
	v_lshlrev_b32_e32 v50, 16, v133
	v_and_b32_e32 v51, 0xffff0000, v133
	v_lshlrev_b32_e32 v52, 16, v134
	v_and_b32_e32 v53, 0xffff0000, v134
	v_lshlrev_b32_e32 v54, 16, v135
	v_and_b32_e32 v55, 0xffff0000, v135
	v_add_f32_dpp v90, v90, v90 quad_perm:[1,0,3,2] row_mask:0xf bank_mask:0xf
	v_lshlrev_b32_e32 v64, 16, v136
	v_and_b32_e32 v65, 0xffff0000, v136
	v_lshlrev_b32_e32 v66, 16, v137
	v_and_b32_e32 v67, 0xffff0000, v137
	v_add_f32_dpp v90, v90, v90 quad_perm:[2,3,0,1] row_mask:0xf bank_mask:0xf
	v_lshlrev_b32_e32 v68, 16, v138
	v_and_b32_e32 v69, 0xffff0000, v138
	v_lshlrev_b32_e32 v70, 16, v139
	v_and_b32_e32 v71, 0xffff0000, v139
	v_add_f32_dpp v90, v90, v90 row_half_mirror row_mask:0xf bank_mask:0xf
	v_pk_add_f32 v[72:73], v[56:57], v[48:49] neg_lo:[0,1] neg_hi:[0,1]
	v_pk_add_f32 v[74:75], v[58:59], v[50:51] neg_lo:[0,1] neg_hi:[0,1]
	v_pk_add_f32 v[76:77], v[60:61], v[52:53] neg_lo:[0,1] neg_hi:[0,1]
	v_pk_add_f32 v[78:79], v[62:63], v[54:55] neg_lo:[0,1] neg_hi:[0,1]
	v_mul_f32_e32 v92, 0x3c800000, v90
	v_mov_b32_e32 v96, v140
	v_pk_add_f32 v[40:41], v[40:41], v[92:93] op_sel_hi:[1,0] neg_lo:[0,1] neg_hi:[0,1]
	v_pk_add_f32 v[42:43], v[42:43], v[92:93] op_sel_hi:[1,0] neg_lo:[0,1] neg_hi:[0,1]
	v_pk_add_f32 v[44:45], v[44:45], v[92:93] op_sel_hi:[1,0] neg_lo:[0,1] neg_hi:[0,1]
	v_pk_add_f32 v[46:47], v[46:47], v[92:93] op_sel_hi:[1,0] neg_lo:[0,1] neg_hi:[0,1]
	v_pk_mul_f32 v[88:89], v[40:41], v[40:41]
	v_pk_fma_f32 v[88:89], v[42:43], v[42:43], v[88:89]
	v_pk_fma_f32 v[88:89], v[44:45], v[44:45], v[88:89]
	v_pk_fma_f32 v[88:89], v[46:47], v[46:47], v[88:89]
	v_add_f32_e32 v91, v88, v89
	v_pk_fma_f32 v[72:73], v[72:73], v[8:9], v[48:49]
	v_pk_fma_f32 v[74:75], v[74:75], v[10:11], v[50:51]
	v_add_f32_dpp v91, v91, v91 quad_perm:[1,0,3,2] row_mask:0xf bank_mask:0xf
	v_pk_fma_f32 v[76:77], v[76:77], v[12:13], v[52:53]
	v_pk_fma_f32 v[78:79], v[78:79], v[14:15], v[54:55]
	v_add_f32_dpp v91, v91, v91 quad_perm:[2,3,0,1] row_mask:0xf bank_mask:0xf
	s_nop 1
	v_add_f32_dpp v91, v91, v91 row_half_mirror row_mask:0xf bank_mask:0xf
	s_nop 0
	v_fmamk_f32 v94, v91, 0x3c800000, v5
	v_rsq_f32_e32 v94, v94
	s_nop 0
	v_pk_mul_f32 v[40:41], v[40:41], v[94:95] op_sel_hi:[1,0]
	v_pk_mul_f32 v[42:43], v[42:43], v[94:95] op_sel_hi:[1,0]
	v_pk_mul_f32 v[44:45], v[44:45], v[94:95] op_sel_hi:[1,0]
	v_pk_mul_f32 v[46:47], v[46:47], v[94:95] op_sel_hi:[1,0]
	v_pk_fma_f32 v[40:41], v[40:41], v[16:17], v[24:25]
	v_pk_fma_f32 v[42:43], v[42:43], v[18:19], v[26:27]
	v_pk_fma_f32 v[44:45], v[44:45], v[20:21], v[28:29]
	v_pk_fma_f32 v[46:47], v[46:47], v[22:23], v[30:31]
	v_pk_fma_f32 v[80:81], v[72:73], v[96:97], v[40:41] op_sel_hi:[1,0,1]
	v_pk_fma_f32 v[82:83], v[74:75], v[96:97], v[42:43] op_sel_hi:[1,0,1]
	v_pk_fma_f32 v[84:85], v[76:77], v[96:97], v[44:45] op_sel_hi:[1,0,1]
	v_pk_fma_f32 v[86:87], v[78:79], v[96:97], v[46:47] op_sel_hi:[1,0,1]
	v_pk_mul_f32 v[80:81], v[80:81], v[64:65]
	v_pk_mul_f32 v[82:83], v[82:83], v[66:67]
	v_pk_mul_f32 v[84:85], v[84:85], v[68:69]
	v_pk_mul_f32 v[86:87], v[86:87], v[70:71]
	v_cvt_pk_bf16_f32 v72, v80, v81
	v_cvt_pk_bf16_f32 v73, v82, v83
	v_cvt_pk_bf16_f32 v74, v84, v85
	v_cvt_pk_bf16_f32 v75, v86, v87
	global_store_dwordx4 v1, v[72:75], s[8:9]
	s_add_u32 s8, s8, 0x400
	s_addc_u32 s9, s9, 0
	global_load_dwordx4 v[100:103], v1, s[6:7]
	global_load_dwordx4 v[104:107], v1, s[10:11]
	global_load_dwordx4 v[108:111], v1, s[12:13]
	global_load_dword v112, v3, s[14:15]
	s_add_u32 s6, s6, 0x400
	s_addc_u32 s7, s7, 0
	s_add_u32 s10, s10, 0xe00
	s_addc_u32 s11, s11, 0
	s_add_u32 s12, s12, 0xc00
	s_addc_u32 s13, s13, 0
	s_add_u32 s14, s14, 32
	s_addc_u32 s15, s15, 0
	s_waitcnt vmcnt(35)
	v_lshlrev_b32_e32 v40, 16, v142
	v_and_b32_e32 v41, 0xffff0000, v142
	v_lshlrev_b32_e32 v42, 16, v143
	v_and_b32_e32 v43, 0xffff0000, v143
	v_lshlrev_b32_e32 v44, 16, v144
	v_and_b32_e32 v45, 0xffff0000, v144
	v_lshlrev_b32_e32 v46, 16, v145
	v_and_b32_e32 v47, 0xffff0000, v145
	v_pk_add_f32 v[88:89], v[40:41], v[42:43]
	v_pk_add_f32 v[88:89], v[88:89], v[44:45]
	v_pk_add_f32 v[88:89], v[88:89], v[46:47]
	v_add_f32_e32 v90, v88, v89
	v_lshlrev_b32_e32 v56, 16, v146
	v_and_b32_e32 v57, 0xffff0000, v146
	v_lshlrev_b32_e32 v58, 16, v147
	v_and_b32_e32 v59, 0xffff0000, v147
	v_lshlrev_b32_e32 v60, 16, v148
	v_and_b32_e32 v61, 0xffff0000, v148
	v_lshlrev_b32_e32 v62, 16, v149
	v_and_b32_e32 v63, 0xffff0000, v149
	v_add_f32_dpp v90, v90, v90 quad_perm:[1,0,3,2] row_mask:0xf bank_mask:0xf
	v_lshlrev_b32_e32 v64, 16, v150
	v_and_b32_e32 v65, 0xffff0000, v150
	v_lshlrev_b32_e32 v66, 16, v151
	v_and_b32_e32 v67, 0xffff0000, v151
	v_add_f32_dpp v90, v90, v90 quad_perm:[2,3,0,1] row_mask:0xf bank_mask:0xf
	v_lshlrev_b32_e32 v68, 16, v152
	v_and_b32_e32 v69, 0xffff0000, v152
	v_lshlrev_b32_e32 v70, 16, v153
	v_and_b32_e32 v71, 0xffff0000, v153
	v_add_f32_dpp v90, v90, v90 row_half_mirror row_mask:0xf bank_mask:0xf
	v_pk_add_f32 v[72:73], v[48:49], v[56:57] neg_lo:[0,1] neg_hi:[0,1]
	v_pk_add_f32 v[74:75], v[50:51], v[58:59] neg_lo:[0,1] neg_hi:[0,1]
	v_pk_add_f32 v[76:77], v[52:53], v[60:61] neg_lo:[0,1] neg_hi:[0,1]
	v_pk_add_f32 v[78:79], v[54:55], v[62:63] neg_lo:[0,1] neg_hi:[0,1]
	v_mul_f32_e32 v92, 0x3c800000, v90
	v_mov_b32_e32 v96, v154
	v_pk_add_f32 v[40:41], v[40:41], v[92:93] op_sel_hi:[1,0] neg_lo:[0,1] neg_hi:[0,1]
	v_pk_add_f32 v[42:43], v[42:43], v[92:93] op_sel_hi:[1,0] neg_lo:[0,1] neg_hi:[0,1]
	v_pk_add_f32 v[44:45], v[44:45], v[92:93] op_sel_hi:[1,0] neg_lo:[0,1] neg_hi:[0,1]
	v_pk_add_f32 v[46:47], v[46:47], v[92:93] op_sel_hi:[1,0] neg_lo:[0,1] neg_hi:[0,1]
	v_pk_mul_f32 v[88:89], v[40:41], v[40:41]
	v_pk_fma_f32 v[88:89], v[42:43], v[42:43], v[88:89]
	v_pk_fma_f32 v[88:89], v[44:45], v[44:45], v[88:89]
	v_pk_fma_f32 v[88:89], v[46:47], v[46:47], v[88:89]
	v_add_f32_e32 v91, v88, v89
	v_pk_fma_f32 v[72:73], v[72:73], v[8:9], v[56:57]
	v_pk_fma_f32 v[74:75], v[74:75], v[10:11], v[58:59]
	v_add_f32_dpp v91, v91, v91 quad_perm:[1,0,3,2] row_mask:0xf bank_mask:0xf
	v_pk_fma_f32 v[76:77], v[76:77], v[12:13], v[60:61]
	v_pk_fma_f32 v[78:79], v[78:79], v[14:15], v[62:63]
	v_add_f32_dpp v91, v91, v91 quad_perm:[2,3,0,1] row_mask:0xf bank_mask:0xf
	s_nop 1
	v_add_f32_dpp v91, v91, v91 row_half_mirror row_mask:0xf bank_mask:0xf
	s_nop 0
	v_fmamk_f32 v94, v91, 0x3c800000, v5
	v_rsq_f32_e32 v94, v94
	s_nop 0
	v_pk_mul_f32 v[40:41], v[40:41], v[94:95] op_sel_hi:[1,0]
	v_pk_mul_f32 v[42:43], v[42:43], v[94:95] op_sel_hi:[1,0]
	v_pk_mul_f32 v[44:45], v[44:45], v[94:95] op_sel_hi:[1,0]
	v_pk_mul_f32 v[46:47], v[46:47], v[94:95] op_sel_hi:[1,0]
	v_pk_fma_f32 v[40:41], v[40:41], v[16:17], v[24:25]
	v_pk_fma_f32 v[42:43], v[42:43], v[18:19], v[26:27]
	v_pk_fma_f32 v[44:45], v[44:45], v[20:21], v[28:29]
	v_pk_fma_f32 v[46:47], v[46:47], v[22:23], v[30:31]
	v_pk_fma_f32 v[80:81], v[72:73], v[96:97], v[40:41] op_sel_hi:[1,0,1]
	v_pk_fma_f32 v[82:83], v[74:75], v[96:97], v[42:43] op_sel_hi:[1,0,1]
	v_pk_fma_f32 v[84:85], v[76:77], v[96:97], v[44:45] op_sel_hi:[1,0,1]
	v_pk_fma_f32 v[86:87], v[78:79], v[96:97], v[46:47] op_sel_hi:[1,0,1]
	v_pk_mul_f32 v[80:81], v[80:81], v[64:65]
	v_pk_mul_f32 v[82:83], v[82:83], v[66:67]
	v_pk_mul_f32 v[84:85], v[84:85], v[68:69]
	v_pk_mul_f32 v[86:87], v[86:87], v[70:71]
	v_cvt_pk_bf16_f32 v72, v80, v81
	v_cvt_pk_bf16_f32 v73, v82, v83
	v_cvt_pk_bf16_f32 v74, v84, v85
	v_cvt_pk_bf16_f32 v75, v86, v87
	global_store_dwordx4 v1, v[72:75], s[8:9]
	s_add_u32 s8, s8, 0x400
	s_addc_u32 s9, s9, 0
	global_load_dwordx4 v[114:117], v1, s[6:7]
	global_load_dwordx4 v[118:121], v1, s[10:11]
	global_load_dwordx4 v[122:125], v1, s[12:13]
	global_load_dword v126, v3, s[14:15]
	s_add_u32 s6, s6, 0x400
	s_addc_u32 s7, s7, 0
	s_add_u32 s10, s10, 0xe00
	s_addc_u32 s11, s11, 0
	s_add_u32 s12, s12, 0xc00
	s_addc_u32 s13, s13, 0
	s_add_u32 s14, s14, 32
	s_addc_u32 s15, s15, 0
	s_waitcnt vmcnt(35)
	v_lshlrev_b32_e32 v40, 16, v156
	v_and_b32_e32 v41, 0xffff0000, v156
	v_lshlrev_b32_e32 v42, 16, v157
	v_and_b32_e32 v43, 0xffff0000, v157
	v_lshlrev_b32_e32 v44, 16, v158
	v_and_b32_e32 v45, 0xffff0000, v158
	v_lshlrev_b32_e32 v46, 16, v159
	v_and_b32_e32 v47, 0xffff0000, v159
	v_pk_add_f32 v[88:89], v[40:41], v[42:43]
	v_pk_add_f32 v[88:89], v[88:89], v[44:45]
	v_pk_add_f32 v[88:89], v[88:89], v[46:47]
	v_add_f32_e32 v90, v88, v89
	v_lshlrev_b32_e32 v48, 16, v160
	v_and_b32_e32 v49, 0xffff0000, v160
	v_lshlrev_b32_e32 v50, 16, v161
	v_and_b32_e32 v51, 0xffff0000, v161
	v_lshlrev_b32_e32 v52, 16, v162
	v_and_b32_e32 v53, 0xffff0000, v162
	v_lshlrev_b32_e32 v54, 16, v163
	v_and_b32_e32 v55, 0xffff0000, v163
	v_add_f32_dpp v90, v90, v90 quad_perm:[1,0,3,2] row_mask:0xf bank_mask:0xf
	v_lshlrev_b32_e32 v64, 16, v164
	v_and_b32_e32 v65, 0xffff0000, v164
	v_lshlrev_b32_e32 v66, 16, v165
	v_and_b32_e32 v67, 0xffff0000, v165
	v_add_f32_dpp v90, v90, v90 quad_perm:[2,3,0,1] row_mask:0xf bank_mask:0xf
	v_lshlrev_b32_e32 v68, 16, v166
	v_and_b32_e32 v69, 0xffff0000, v166
	v_lshlrev_b32_e32 v70, 16, v167
	v_and_b32_e32 v71, 0xffff0000, v167
	v_add_f32_dpp v90, v90, v90 row_half_mirror row_mask:0xf bank_mask:0xf
	v_pk_add_f32 v[72:73], v[56:57], v[48:49] neg_lo:[0,1] neg_hi:[0,1]
	v_pk_add_f32 v[74:75], v[58:59], v[50:51] neg_lo:[0,1] neg_hi:[0,1]
	v_pk_add_f32 v[76:77], v[60:61], v[52:53] neg_lo:[0,1] neg_hi:[0,1]
	v_pk_add_f32 v[78:79], v[62:63], v[54:55] neg_lo:[0,1] neg_hi:[0,1]
	v_mul_f32_e32 v92, 0x3c800000, v90
	v_mov_b32_e32 v96, v168
	v_pk_add_f32 v[40:41], v[40:41], v[92:93] op_sel_hi:[1,0] neg_lo:[0,1] neg_hi:[0,1]
	v_pk_add_f32 v[42:43], v[42:43], v[92:93] op_sel_hi:[1,0] neg_lo:[0,1] neg_hi:[0,1]
	v_pk_add_f32 v[44:45], v[44:45], v[92:93] op_sel_hi:[1,0] neg_lo:[0,1] neg_hi:[0,1]
	v_pk_add_f32 v[46:47], v[46:47], v[92:93] op_sel_hi:[1,0] neg_lo:[0,1] neg_hi:[0,1]
	v_pk_mul_f32 v[88:89], v[40:41], v[40:41]
	v_pk_fma_f32 v[88:89], v[42:43], v[42:43], v[88:89]
	v_pk_fma_f32 v[88:89], v[44:45], v[44:45], v[88:89]
	v_pk_fma_f32 v[88:89], v[46:47], v[46:47], v[88:89]
	v_add_f32_e32 v91, v88, v89
	v_pk_fma_f32 v[72:73], v[72:73], v[8:9], v[48:49]
	v_pk_fma_f32 v[74:75], v[74:75], v[10:11], v[50:51]
	v_add_f32_dpp v91, v91, v91 quad_perm:[1,0,3,2] row_mask:0xf bank_mask:0xf
	v_pk_fma_f32 v[76:77], v[76:77], v[12:13], v[52:53]
	v_pk_fma_f32 v[78:79], v[78:79], v[14:15], v[54:55]
	v_add_f32_dpp v91, v91, v91 quad_perm:[2,3,0,1] row_mask:0xf bank_mask:0xf
	s_nop 1
	v_add_f32_dpp v91, v91, v91 row_half_mirror row_mask:0xf bank_mask:0xf
	s_nop 0
	v_fmamk_f32 v94, v91, 0x3c800000, v5
	v_rsq_f32_e32 v94, v94
	s_nop 0
	v_pk_mul_f32 v[40:41], v[40:41], v[94:95] op_sel_hi:[1,0]
	v_pk_mul_f32 v[42:43], v[42:43], v[94:95] op_sel_hi:[1,0]
	v_pk_mul_f32 v[44:45], v[44:45], v[94:95] op_sel_hi:[1,0]
	v_pk_mul_f32 v[46:47], v[46:47], v[94:95] op_sel_hi:[1,0]
	v_pk_fma_f32 v[40:41], v[40:41], v[16:17], v[24:25]
	v_pk_fma_f32 v[42:43], v[42:43], v[18:19], v[26:27]
	v_pk_fma_f32 v[44:45], v[44:45], v[20:21], v[28:29]
	v_pk_fma_f32 v[46:47], v[46:47], v[22:23], v[30:31]
	v_pk_fma_f32 v[80:81], v[72:73], v[96:97], v[40:41] op_sel_hi:[1,0,1]
	v_pk_fma_f32 v[82:83], v[74:75], v[96:97], v[42:43] op_sel_hi:[1,0,1]
	v_pk_fma_f32 v[84:85], v[76:77], v[96:97], v[44:45] op_sel_hi:[1,0,1]
	v_pk_fma_f32 v[86:87], v[78:79], v[96:97], v[46:47] op_sel_hi:[1,0,1]
	v_pk_mul_f32 v[80:81], v[80:81], v[64:65]
	v_pk_mul_f32 v[82:83], v[82:83], v[66:67]
	v_pk_mul_f32 v[84:85], v[84:85], v[68:69]
	v_pk_mul_f32 v[86:87], v[86:87], v[70:71]
	v_cvt_pk_bf16_f32 v72, v80, v81
	v_cvt_pk_bf16_f32 v73, v82, v83
	v_cvt_pk_bf16_f32 v74, v84, v85
	v_cvt_pk_bf16_f32 v75, v86, v87
	global_store_dwordx4 v1, v[72:75], s[8:9]
	s_add_u32 s8, s8, 0x400
	s_addc_u32 s9, s9, 0
	s_waitcnt vmcnt(31)
	v_lshlrev_b32_e32 v40, 16, v170
	v_and_b32_e32 v41, 0xffff0000, v170
	v_lshlrev_b32_e32 v42, 16, v171
	v_and_b32_e32 v43, 0xffff0000, v171
	v_lshlrev_b32_e32 v44, 16, v172
	v_and_b32_e32 v45, 0xffff0000, v172
	v_lshlrev_b32_e32 v46, 16, v173
	v_and_b32_e32 v47, 0xffff0000, v173
	v_pk_add_f32 v[88:89], v[40:41], v[42:43]
	v_pk_add_f32 v[88:89], v[88:89], v[44:45]
	v_pk_add_f32 v[88:89], v[88:89], v[46:47]
	v_add_f32_e32 v90, v88, v89
	v_lshlrev_b32_e32 v56, 16, v174
	v_and_b32_e32 v57, 0xffff0000, v174
	v_lshlrev_b32_e32 v58, 16, v175
	v_and_b32_e32 v59, 0xffff0000, v175
	v_lshlrev_b32_e32 v60, 16, v176
	v_and_b32_e32 v61, 0xffff0000, v176
	v_lshlrev_b32_e32 v62, 16, v177
	v_and_b32_e32 v63, 0xffff0000, v177
	v_add_f32_dpp v90, v90, v90 quad_perm:[1,0,3,2] row_mask:0xf bank_mask:0xf
	v_lshlrev_b32_e32 v64, 16, v178
	v_and_b32_e32 v65, 0xffff0000, v178
	v_lshlrev_b32_e32 v66, 16, v179
	v_and_b32_e32 v67, 0xffff0000, v179
	v_add_f32_dpp v90, v90, v90 quad_perm:[2,3,0,1] row_mask:0xf bank_mask:0xf
	v_lshlrev_b32_e32 v68, 16, v180
	v_and_b32_e32 v69, 0xffff0000, v180
	v_lshlrev_b32_e32 v70, 16, v181
	v_and_b32_e32 v71, 0xffff0000, v181
	v_add_f32_dpp v90, v90, v90 row_half_mirror row_mask:0xf bank_mask:0xf
	v_pk_add_f32 v[72:73], v[48:49], v[56:57] neg_lo:[0,1] neg_hi:[0,1]
	v_pk_add_f32 v[74:75], v[50:51], v[58:59] neg_lo:[0,1] neg_hi:[0,1]
	v_pk_add_f32 v[76:77], v[52:53], v[60:61] neg_lo:[0,1] neg_hi:[0,1]
	v_pk_add_f32 v[78:79], v[54:55], v[62:63] neg_lo:[0,1] neg_hi:[0,1]
	v_mul_f32_e32 v92, 0x3c800000, v90
	v_mov_b32_e32 v96, v182
	v_pk_add_f32 v[40:41], v[40:41], v[92:93] op_sel_hi:[1,0] neg_lo:[0,1] neg_hi:[0,1]
	v_pk_add_f32 v[42:43], v[42:43], v[92:93] op_sel_hi:[1,0] neg_lo:[0,1] neg_hi:[0,1]
	v_pk_add_f32 v[44:45], v[44:45], v[92:93] op_sel_hi:[1,0] neg_lo:[0,1] neg_hi:[0,1]
	v_pk_add_f32 v[46:47], v[46:47], v[92:93] op_sel_hi:[1,0] neg_lo:[0,1] neg_hi:[0,1]
	v_pk_mul_f32 v[88:89], v[40:41], v[40:41]
	v_pk_fma_f32 v[88:89], v[42:43], v[42:43], v[88:89]
	v_pk_fma_f32 v[88:89], v[44:45], v[44:45], v[88:89]
	v_pk_fma_f32 v[88:89], v[46:47], v[46:47], v[88:89]
	v_add_f32_e32 v91, v88, v89
	v_pk_fma_f32 v[72:73], v[72:73], v[8:9], v[56:57]
	v_pk_fma_f32 v[74:75], v[74:75], v[10:11], v[58:59]
	v_add_f32_dpp v91, v91, v91 quad_perm:[1,0,3,2] row_mask:0xf bank_mask:0xf
	v_pk_fma_f32 v[76:77], v[76:77], v[12:13], v[60:61]
	v_pk_fma_f32 v[78:79], v[78:79], v[14:15], v[62:63]
	v_add_f32_dpp v91, v91, v91 quad_perm:[2,3,0,1] row_mask:0xf bank_mask:0xf
	s_nop 1
	v_add_f32_dpp v91, v91, v91 row_half_mirror row_mask:0xf bank_mask:0xf
	s_nop 0
	v_fmamk_f32 v94, v91, 0x3c800000, v5
	v_rsq_f32_e32 v94, v94
	s_nop 0
	v_pk_mul_f32 v[40:41], v[40:41], v[94:95] op_sel_hi:[1,0]
	v_pk_mul_f32 v[42:43], v[42:43], v[94:95] op_sel_hi:[1,0]
	v_pk_mul_f32 v[44:45], v[44:45], v[94:95] op_sel_hi:[1,0]
	v_pk_mul_f32 v[46:47], v[46:47], v[94:95] op_sel_hi:[1,0]
	v_pk_fma_f32 v[40:41], v[40:41], v[16:17], v[24:25]
	v_pk_fma_f32 v[42:43], v[42:43], v[18:19], v[26:27]
	v_pk_fma_f32 v[44:45], v[44:45], v[20:21], v[28:29]
	v_pk_fma_f32 v[46:47], v[46:47], v[22:23], v[30:31]
	v_pk_fma_f32 v[80:81], v[72:73], v[96:97], v[40:41] op_sel_hi:[1,0,1]
	v_pk_fma_f32 v[82:83], v[74:75], v[96:97], v[42:43] op_sel_hi:[1,0,1]
	v_pk_fma_f32 v[84:85], v[76:77], v[96:97], v[44:45] op_sel_hi:[1,0,1]
	v_pk_fma_f32 v[86:87], v[78:79], v[96:97], v[46:47] op_sel_hi:[1,0,1]
	v_pk_mul_f32 v[80:81], v[80:81], v[64:65]
	v_pk_mul_f32 v[82:83], v[82:83], v[66:67]
	v_pk_mul_f32 v[84:85], v[84:85], v[68:69]
	v_pk_mul_f32 v[86:87], v[86:87], v[70:71]
	v_cvt_pk_bf16_f32 v72, v80, v81
	v_cvt_pk_bf16_f32 v73, v82, v83
	v_cvt_pk_bf16_f32 v74, v84, v85
	v_cvt_pk_bf16_f32 v75, v86, v87
	global_store_dwordx4 v1, v[72:75], s[8:9]
	s_add_u32 s8, s8, 0x400
	s_addc_u32 s9, s9, 0
	s_waitcnt vmcnt(27)
	v_lshlrev_b32_e32 v40, 16, v184
	v_and_b32_e32 v41, 0xffff0000, v184
	v_lshlrev_b32_e32 v42, 16, v185
	v_and_b32_e32 v43, 0xffff0000, v185
	v_lshlrev_b32_e32 v44, 16, v186
	v_and_b32_e32 v45, 0xffff0000, v186
	v_lshlrev_b32_e32 v46, 16, v187
	v_and_b32_e32 v47, 0xffff0000, v187
	v_pk_add_f32 v[88:89], v[40:41], v[42:43]
	v_pk_add_f32 v[88:89], v[88:89], v[44:45]
	v_pk_add_f32 v[88:89], v[88:89], v[46:47]
	v_add_f32_e32 v90, v88, v89
	v_lshlrev_b32_e32 v48, 16, v188
	v_and_b32_e32 v49, 0xffff0000, v188
	v_lshlrev_b32_e32 v50, 16, v189
	v_and_b32_e32 v51, 0xffff0000, v189
	v_lshlrev_b32_e32 v52, 16, v190
	v_and_b32_e32 v53, 0xffff0000, v190
	v_lshlrev_b32_e32 v54, 16, v191
	v_and_b32_e32 v55, 0xffff0000, v191
	v_add_f32_dpp v90, v90, v90 quad_perm:[1,0,3,2] row_mask:0xf bank_mask:0xf
	v_lshlrev_b32_e32 v64, 16, v192
	v_and_b32_e32 v65, 0xffff0000, v192
	v_lshlrev_b32_e32 v66, 16, v193
	v_and_b32_e32 v67, 0xffff0000, v193
	v_add_f32_dpp v90, v90, v90 quad_perm:[2,3,0,1] row_mask:0xf bank_mask:0xf
	v_lshlrev_b32_e32 v68, 16, v194
	v_and_b32_e32 v69, 0xffff0000, v194
	v_lshlrev_b32_e32 v70, 16, v195
	v_and_b32_e32 v71, 0xffff0000, v195
	v_add_f32_dpp v90, v90, v90 row_half_mirror row_mask:0xf bank_mask:0xf
	v_pk_add_f32 v[72:73], v[56:57], v[48:49] neg_lo:[0,1] neg_hi:[0,1]
	v_pk_add_f32 v[74:75], v[58:59], v[50:51] neg_lo:[0,1] neg_hi:[0,1]
	v_pk_add_f32 v[76:77], v[60:61], v[52:53] neg_lo:[0,1] neg_hi:[0,1]
	v_pk_add_f32 v[78:79], v[62:63], v[54:55] neg_lo:[0,1] neg_hi:[0,1]
	v_mul_f32_e32 v92, 0x3c800000, v90
	v_mov_b32_e32 v96, v196
	v_pk_add_f32 v[40:41], v[40:41], v[92:93] op_sel_hi:[1,0] neg_lo:[0,1] neg_hi:[0,1]
	v_pk_add_f32 v[42:43], v[42:43], v[92:93] op_sel_hi:[1,0] neg_lo:[0,1] neg_hi:[0,1]
	v_pk_add_f32 v[44:45], v[44:45], v[92:93] op_sel_hi:[1,0] neg_lo:[0,1] neg_hi:[0,1]
	v_pk_add_f32 v[46:47], v[46:47], v[92:93] op_sel_hi:[1,0] neg_lo:[0,1] neg_hi:[0,1]
	v_pk_mul_f32 v[88:89], v[40:41], v[40:41]
	v_pk_fma_f32 v[88:89], v[42:43], v[42:43], v[88:89]
	v_pk_fma_f32 v[88:89], v[44:45], v[44:45], v[88:89]
	v_pk_fma_f32 v[88:89], v[46:47], v[46:47], v[88:89]
	v_add_f32_e32 v91, v88, v89
	v_pk_fma_f32 v[72:73], v[72:73], v[8:9], v[48:49]
	v_pk_fma_f32 v[74:75], v[74:75], v[10:11], v[50:51]
	v_add_f32_dpp v91, v91, v91 quad_perm:[1,0,3,2] row_mask:0xf bank_mask:0xf
	v_pk_fma_f32 v[76:77], v[76:77], v[12:13], v[52:53]
	v_pk_fma_f32 v[78:79], v[78:79], v[14:15], v[54:55]
	v_add_f32_dpp v91, v91, v91 quad_perm:[2,3,0,1] row_mask:0xf bank_mask:0xf
	s_nop 1
	v_add_f32_dpp v91, v91, v91 row_half_mirror row_mask:0xf bank_mask:0xf
	s_nop 0
	v_fmamk_f32 v94, v91, 0x3c800000, v5
	v_rsq_f32_e32 v94, v94
	s_nop 0
	v_pk_mul_f32 v[40:41], v[40:41], v[94:95] op_sel_hi:[1,0]
	v_pk_mul_f32 v[42:43], v[42:43], v[94:95] op_sel_hi:[1,0]
	v_pk_mul_f32 v[44:45], v[44:45], v[94:95] op_sel_hi:[1,0]
	v_pk_mul_f32 v[46:47], v[46:47], v[94:95] op_sel_hi:[1,0]
	v_pk_fma_f32 v[40:41], v[40:41], v[16:17], v[24:25]
	v_pk_fma_f32 v[42:43], v[42:43], v[18:19], v[26:27]
	v_pk_fma_f32 v[44:45], v[44:45], v[20:21], v[28:29]
	v_pk_fma_f32 v[46:47], v[46:47], v[22:23], v[30:31]
	v_pk_fma_f32 v[80:81], v[72:73], v[96:97], v[40:41] op_sel_hi:[1,0,1]
	v_pk_fma_f32 v[82:83], v[74:75], v[96:97], v[42:43] op_sel_hi:[1,0,1]
	v_pk_fma_f32 v[84:85], v[76:77], v[96:97], v[44:45] op_sel_hi:[1,0,1]
	v_pk_fma_f32 v[86:87], v[78:79], v[96:97], v[46:47] op_sel_hi:[1,0,1]
	v_pk_mul_f32 v[80:81], v[80:81], v[64:65]
	v_pk_mul_f32 v[82:83], v[82:83], v[66:67]
	v_pk_mul_f32 v[84:85], v[84:85], v[68:69]
	v_pk_mul_f32 v[86:87], v[86:87], v[70:71]
	v_cvt_pk_bf16_f32 v72, v80, v81
	v_cvt_pk_bf16_f32 v73, v82, v83
	v_cvt_pk_bf16_f32 v74, v84, v85
	v_cvt_pk_bf16_f32 v75, v86, v87
	global_store_dwordx4 v1, v[72:75], s[8:9]
	s_add_u32 s8, s8, 0x400
	s_addc_u32 s9, s9, 0
	s_waitcnt vmcnt(23)
	v_lshlrev_b32_e32 v40, 16, v198
	v_and_b32_e32 v41, 0xffff0000, v198
	v_lshlrev_b32_e32 v42, 16, v199
	v_and_b32_e32 v43, 0xffff0000, v199
	v_lshlrev_b32_e32 v44, 16, v200
	v_and_b32_e32 v45, 0xffff0000, v200
	v_lshlrev_b32_e32 v46, 16, v201
	v_and_b32_e32 v47, 0xffff0000, v201
	v_pk_add_f32 v[88:89], v[40:41], v[42:43]
	v_pk_add_f32 v[88:89], v[88:89], v[44:45]
	v_pk_add_f32 v[88:89], v[88:89], v[46:47]
	v_add_f32_e32 v90, v88, v89
	v_lshlrev_b32_e32 v56, 16, v202
	v_and_b32_e32 v57, 0xffff0000, v202
	v_lshlrev_b32_e32 v58, 16, v203
	v_and_b32_e32 v59, 0xffff0000, v203
	v_lshlrev_b32_e32 v60, 16, v204
	v_and_b32_e32 v61, 0xffff0000, v204
	v_lshlrev_b32_e32 v62, 16, v205
	v_and_b32_e32 v63, 0xffff0000, v205
	v_add_f32_dpp v90, v90, v90 quad_perm:[1,0,3,2] row_mask:0xf bank_mask:0xf
	v_lshlrev_b32_e32 v64, 16, v206
	v_and_b32_e32 v65, 0xffff0000, v206
	v_lshlrev_b32_e32 v66, 16, v207
	v_and_b32_e32 v67, 0xffff0000, v207
	v_add_f32_dpp v90, v90, v90 quad_perm:[2,3,0,1] row_mask:0xf bank_mask:0xf
	v_lshlrev_b32_e32 v68, 16, v208
	v_and_b32_e32 v69, 0xffff0000, v208
	v_lshlrev_b32_e32 v70, 16, v209
	v_and_b32_e32 v71, 0xffff0000, v209
	v_add_f32_dpp v90, v90, v90 row_half_mirror row_mask:0xf bank_mask:0xf
	v_pk_add_f32 v[72:73], v[48:49], v[56:57] neg_lo:[0,1] neg_hi:[0,1]
	v_pk_add_f32 v[74:75], v[50:51], v[58:59] neg_lo:[0,1] neg_hi:[0,1]
	v_pk_add_f32 v[76:77], v[52:53], v[60:61] neg_lo:[0,1] neg_hi:[0,1]
	v_pk_add_f32 v[78:79], v[54:55], v[62:63] neg_lo:[0,1] neg_hi:[0,1]
	v_mul_f32_e32 v92, 0x3c800000, v90
	v_mov_b32_e32 v96, v210
	v_pk_add_f32 v[40:41], v[40:41], v[92:93] op_sel_hi:[1,0] neg_lo:[0,1] neg_hi:[0,1]
	v_pk_add_f32 v[42:43], v[42:43], v[92:93] op_sel_hi:[1,0] neg_lo:[0,1] neg_hi:[0,1]
	v_pk_add_f32 v[44:45], v[44:45], v[92:93] op_sel_hi:[1,0] neg_lo:[0,1] neg_hi:[0,1]
	v_pk_add_f32 v[46:47], v[46:47], v[92:93] op_sel_hi:[1,0] neg_lo:[0,1] neg_hi:[0,1]
	v_pk_mul_f32 v[88:89], v[40:41], v[40:41]
	v_pk_fma_f32 v[88:89], v[42:43], v[42:43], v[88:89]
	v_pk_fma_f32 v[88:89], v[44:45], v[44:45], v[88:89]
	v_pk_fma_f32 v[88:89], v[46:47], v[46:47], v[88:89]
	v_add_f32_e32 v91, v88, v89
	v_pk_fma_f32 v[72:73], v[72:73], v[8:9], v[56:57]
	v_pk_fma_f32 v[74:75], v[74:75], v[10:11], v[58:59]
	v_add_f32_dpp v91, v91, v91 quad_perm:[1,0,3,2] row_mask:0xf bank_mask:0xf
	v_pk_fma_f32 v[76:77], v[76:77], v[12:13], v[60:61]
	v_pk_fma_f32 v[78:79], v[78:79], v[14:15], v[62:63]
	v_add_f32_dpp v91, v91, v91 quad_perm:[2,3,0,1] row_mask:0xf bank_mask:0xf
	s_nop 1
	v_add_f32_dpp v91, v91, v91 row_half_mirror row_mask:0xf bank_mask:0xf
	s_nop 0
	v_fmamk_f32 v94, v91, 0x3c800000, v5
	v_rsq_f32_e32 v94, v94
	s_nop 0
	v_pk_mul_f32 v[40:41], v[40:41], v[94:95] op_sel_hi:[1,0]
	v_pk_mul_f32 v[42:43], v[42:43], v[94:95] op_sel_hi:[1,0]
	v_pk_mul_f32 v[44:45], v[44:45], v[94:95] op_sel_hi:[1,0]
	v_pk_mul_f32 v[46:47], v[46:47], v[94:95] op_sel_hi:[1,0]
	v_pk_fma_f32 v[40:41], v[40:41], v[16:17], v[24:25]
	v_pk_fma_f32 v[42:43], v[42:43], v[18:19], v[26:27]
	v_pk_fma_f32 v[44:45], v[44:45], v[20:21], v[28:29]
	v_pk_fma_f32 v[46:47], v[46:47], v[22:23], v[30:31]
	v_pk_fma_f32 v[80:81], v[72:73], v[96:97], v[40:41] op_sel_hi:[1,0,1]
	v_pk_fma_f32 v[82:83], v[74:75], v[96:97], v[42:43] op_sel_hi:[1,0,1]
	v_pk_fma_f32 v[84:85], v[76:77], v[96:97], v[44:45] op_sel_hi:[1,0,1]
	v_pk_fma_f32 v[86:87], v[78:79], v[96:97], v[46:47] op_sel_hi:[1,0,1]
	v_pk_mul_f32 v[80:81], v[80:81], v[64:65]
	v_pk_mul_f32 v[82:83], v[82:83], v[66:67]
	v_pk_mul_f32 v[84:85], v[84:85], v[68:69]
	v_pk_mul_f32 v[86:87], v[86:87], v[70:71]
	v_cvt_pk_bf16_f32 v72, v80, v81
	v_cvt_pk_bf16_f32 v73, v82, v83
	v_cvt_pk_bf16_f32 v74, v84, v85
	v_cvt_pk_bf16_f32 v75, v86, v87
	global_store_dwordx4 v1, v[72:75], s[8:9]
	s_add_u32 s8, s8, 0x400
	s_addc_u32 s9, s9, 0
	s_waitcnt vmcnt(19)
	v_lshlrev_b32_e32 v40, 16, v212
	v_and_b32_e32 v41, 0xffff0000, v212
	v_lshlrev_b32_e32 v42, 16, v213
	v_and_b32_e32 v43, 0xffff0000, v213
	v_lshlrev_b32_e32 v44, 16, v214
	v_and_b32_e32 v45, 0xffff0000, v214
	v_lshlrev_b32_e32 v46, 16, v215
	v_and_b32_e32 v47, 0xffff0000, v215
	v_pk_add_f32 v[88:89], v[40:41], v[42:43]
	v_pk_add_f32 v[88:89], v[88:89], v[44:45]
	v_pk_add_f32 v[88:89], v[88:89], v[46:47]
	v_add_f32_e32 v90, v88, v89
	v_lshlrev_b32_e32 v48, 16, v216
	v_and_b32_e32 v49, 0xffff0000, v216
	v_lshlrev_b32_e32 v50, 16, v217
	v_and_b32_e32 v51, 0xffff0000, v217
	v_lshlrev_b32_e32 v52, 16, v218
	v_and_b32_e32 v53, 0xffff0000, v218
	v_lshlrev_b32_e32 v54, 16, v219
	v_and_b32_e32 v55, 0xffff0000, v219
	v_add_f32_dpp v90, v90, v90 quad_perm:[1,0,3,2] row_mask:0xf bank_mask:0xf
	v_lshlrev_b32_e32 v64, 16, v220
	v_and_b32_e32 v65, 0xffff0000, v220
	v_lshlrev_b32_e32 v66, 16, v221
	v_and_b32_e32 v67, 0xffff0000, v221
	v_add_f32_dpp v90, v90, v90 quad_perm:[2,3,0,1] row_mask:0xf bank_mask:0xf
	v_lshlrev_b32_e32 v68, 16, v222
	v_and_b32_e32 v69, 0xffff0000, v222
	v_lshlrev_b32_e32 v70, 16, v223
	v_and_b32_e32 v71, 0xffff0000, v223
	v_add_f32_dpp v90, v90, v90 row_half_mirror row_mask:0xf bank_mask:0xf
	v_pk_add_f32 v[72:73], v[56:57], v[48:49] neg_lo:[0,1] neg_hi:[0,1]
	v_pk_add_f32 v[74:75], v[58:59], v[50:51] neg_lo:[0,1] neg_hi:[0,1]
	v_pk_add_f32 v[76:77], v[60:61], v[52:53] neg_lo:[0,1] neg_hi:[0,1]
	v_pk_add_f32 v[78:79], v[62:63], v[54:55] neg_lo:[0,1] neg_hi:[0,1]
	v_mul_f32_e32 v92, 0x3c800000, v90
	v_mov_b32_e32 v96, v224
	v_pk_add_f32 v[40:41], v[40:41], v[92:93] op_sel_hi:[1,0] neg_lo:[0,1] neg_hi:[0,1]
	v_pk_add_f32 v[42:43], v[42:43], v[92:93] op_sel_hi:[1,0] neg_lo:[0,1] neg_hi:[0,1]
	v_pk_add_f32 v[44:45], v[44:45], v[92:93] op_sel_hi:[1,0] neg_lo:[0,1] neg_hi:[0,1]
	v_pk_add_f32 v[46:47], v[46:47], v[92:93] op_sel_hi:[1,0] neg_lo:[0,1] neg_hi:[0,1]
	v_pk_mul_f32 v[88:89], v[40:41], v[40:41]
	v_pk_fma_f32 v[88:89], v[42:43], v[42:43], v[88:89]
	v_pk_fma_f32 v[88:89], v[44:45], v[44:45], v[88:89]
	v_pk_fma_f32 v[88:89], v[46:47], v[46:47], v[88:89]
	v_add_f32_e32 v91, v88, v89
	v_pk_fma_f32 v[72:73], v[72:73], v[8:9], v[48:49]
	v_pk_fma_f32 v[74:75], v[74:75], v[10:11], v[50:51]
	v_add_f32_dpp v91, v91, v91 quad_perm:[1,0,3,2] row_mask:0xf bank_mask:0xf
	v_pk_fma_f32 v[76:77], v[76:77], v[12:13], v[52:53]
	v_pk_fma_f32 v[78:79], v[78:79], v[14:15], v[54:55]
	v_add_f32_dpp v91, v91, v91 quad_perm:[2,3,0,1] row_mask:0xf bank_mask:0xf
	s_nop 1
	v_add_f32_dpp v91, v91, v91 row_half_mirror row_mask:0xf bank_mask:0xf
	s_nop 0
	v_fmamk_f32 v94, v91, 0x3c800000, v5
	v_rsq_f32_e32 v94, v94
	s_nop 0
	v_pk_mul_f32 v[40:41], v[40:41], v[94:95] op_sel_hi:[1,0]
	v_pk_mul_f32 v[42:43], v[42:43], v[94:95] op_sel_hi:[1,0]
	v_pk_mul_f32 v[44:45], v[44:45], v[94:95] op_sel_hi:[1,0]
	v_pk_mul_f32 v[46:47], v[46:47], v[94:95] op_sel_hi:[1,0]
	v_pk_fma_f32 v[40:41], v[40:41], v[16:17], v[24:25]
	v_pk_fma_f32 v[42:43], v[42:43], v[18:19], v[26:27]
	v_pk_fma_f32 v[44:45], v[44:45], v[20:21], v[28:29]
	v_pk_fma_f32 v[46:47], v[46:47], v[22:23], v[30:31]
	v_pk_fma_f32 v[80:81], v[72:73], v[96:97], v[40:41] op_sel_hi:[1,0,1]
	v_pk_fma_f32 v[82:83], v[74:75], v[96:97], v[42:43] op_sel_hi:[1,0,1]
	v_pk_fma_f32 v[84:85], v[76:77], v[96:97], v[44:45] op_sel_hi:[1,0,1]
	v_pk_fma_f32 v[86:87], v[78:79], v[96:97], v[46:47] op_sel_hi:[1,0,1]
	v_pk_mul_f32 v[80:81], v[80:81], v[64:65]
	v_pk_mul_f32 v[82:83], v[82:83], v[66:67]
	v_pk_mul_f32 v[84:85], v[84:85], v[68:69]
	v_pk_mul_f32 v[86:87], v[86:87], v[70:71]
	v_cvt_pk_bf16_f32 v72, v80, v81
	v_cvt_pk_bf16_f32 v73, v82, v83
	v_cvt_pk_bf16_f32 v74, v84, v85
	v_cvt_pk_bf16_f32 v75, v86, v87
	global_store_dwordx4 v1, v[72:75], s[8:9]
	s_add_u32 s8, s8, 0x400
	s_addc_u32 s9, s9, 0
	s_waitcnt vmcnt(15)
	v_lshlrev_b32_e32 v40, 16, v226
	v_and_b32_e32 v41, 0xffff0000, v226
	v_lshlrev_b32_e32 v42, 16, v227
	v_and_b32_e32 v43, 0xffff0000, v227
	v_lshlrev_b32_e32 v44, 16, v228
	v_and_b32_e32 v45, 0xffff0000, v228
	v_lshlrev_b32_e32 v46, 16, v229
	v_and_b32_e32 v47, 0xffff0000, v229
	v_pk_add_f32 v[88:89], v[40:41], v[42:43]
	v_pk_add_f32 v[88:89], v[88:89], v[44:45]
	v_pk_add_f32 v[88:89], v[88:89], v[46:47]
	v_add_f32_e32 v90, v88, v89
	v_lshlrev_b32_e32 v56, 16, v230
	v_and_b32_e32 v57, 0xffff0000, v230
	v_lshlrev_b32_e32 v58, 16, v231
	v_and_b32_e32 v59, 0xffff0000, v231
	v_lshlrev_b32_e32 v60, 16, v232
	v_and_b32_e32 v61, 0xffff0000, v232
	v_lshlrev_b32_e32 v62, 16, v233
	v_and_b32_e32 v63, 0xffff0000, v233
	v_add_f32_dpp v90, v90, v90 quad_perm:[1,0,3,2] row_mask:0xf bank_mask:0xf
	v_lshlrev_b32_e32 v64, 16, v234
	v_and_b32_e32 v65, 0xffff0000, v234
	v_lshlrev_b32_e32 v66, 16, v235
	v_and_b32_e32 v67, 0xffff0000, v235
	v_add_f32_dpp v90, v90, v90 quad_perm:[2,3,0,1] row_mask:0xf bank_mask:0xf
	v_lshlrev_b32_e32 v68, 16, v236
	v_and_b32_e32 v69, 0xffff0000, v236
	v_lshlrev_b32_e32 v70, 16, v237
	v_and_b32_e32 v71, 0xffff0000, v237
	v_add_f32_dpp v90, v90, v90 row_half_mirror row_mask:0xf bank_mask:0xf
	v_pk_add_f32 v[72:73], v[48:49], v[56:57] neg_lo:[0,1] neg_hi:[0,1]
	v_pk_add_f32 v[74:75], v[50:51], v[58:59] neg_lo:[0,1] neg_hi:[0,1]
	v_pk_add_f32 v[76:77], v[52:53], v[60:61] neg_lo:[0,1] neg_hi:[0,1]
	v_pk_add_f32 v[78:79], v[54:55], v[62:63] neg_lo:[0,1] neg_hi:[0,1]
	v_mul_f32_e32 v92, 0x3c800000, v90
	v_mov_b32_e32 v96, v238
	v_pk_add_f32 v[40:41], v[40:41], v[92:93] op_sel_hi:[1,0] neg_lo:[0,1] neg_hi:[0,1]
	v_pk_add_f32 v[42:43], v[42:43], v[92:93] op_sel_hi:[1,0] neg_lo:[0,1] neg_hi:[0,1]
	v_pk_add_f32 v[44:45], v[44:45], v[92:93] op_sel_hi:[1,0] neg_lo:[0,1] neg_hi:[0,1]
	v_pk_add_f32 v[46:47], v[46:47], v[92:93] op_sel_hi:[1,0] neg_lo:[0,1] neg_hi:[0,1]
	v_pk_mul_f32 v[88:89], v[40:41], v[40:41]
	v_pk_fma_f32 v[88:89], v[42:43], v[42:43], v[88:89]
	v_pk_fma_f32 v[88:89], v[44:45], v[44:45], v[88:89]
	v_pk_fma_f32 v[88:89], v[46:47], v[46:47], v[88:89]
	v_add_f32_e32 v91, v88, v89
	v_pk_fma_f32 v[72:73], v[72:73], v[8:9], v[56:57]
	v_pk_fma_f32 v[74:75], v[74:75], v[10:11], v[58:59]
	v_add_f32_dpp v91, v91, v91 quad_perm:[1,0,3,2] row_mask:0xf bank_mask:0xf
	v_pk_fma_f32 v[76:77], v[76:77], v[12:13], v[60:61]
	v_pk_fma_f32 v[78:79], v[78:79], v[14:15], v[62:63]
	v_add_f32_dpp v91, v91, v91 quad_perm:[2,3,0,1] row_mask:0xf bank_mask:0xf
	s_nop 1
	v_add_f32_dpp v91, v91, v91 row_half_mirror row_mask:0xf bank_mask:0xf
	s_nop 0
	v_fmamk_f32 v94, v91, 0x3c800000, v5
	v_rsq_f32_e32 v94, v94
	s_nop 0
	v_pk_mul_f32 v[40:41], v[40:41], v[94:95] op_sel_hi:[1,0]
	v_pk_mul_f32 v[42:43], v[42:43], v[94:95] op_sel_hi:[1,0]
	v_pk_mul_f32 v[44:45], v[44:45], v[94:95] op_sel_hi:[1,0]
	v_pk_mul_f32 v[46:47], v[46:47], v[94:95] op_sel_hi:[1,0]
	v_pk_fma_f32 v[40:41], v[40:41], v[16:17], v[24:25]
	v_pk_fma_f32 v[42:43], v[42:43], v[18:19], v[26:27]
	v_pk_fma_f32 v[44:45], v[44:45], v[20:21], v[28:29]
	v_pk_fma_f32 v[46:47], v[46:47], v[22:23], v[30:31]
	v_pk_fma_f32 v[80:81], v[72:73], v[96:97], v[40:41] op_sel_hi:[1,0,1]
	v_pk_fma_f32 v[82:83], v[74:75], v[96:97], v[42:43] op_sel_hi:[1,0,1]
	v_pk_fma_f32 v[84:85], v[76:77], v[96:97], v[44:45] op_sel_hi:[1,0,1]
	v_pk_fma_f32 v[86:87], v[78:79], v[96:97], v[46:47] op_sel_hi:[1,0,1]
	v_pk_mul_f32 v[80:81], v[80:81], v[64:65]
	v_pk_mul_f32 v[82:83], v[82:83], v[66:67]
	v_pk_mul_f32 v[84:85], v[84:85], v[68:69]
	v_pk_mul_f32 v[86:87], v[86:87], v[70:71]
	v_cvt_pk_bf16_f32 v72, v80, v81
	v_cvt_pk_bf16_f32 v73, v82, v83
	v_cvt_pk_bf16_f32 v74, v84, v85
	v_cvt_pk_bf16_f32 v75, v86, v87
	global_store_dwordx4 v1, v[72:75], s[8:9]
	s_add_u32 s8, s8, 0x400
	s_addc_u32 s9, s9, 0
	s_waitcnt vmcnt(11)
	v_lshlrev_b32_e32 v40, 16, v100
	v_and_b32_e32 v41, 0xffff0000, v100
	v_lshlrev_b32_e32 v42, 16, v101
	v_and_b32_e32 v43, 0xffff0000, v101
	v_lshlrev_b32_e32 v44, 16, v102
	v_and_b32_e32 v45, 0xffff0000, v102
	v_lshlrev_b32_e32 v46, 16, v103
	v_and_b32_e32 v47, 0xffff0000, v103
	v_pk_add_f32 v[88:89], v[40:41], v[42:43]
	v_pk_add_f32 v[88:89], v[88:89], v[44:45]
	v_pk_add_f32 v[88:89], v[88:89], v[46:47]
	v_add_f32_e32 v90, v88, v89
	v_lshlrev_b32_e32 v48, 16, v104
	v_and_b32_e32 v49, 0xffff0000, v104
	v_lshlrev_b32_e32 v50, 16, v105
	v_and_b32_e32 v51, 0xffff0000, v105
	v_lshlrev_b32_e32 v52, 16, v106
	v_and_b32_e32 v53, 0xffff0000, v106
	v_lshlrev_b32_e32 v54, 16, v107
	v_and_b32_e32 v55, 0xffff0000, v107
	v_add_f32_dpp v90, v90, v90 quad_perm:[1,0,3,2] row_mask:0xf bank_mask:0xf
	v_lshlrev_b32_e32 v64, 16, v108
	v_and_b32_e32 v65, 0xffff0000, v108
	v_lshlrev_b32_e32 v66, 16, v109
	v_and_b32_e32 v67, 0xffff0000, v109
	v_add_f32_dpp v90, v90, v90 quad_perm:[2,3,0,1] row_mask:0xf bank_mask:0xf
	v_lshlrev_b32_e32 v68, 16, v110
	v_and_b32_e32 v69, 0xffff0000, v110
	v_lshlrev_b32_e32 v70, 16, v111
	v_and_b32_e32 v71, 0xffff0000, v111
	v_add_f32_dpp v90, v90, v90 row_half_mirror row_mask:0xf bank_mask:0xf
	v_pk_add_f32 v[72:73], v[56:57], v[48:49] neg_lo:[0,1] neg_hi:[0,1]
	v_pk_add_f32 v[74:75], v[58:59], v[50:51] neg_lo:[0,1] neg_hi:[0,1]
	v_pk_add_f32 v[76:77], v[60:61], v[52:53] neg_lo:[0,1] neg_hi:[0,1]
	v_pk_add_f32 v[78:79], v[62:63], v[54:55] neg_lo:[0,1] neg_hi:[0,1]
	v_mul_f32_e32 v92, 0x3c800000, v90
	v_mov_b32_e32 v96, v112
	v_pk_add_f32 v[40:41], v[40:41], v[92:93] op_sel_hi:[1,0] neg_lo:[0,1] neg_hi:[0,1]
	v_pk_add_f32 v[42:43], v[42:43], v[92:93] op_sel_hi:[1,0] neg_lo:[0,1] neg_hi:[0,1]
	v_pk_add_f32 v[44:45], v[44:45], v[92:93] op_sel_hi:[1,0] neg_lo:[0,1] neg_hi:[0,1]
	v_pk_add_f32 v[46:47], v[46:47], v[92:93] op_sel_hi:[1,0] neg_lo:[0,1] neg_hi:[0,1]
	v_pk_mul_f32 v[88:89], v[40:41], v[40:41]
	v_pk_fma_f32 v[88:89], v[42:43], v[42:43], v[88:89]
	v_pk_fma_f32 v[88:89], v[44:45], v[44:45], v[88:89]
	v_pk_fma_f32 v[88:89], v[46:47], v[46:47], v[88:89]
	v_add_f32_e32 v91, v88, v89
	v_pk_fma_f32 v[72:73], v[72:73], v[8:9], v[48:49]
	v_pk_fma_f32 v[74:75], v[74:75], v[10:11], v[50:51]
	v_add_f32_dpp v91, v91, v91 quad_perm:[1,0,3,2] row_mask:0xf bank_mask:0xf
	v_pk_fma_f32 v[76:77], v[76:77], v[12:13], v[52:53]
	v_pk_fma_f32 v[78:79], v[78:79], v[14:15], v[54:55]
	v_add_f32_dpp v91, v91, v91 quad_perm:[2,3,0,1] row_mask:0xf bank_mask:0xf
	s_nop 1
	v_add_f32_dpp v91, v91, v91 row_half_mirror row_mask:0xf bank_mask:0xf
	s_nop 0
	v_fmamk_f32 v94, v91, 0x3c800000, v5
	v_rsq_f32_e32 v94, v94
	s_nop 0
	v_pk_mul_f32 v[40:41], v[40:41], v[94:95] op_sel_hi:[1,0]
	v_pk_mul_f32 v[42:43], v[42:43], v[94:95] op_sel_hi:[1,0]
	v_pk_mul_f32 v[44:45], v[44:45], v[94:95] op_sel_hi:[1,0]
	v_pk_mul_f32 v[46:47], v[46:47], v[94:95] op_sel_hi:[1,0]
	v_pk_fma_f32 v[40:41], v[40:41], v[16:17], v[24:25]
	v_pk_fma_f32 v[42:43], v[42:43], v[18:19], v[26:27]
	v_pk_fma_f32 v[44:45], v[44:45], v[20:21], v[28:29]
	v_pk_fma_f32 v[46:47], v[46:47], v[22:23], v[30:31]
	v_pk_fma_f32 v[80:81], v[72:73], v[96:97], v[40:41] op_sel_hi:[1,0,1]
	v_pk_fma_f32 v[82:83], v[74:75], v[96:97], v[42:43] op_sel_hi:[1,0,1]
	v_pk_fma_f32 v[84:85], v[76:77], v[96:97], v[44:45] op_sel_hi:[1,0,1]
	v_pk_fma_f32 v[86:87], v[78:79], v[96:97], v[46:47] op_sel_hi:[1,0,1]
	v_pk_mul_f32 v[80:81], v[80:81], v[64:65]
	v_pk_mul_f32 v[82:83], v[82:83], v[66:67]
	v_pk_mul_f32 v[84:85], v[84:85], v[68:69]
	v_pk_mul_f32 v[86:87], v[86:87], v[70:71]
	v_cvt_pk_bf16_f32 v72, v80, v81
	v_cvt_pk_bf16_f32 v73, v82, v83
	v_cvt_pk_bf16_f32 v74, v84, v85
	v_cvt_pk_bf16_f32 v75, v86, v87
	global_store_dwordx4 v1, v[72:75], s[8:9]
	s_add_u32 s8, s8, 0x400
	s_addc_u32 s9, s9, 0
	s_waitcnt vmcnt(7)
	v_lshlrev_b32_e32 v40, 16, v114
	v_and_b32_e32 v41, 0xffff0000, v114
	v_lshlrev_b32_e32 v42, 16, v115
	v_and_b32_e32 v43, 0xffff0000, v115
	v_lshlrev_b32_e32 v44, 16, v116
	v_and_b32_e32 v45, 0xffff0000, v116
	v_lshlrev_b32_e32 v46, 16, v117
	v_and_b32_e32 v47, 0xffff0000, v117
	v_pk_add_f32 v[88:89], v[40:41], v[42:43]
	v_pk_add_f32 v[88:89], v[88:89], v[44:45]
	v_pk_add_f32 v[88:89], v[88:89], v[46:47]
	v_add_f32_e32 v90, v88, v89
	v_lshlrev_b32_e32 v56, 16, v118
	v_and_b32_e32 v57, 0xffff0000, v118
	v_lshlrev_b32_e32 v58, 16, v119
	v_and_b32_e32 v59, 0xffff0000, v119
	v_lshlrev_b32_e32 v60, 16, v120
	v_and_b32_e32 v61, 0xffff0000, v120
	v_lshlrev_b32_e32 v62, 16, v121
	v_and_b32_e32 v63, 0xffff0000, v121
	v_add_f32_dpp v90, v90, v90 quad_perm:[1,0,3,2] row_mask:0xf bank_mask:0xf
	v_lshlrev_b32_e32 v64, 16, v122
	v_and_b32_e32 v65, 0xffff0000, v122
	v_lshlrev_b32_e32 v66, 16, v123
	v_and_b32_e32 v67, 0xffff0000, v123
	v_add_f32_dpp v90, v90, v90 quad_perm:[2,3,0,1] row_mask:0xf bank_mask:0xf
	v_lshlrev_b32_e32 v68, 16, v124
	v_and_b32_e32 v69, 0xffff0000, v124
	v_lshlrev_b32_e32 v70, 16, v125
	v_and_b32_e32 v71, 0xffff0000, v125
	v_add_f32_dpp v90, v90, v90 row_half_mirror row_mask:0xf bank_mask:0xf
	v_pk_add_f32 v[72:73], v[48:49], v[56:57] neg_lo:[0,1] neg_hi:[0,1]
	v_pk_add_f32 v[74:75], v[50:51], v[58:59] neg_lo:[0,1] neg_hi:[0,1]
	v_pk_add_f32 v[76:77], v[52:53], v[60:61] neg_lo:[0,1] neg_hi:[0,1]
	v_pk_add_f32 v[78:79], v[54:55], v[62:63] neg_lo:[0,1] neg_hi:[0,1]
	v_mul_f32_e32 v92, 0x3c800000, v90
	v_mov_b32_e32 v96, v126
	v_pk_add_f32 v[40:41], v[40:41], v[92:93] op_sel_hi:[1,0] neg_lo:[0,1] neg_hi:[0,1]
	v_pk_add_f32 v[42:43], v[42:43], v[92:93] op_sel_hi:[1,0] neg_lo:[0,1] neg_hi:[0,1]
	v_pk_add_f32 v[44:45], v[44:45], v[92:93] op_sel_hi:[1,0] neg_lo:[0,1] neg_hi:[0,1]
	v_pk_add_f32 v[46:47], v[46:47], v[92:93] op_sel_hi:[1,0] neg_lo:[0,1] neg_hi:[0,1]
	v_pk_mul_f32 v[88:89], v[40:41], v[40:41]
	v_pk_fma_f32 v[88:89], v[42:43], v[42:43], v[88:89]
	v_pk_fma_f32 v[88:89], v[44:45], v[44:45], v[88:89]
	v_pk_fma_f32 v[88:89], v[46:47], v[46:47], v[88:89]
	v_add_f32_e32 v91, v88, v89
	v_pk_fma_f32 v[72:73], v[72:73], v[8:9], v[56:57]
	v_pk_fma_f32 v[74:75], v[74:75], v[10:11], v[58:59]
	v_add_f32_dpp v91, v91, v91 quad_perm:[1,0,3,2] row_mask:0xf bank_mask:0xf
	v_pk_fma_f32 v[76:77], v[76:77], v[12:13], v[60:61]
	v_pk_fma_f32 v[78:79], v[78:79], v[14:15], v[62:63]
	v_add_f32_dpp v91, v91, v91 quad_perm:[2,3,0,1] row_mask:0xf bank_mask:0xf
	s_nop 1
	v_add_f32_dpp v91, v91, v91 row_half_mirror row_mask:0xf bank_mask:0xf
	s_nop 0
	v_fmamk_f32 v94, v91, 0x3c800000, v5
	v_rsq_f32_e32 v94, v94
	s_nop 0
	v_pk_mul_f32 v[40:41], v[40:41], v[94:95] op_sel_hi:[1,0]
	v_pk_mul_f32 v[42:43], v[42:43], v[94:95] op_sel_hi:[1,0]
	v_pk_mul_f32 v[44:45], v[44:45], v[94:95] op_sel_hi:[1,0]
	v_pk_mul_f32 v[46:47], v[46:47], v[94:95] op_sel_hi:[1,0]
	v_pk_fma_f32 v[40:41], v[40:41], v[16:17], v[24:25]
	v_pk_fma_f32 v[42:43], v[42:43], v[18:19], v[26:27]
	v_pk_fma_f32 v[44:45], v[44:45], v[20:21], v[28:29]
	v_pk_fma_f32 v[46:47], v[46:47], v[22:23], v[30:31]
	v_pk_fma_f32 v[80:81], v[72:73], v[96:97], v[40:41] op_sel_hi:[1,0,1]
	v_pk_fma_f32 v[82:83], v[74:75], v[96:97], v[42:43] op_sel_hi:[1,0,1]
	v_pk_fma_f32 v[84:85], v[76:77], v[96:97], v[44:45] op_sel_hi:[1,0,1]
	v_pk_fma_f32 v[86:87], v[78:79], v[96:97], v[46:47] op_sel_hi:[1,0,1]
	v_pk_mul_f32 v[80:81], v[80:81], v[64:65]
	v_pk_mul_f32 v[82:83], v[82:83], v[66:67]
	v_pk_mul_f32 v[84:85], v[84:85], v[68:69]
	v_pk_mul_f32 v[86:87], v[86:87], v[70:71]
	v_cvt_pk_bf16_f32 v72, v80, v81
	v_cvt_pk_bf16_f32 v73, v82, v83
	v_cvt_pk_bf16_f32 v74, v84, v85
	v_cvt_pk_bf16_f32 v75, v86, v87
	global_store_dwordx4 v1, v[72:75], s[8:9]
	s_add_u32 s8, s8, 0x400
	s_addc_u32 s9, s9, 0
	s_branch .LBB0_987
.Lp5_compiled:
	s_mov_b32 s3, 0
	s_and_b32 s0, s87, 0xffffffc0
	s_ashr_i32 s1, s0, 31
	s_lshl_b64 s[4:5], s[2:3], 9
	s_add_u32 s4, s4, s0
	s_addc_u32 s5, s5, s1
	v_mbcnt_lo_u32_b32 v26, -1, 0
	v_mbcnt_hi_u32_b32 v26, -1, v26
	s_mov_b64 s[18:19], 0x400000
	v_ashrrev_i32_e32 v27, 31, v26
	v_lshl_add_u64 v[24:25], s[4:5], 0, v[26:27]
	v_cmp_gt_u64_e32 vcc, s[18:19], v[24:25]
	s_and_saveexec_b64 s[20:21], vcc
	s_cbranch_execz .LBB0_986
	v_lshlrev_b32_e32 v0, 3, v26
	v_and_b32_e32 v28, 0x1f8, v0
	s_waitcnt vmcnt(0)
	v_mov_b32_e32 v69, 0
	v_lshlrev_b32_e32 v68, 2, v28
	v_lshl_add_u64 v[0:1], s[46:47], 0, v[68:69]
	v_readlane_b32 s48, v255, 7
	v_add_co_u32_e32 v32, vcc, 0x1000, v0
	v_readlane_b32 s60, v255, 19
	v_readlane_b32 s61, v255, 20
	s_mov_b64 s[4:5], 0x1000
	v_addc_co_u32_e32 v33, vcc, 0, v1, vcc
	v_readlane_b32 s62, v255, 21
	v_readlane_b32 s63, v255, 22
	s_mov_b64 s[12:13], s[60:61]
	v_lshl_add_u64 v[30:31], v[0:1], 0, s[4:5]
	global_load_dwordx4 v[0:3], v[32:33], off
	global_load_dwordx4 v[4:7], v[30:31], off offset:16
	s_mov_b64 s[14:15], s[62:63]
	global_load_dwordx4 v[8:11], v68, s[12:13]
	global_load_dwordx4 v[12:15], v68, s[14:15]
	global_load_dwordx4 v[16:19], v68, s[12:13] offset:16
	global_load_dwordx4 v[20:23], v68, s[14:15] offset:16
	v_lshlrev_b32_e32 v68, 1, v28
	v_lshrrev_b32_e32 v29, 1, v26
	v_lshl_add_u64 v[30:31], s[96:97], 0, v[68:69]
	s_mov_b64 s[6:7], 0x1d800000
	v_and_b32_e32 v68, 28, v29
	v_mbcnt_lo_u32_b32 v29, -1, 0
	v_lshl_add_u64 v[70:71], v[30:31], 0, s[6:7]
	v_lshl_add_u64 v[32:33], s[96:97], 0, v[68:69]
	s_mov_b64 s[6:7], 0x4100000
	v_mbcnt_hi_u32_b32 v29, -1, v29
	v_lshl_add_u64 v[72:73], v[32:33], 0, s[6:7]
	v_and_b32_e32 v33, 64, v29
	v_xor_b32_e32 v32, 1, v29
	v_add_u32_e32 v33, 64, v33
	v_cmp_lt_i32_e32 vcc, v32, v33
	s_mov_b64 s[6:7], 0x37800000
	s_ashr_i32 s5, s92, 31
	v_cndmask_b32_e32 v32, v29, v32, vcc
	v_lshlrev_b32_e32 v88, 2, v32
	v_xor_b32_e32 v32, 2, v29
	v_cmp_lt_i32_e32 vcc, v32, v33
	s_mov_b32 s4, s92
	v_lshl_add_u64 v[74:75], v[30:31], 0, s[6:7]
	v_cndmask_b32_e32 v32, v29, v32, vcc
	s_mov_b64 s[6:7], 0xf800000
	s_lshl_b64 s[22:23], s[4:5], 9
	v_lshlrev_b32_e32 v89, 2, v32
	v_xor_b32_e32 v32, 4, v29
	v_lshl_add_u64 v[76:77], v[30:31], 0, s[6:7]
	s_lshl_b64 s[26:27], s[4:5], 14
	s_lshl_b64 s[28:29], s[4:5], 10
	s_lshl_b64 s[30:31], s[4:5], 13
	s_lshl_b64 s[6:7], s[2:3], 12
	s_lshl_b64 s[0:1], s[0:1], 3
	v_cmp_lt_i32_e32 vcc, v32, v33
	s_add_u32 s0, s0, s6
	s_addc_u32 s1, s1, s7
	v_cndmask_b32_e32 v29, v29, v32, vcc
	s_lshl_b64 s[38:39], s[4:5], 12
	v_lshlrev_b32_e32 v90, 2, v29
	v_lshlrev_b64 v[78:79], 3, v[24:25]
	v_lshl_add_u64 v[80:81], v[26:27], 3, s[0:1]
	s_mul_hi_i32 s35, s92, 0x600
	s_mul_i32 s34, s92, 0x600
	s_mul_i32 s3, s92, 0x3000
	s_mov_b64 s[40:41], 0
	s_movk_i32 s31, 0xe00
	s_movk_i32 s39, 0xc00
	v_lshlrev_b32_e32 v82, 1, v28
	s_mov_b32 s46, 0x2b800000
	v_mov_b32_e32 v91, 0x3a27c5ac
	s_mov_b32 s47, 0x800000
	s_mov_b64 s[42:43], 0x3fffff
	v_mov_b64_e32 v[84:85], s[96:97]
	v_mov_b32_e32 v83, v69
	v_readlane_b32 s49, v255, 8
	v_readlane_b32 s50, v255, 9
	v_readlane_b32 s51, v255, 10
	v_readlane_b32 s52, v255, 11
	v_readlane_b32 s53, v255, 12
	v_readlane_b32 s54, v255, 13
	v_readlane_b32 s55, v255, 14
	v_readlane_b32 s56, v255, 15
	v_readlane_b32 s57, v255, 16
	v_readlane_b32 s58, v255, 17
	v_readlane_b32 s59, v255, 18
	s_branch .LBB0_980
